# v18 + d*u skip-term operand taken from an LDS copy of the already-loaded u tile (no second global read of u)
# baseline (speedup 1.0000x reference)
.LBB0_340:
	s_cmp_lt_i32 s96, 4
	s_cselect_b64 s[0:1], -1, 0
	s_and_b64 s[8:9], s[0:1], s[4:5]
	s_andn2_b64 vcc, exec, s[8:9]
	s_cbranch_vccnz .LBB0_393
	v_cmp_gt_u32_e32 vcc, 2, v190
	s_and_saveexec_b64 s[0:1], vcc
	v_lshlrev_b32_e32 v2, 2, v190
	v_add_u32_e32 v2, 0x21000, v2
	v_mov_b32_e32 v3, 0
	ds_write_b32 v2, v3
	s_mov_b64 exec, s[0:1]
	v_and_b32_e32 v172, 31, v191
	v_lshrrev_b32_e32 v173, 5, v191
	v_and_b32_e32 v174, 1, v191
	v_and_b32_e32 v175, 15, v191
	v_lshrrev_b32_e32 v176, 4, v191
	s_mul_i32 s20, s89, 0x3200
	v_lshl_add_u32 v151, v191, 2, s20
	v_mul_u32_u24_e32 v182, 0x110, v175
	v_lshl_add_u32 v182, v176, 4, v182
	v_add_u32_e32 v152, s20, v182
	v_mul_u32_u24_e32 v182, 0x1800, v172
	v_lshl_add_u32 v150, v173, 4, v182
	v_lshlrev_b32_e32 v182, 5, v172
	v_lshl_add_u32 v182, v173, 4, v182
	s_add_u32 s22, s20, 0x2200
	v_add_u32_e32 v162, s22, v182
	v_lshlrev_b32_e32 v182, 5, v175
	v_lshl_add_u32 v182, v176, 3, v182
	v_add_u32_e32 v163, s22, v182
	v_mul_u32_u24_e32 v182, 0x1800, v175
	v_lshl_add_u32 v154, v176, 3, v182
	v_add_u32_e32 v158, 0x18000, v154
	v_lshlrev_b32_e32 v182, 12, v175
	v_lshl_add_u32 v153, v176, 4, v182
	v_add_u32_e32 v157, 0x10000, v153
	v_lshlrev_b32_e32 v182, 11, v175
	v_lshl_add_u32 v156, v176, 3, v182
	v_add_u32_e32 v159, 0x8000, v156
	s_and_b32 s21, s89, 3
	s_lshl_b32 s21, s21, 13
	s_add_u32 s21, s21, 0x19000
	v_lshlrev_b32_e32 v182, 5, v175
	v_lshl_add_u32 v182, v176, 3, v182
	v_add_u32_e32 v155, s21, v182
	v_lshrrev_b32_e32 v182, 4, v172
	v_lshlrev_b32_e32 v182, 10, v182
	v_lshl_add_u32 v182, v175, 4, v182
	v_lshl_add_u32 v177, v173, 8, v182
	v_lshrrev_b32_e32 v182, 1, v176
	v_lshlrev_b32_e32 v182, 8, v182
	v_and_b32_e32 v183, 1, v176
	v_lshl_add_u32 v182, v183, 3, v182
	v_lshl_add_u32 v178, v175, 4, v182
	v_lshrrev_b32_e32 v182, 1, v172
	v_lshl_add_u32 v182, v173, 5, v182
	v_lshlrev_b32_e32 v179, 3, v182
	v_lshlrev_b32_e32 v183, 14, v174
	v_lshl_add_u32 v180, v182, 2, v183
	v_lshlrev_b32_e32 v181, 4, v176
	s_waitcnt vmcnt(0) lgkmcnt(0)
	s_barrier
	s_cmp_lt_u32 s89, 4
	s_cbranch_scc0 .Lssm_ctx
	s_lshr_b32 s21, s89, 1
	s_and_b32 s22, s2, 7
	s_lshl_b32 s22, s22, 6
	s_lshr_b32 s26, s2, 3
	s_lshl_b32 s26, s26, 1
	s_add_u32 s22, s22, s26
	s_add_u32 s22, s22, s21
	s_lshr_b32 s23, s22, 6
	s_and_b32 s24, s22, 63
	s_lshl_b32 s25, s23, 10
	s_add_u32 s25, s25, 0x2000
	s_and_b32 s26, s89, 1
	s_cmp_eq_u32 s26, 0
	s_cbranch_scc0 .Lssm_lat_bwd
	s_add_u32 s28, s24, 0
	s_lshl_b32 s29, s28, 13
	s_add_u32 s29, s29, 0x200000
	s_add_u32 s10, s62, s29
	s_addc_u32 s11, s63, 0
	global_load_dwordx4 v[84:87], v177, s[10:11]
	global_load_dwordx4 v[88:91], v177, s[10:11] offset:2048
	s_add_u32 s12, s10, 0x1000
	s_addc_u32 s13, s11, 0
	global_load_dwordx4 v[92:95], v177, s[12:13]
	global_load_dwordx4 v[96:99], v177, s[12:13] offset:2048
	s_lshl_b32 s29, s28, 12
	s_add_u32 s29, s29, 0x300000
	s_add_u32 s16, s62, s29
	s_addc_u32 s17, s63, 0
	global_load_dwordx2 v[2:3], v178, s[16:17]
	global_load_dwordx2 v[4:5], v178, s[16:17] offset:1024
	global_load_dwordx2 v[6:7], v178, s[16:17] offset:512
	global_load_dwordx2 v[8:9], v178, s[16:17] offset:1536
	global_load_dwordx2 v[10:11], v178, s[16:17] offset:2048
	global_load_dwordx2 v[12:13], v178, s[16:17] offset:3072
	global_load_dwordx2 v[14:15], v178, s[16:17] offset:2560
	global_load_dwordx2 v[16:17], v178, s[16:17] offset:3584
	s_lshl_b32 s29, s28, 9
	s_add_u32 s29, s29, 0x100000
	s_add_u32 s18, s62, s29
	s_addc_u32 s19, s63, 0
	global_load_dwordx2 v[116:117], v179, s[18:19]
	global_load_dwordx2 v[118:119], v179, s[18:19] offset:128
	s_lshl_b32 s30, s23, 1
	s_lshl_b32 s30, s30, 15
	s_lshl_b32 s31, s24, 8
	s_add_u32 s30, s30, s31
	v_readlane_b32 s34, v254, 10
	v_readlane_b32 s35, v254, 11
	s_nop 3
	s_add_u32 s34, s34, s30
	s_addc_u32 s35, s35, 0
	global_load_dword v120, v180, s[34:35]
	global_load_dword v121, v180, s[34:35] offset:64
	v_readlane_b32 s34, v254, 28
	v_readlane_b32 s35, v254, 29
	s_nop 3
	s_lshl_b32 s31, s24, 6
	s_add_u32 s34, s34, s31
	s_addc_u32 s35, s35, 0
	global_load_dwordx4 v[164:167], v181, s[34:35]
	s_mul_i32 s31, s25, 0x1800
	s_lshl_b32 s29, s24, 5
	s_add_u32 s31, s31, s29
	s_add_u32 s31, s31, 0x8801000
	s_add_u32 s4, s62, s31
	s_addc_u32 s5, s63, 0
	s_lshl_b32 s31, s25, 12
	s_lshl_b32 s29, s24, 6
	s_add_u32 s31, s31, s29
	s_add_u32 s6, s60, s31
	s_addc_u32 s7, s61, 0
	s_add_u32 s34, s4, 0
	s_addc_u32 s35, s5, 0
	global_load_dwordx4 v[80:83], v150, s[34:35]
	s_mov_b64 s[10:11], s[34:35]
	s_add_u32 s10, s10, 196608
	s_addc_u32 s11, s11, 0
	global_load_dwordx4 v[144:147], v150, s[10:11]
	s_mov_b64 s[34:35], s[10:11]
	s_add_u32 s10, s10, 196608
	s_addc_u32 s11, s11, 0
	s_add_u32 s12, s6, 0
	s_addc_u32 s13, s7, 0
	s_mov_b32 s14, 0
	s_mov_b32 s40, 0xffff0000
	s_waitcnt vmcnt(0)
	v_and_b32_e32 v182, 0xffff, v2
	v_lshrrev_b32_e32 v183, 16, v2
	v_and_b32_e32 v184, 0xffff, v3
	v_lshrrev_b32_e32 v185, 16, v3
	v_lshl_or_b32 v100, v4, 16, v182
	v_and_or_b32 v101, v4, s40, v183
	v_lshl_or_b32 v102, v5, 16, v184
	v_and_or_b32 v103, v5, s40, v185
	v_and_b32_e32 v182, 0xffff, v6
	v_lshrrev_b32_e32 v183, 16, v6
	v_and_b32_e32 v184, 0xffff, v7
	v_lshrrev_b32_e32 v185, 16, v7
	v_lshl_or_b32 v104, v8, 16, v182
	v_and_or_b32 v105, v8, s40, v183
	v_lshl_or_b32 v106, v9, 16, v184
	v_and_or_b32 v107, v9, s40, v185
	v_and_b32_e32 v182, 0xffff, v10
	v_lshrrev_b32_e32 v183, 16, v10
	v_and_b32_e32 v184, 0xffff, v11
	v_lshrrev_b32_e32 v185, 16, v11
	v_lshl_or_b32 v108, v12, 16, v182
	v_and_or_b32 v109, v12, s40, v183
	v_lshl_or_b32 v110, v13, 16, v184
	v_and_or_b32 v111, v13, s40, v185
	v_and_b32_e32 v182, 0xffff, v14
	v_lshrrev_b32_e32 v183, 16, v14
	v_and_b32_e32 v184, 0xffff, v15
	v_lshrrev_b32_e32 v185, 16, v15
	v_lshl_or_b32 v112, v16, 16, v182
	v_and_or_b32 v113, v16, s40, v183
	v_lshl_or_b32 v114, v17, 16, v184
	v_and_or_b32 v115, v17, s40, v185
	v_cmp_eq_u32_e32 vcc, 1, v174
	v_xor_b32_e32 v182, 0x80000000, v117
	v_xor_b32_e32 v183, 0x80000000, v119
	s_nop 1
	v_cndmask_b32_e32 v122, v182, v117, vcc
	v_cndmask_b32_e32 v123, v183, v119, vcc

.Lssm_spin_done_d0m0:
	s_mov_b64 s[42:43], s[12:13]
	s_add_u32 s42, s42, 67108864
	s_addc_u32 s43, s43, 0
	s_lshl_b32 s31, s25, 11
	s_lshl_b32 s29, s24, 5
	s_add_u32 s31, s31, s29
	s_add_u32 s31, s31, 344981504
	s_add_u32 s12, s62, s31
	s_addc_u32 s13, s63, 0
	s_mov_b64 s[64:65], s[34:35]
	s_sub_u32 s64, s64, 196608
	s_subb_u32 s65, s65, 0
	global_load_dwordx4 v[6:9], v153, s[42:43]
	global_load_dwordx4 v[10:13], v157, s[42:43]
	s_add_u32 s42, s42, 131072
	s_addc_u32 s43, s43, 0
	s_waitcnt vmcnt(0)
.Lssm_tileB_d0m0:
	s_waitcnt vmcnt(7)
	v_mfma_f32_32x32x16_bf16 v[16:31], v[80:83], v[84:87], 0
	v_mfma_f32_32x32x16_bf16 v[32:47], v[80:83], v[88:91], 0
	v_mfma_f32_32x32x16_bf16 v[48:63], v[80:83], v[92:95], 0
	v_mfma_f32_32x32x16_bf16 v[64:79], v[80:83], v[96:99], 0
	ds_write_b128 v162, v[80:83]
	global_load_dwordx4 v[172:175], v153, s[42:43]
	global_load_dwordx4 v[176:179], v157, s[42:43]
	s_add_u32 s42, s42, 131072
	s_addc_u32 s43, s43, 0
	s_nop 11
	global_load_dwordx4 v[80:83], v150, s[10:11]
	s_add_u32 s34, s34, 196608
	s_addc_u32 s35, s35, 0
	s_add_u32 s10, s10, 196608
	s_addc_u32 s11, s11, 0
	v_permlane32_swap_b32_e32 v16, v48
	v_permlane32_swap_b32_e32 v17, v49
	v_permlane32_swap_b32_e32 v18, v50
	v_permlane32_swap_b32_e32 v19, v51
	v_permlane32_swap_b32_e32 v20, v52
	v_permlane32_swap_b32_e32 v21, v53
	v_permlane32_swap_b32_e32 v22, v54
	v_permlane32_swap_b32_e32 v23, v55
	v_permlane32_swap_b32_e32 v24, v56
	v_permlane32_swap_b32_e32 v25, v57
	v_permlane32_swap_b32_e32 v26, v58
	v_permlane32_swap_b32_e32 v27, v59
	v_permlane32_swap_b32_e32 v28, v60
	v_permlane32_swap_b32_e32 v29, v61
	v_permlane32_swap_b32_e32 v30, v62
	v_permlane32_swap_b32_e32 v31, v63
	v_permlane32_swap_b32_e32 v32, v64
	v_permlane32_swap_b32_e32 v33, v65
	v_permlane32_swap_b32_e32 v34, v66
	v_permlane32_swap_b32_e32 v35, v67
	v_permlane32_swap_b32_e32 v36, v68
	v_permlane32_swap_b32_e32 v37, v69
	v_permlane32_swap_b32_e32 v38, v70
	v_permlane32_swap_b32_e32 v39, v71
	v_permlane32_swap_b32_e32 v40, v72
	v_permlane32_swap_b32_e32 v41, v73
	v_permlane32_swap_b32_e32 v42, v74
	v_permlane32_swap_b32_e32 v43, v75
	v_permlane32_swap_b32_e32 v44, v76
	v_permlane32_swap_b32_e32 v45, v77
	v_permlane32_swap_b32_e32 v46, v78
	v_permlane32_swap_b32_e32 v47, v79
	v_fmac_f32_e32 v16, v116, v120
	v_fmac_f32_e32 v32, v118, v121
	v_fmac_f32_dpp v16, v120, v122 quad_perm:[1,0,3,2] row_mask:0xf bank_mask:0xf
	v_fmac_f32_dpp v32, v121, v123 quad_perm:[1,0,3,2] row_mask:0xf bank_mask:0xf
	v_cvt_pk_bf16_f32 v148, v16, v32
	ds_write_b32 v151, v148
	v_fmac_f32_e32 v17, v116, v16
	v_fmac_f32_e32 v33, v118, v32
	v_fmac_f32_dpp v17, v16, v122 quad_perm:[1,0,3,2] row_mask:0xf bank_mask:0xf
	v_fmac_f32_dpp v33, v32, v123 quad_perm:[1,0,3,2] row_mask:0xf bank_mask:0xf
	v_cvt_pk_bf16_f32 v149, v17, v33
	ds_write_b32 v151, v149 offset:272
	v_fmac_f32_e32 v18, v116, v17
	v_fmac_f32_e32 v34, v118, v33
	v_fmac_f32_dpp v18, v17, v122 quad_perm:[1,0,3,2] row_mask:0xf bank_mask:0xf
	v_fmac_f32_dpp v34, v33, v123 quad_perm:[1,0,3,2] row_mask:0xf bank_mask:0xf
	v_cvt_pk_bf16_f32 v148, v18, v34
	ds_write_b32 v151, v148 offset:544
	v_fmac_f32_e32 v19, v116, v18
	v_fmac_f32_e32 v35, v118, v34
	v_fmac_f32_dpp v19, v18, v122 quad_perm:[1,0,3,2] row_mask:0xf bank_mask:0xf
	v_fmac_f32_dpp v35, v34, v123 quad_perm:[1,0,3,2] row_mask:0xf bank_mask:0xf
	v_cvt_pk_bf16_f32 v149, v19, v35
	ds_write_b32 v151, v149 offset:816
	v_fmac_f32_e32 v48, v116, v19
	v_fmac_f32_e32 v64, v118, v35
	v_fmac_f32_dpp v48, v19, v122 quad_perm:[1,0,3,2] row_mask:0xf bank_mask:0xf
	v_fmac_f32_dpp v64, v35, v123 quad_perm:[1,0,3,2] row_mask:0xf bank_mask:0xf
	v_cvt_pk_bf16_f32 v148, v48, v64
	ds_write_b32 v151, v148 offset:1088
	v_fmac_f32_e32 v49, v116, v48
	v_fmac_f32_e32 v65, v118, v64
	v_fmac_f32_dpp v49, v48, v122 quad_perm:[1,0,3,2] row_mask:0xf bank_mask:0xf
	v_fmac_f32_dpp v65, v64, v123 quad_perm:[1,0,3,2] row_mask:0xf bank_mask:0xf
	v_cvt_pk_bf16_f32 v149, v49, v65
	ds_write_b32 v151, v149 offset:1360
	v_fmac_f32_e32 v50, v116, v49
	v_fmac_f32_e32 v66, v118, v65
	v_fmac_f32_dpp v50, v49, v122 quad_perm:[1,0,3,2] row_mask:0xf bank_mask:0xf
	v_fmac_f32_dpp v66, v65, v123 quad_perm:[1,0,3,2] row_mask:0xf bank_mask:0xf
	v_cvt_pk_bf16_f32 v148, v50, v66
	ds_write_b32 v151, v148 offset:1632
	v_fmac_f32_e32 v51, v116, v50
	v_fmac_f32_e32 v67, v118, v66
	v_fmac_f32_dpp v51, v50, v122 quad_perm:[1,0,3,2] row_mask:0xf bank_mask:0xf
	v_fmac_f32_dpp v67, v66, v123 quad_perm:[1,0,3,2] row_mask:0xf bank_mask:0xf
	v_cvt_pk_bf16_f32 v149, v51, v67
	ds_write_b32 v151, v149 offset:1904
	v_fmac_f32_e32 v20, v116, v51
	v_fmac_f32_e32 v36, v118, v67
	v_fmac_f32_dpp v20, v51, v122 quad_perm:[1,0,3,2] row_mask:0xf bank_mask:0xf
	v_fmac_f32_dpp v36, v67, v123 quad_perm:[1,0,3,2] row_mask:0xf bank_mask:0xf
	v_cvt_pk_bf16_f32 v148, v20, v36
	ds_write_b32 v151, v148 offset:2176
	v_fmac_f32_e32 v21, v116, v20
	v_fmac_f32_e32 v37, v118, v36
	v_fmac_f32_dpp v21, v20, v122 quad_perm:[1,0,3,2] row_mask:0xf bank_mask:0xf
	v_fmac_f32_dpp v37, v36, v123 quad_perm:[1,0,3,2] row_mask:0xf bank_mask:0xf
	v_cvt_pk_bf16_f32 v149, v21, v37
	ds_write_b32 v151, v149 offset:2448
	v_fmac_f32_e32 v22, v116, v21
	v_fmac_f32_e32 v38, v118, v37
	v_fmac_f32_dpp v22, v21, v122 quad_perm:[1,0,3,2] row_mask:0xf bank_mask:0xf
	v_fmac_f32_dpp v38, v37, v123 quad_perm:[1,0,3,2] row_mask:0xf bank_mask:0xf
	v_cvt_pk_bf16_f32 v148, v22, v38
	ds_write_b32 v151, v148 offset:2720
	v_fmac_f32_e32 v23, v116, v22
	v_fmac_f32_e32 v39, v118, v38
	v_fmac_f32_dpp v23, v22, v122 quad_perm:[1,0,3,2] row_mask:0xf bank_mask:0xf
	v_fmac_f32_dpp v39, v38, v123 quad_perm:[1,0,3,2] row_mask:0xf bank_mask:0xf
	v_cvt_pk_bf16_f32 v149, v23, v39
	ds_write_b32 v151, v149 offset:2992
	v_fmac_f32_e32 v52, v116, v23
	v_fmac_f32_e32 v68, v118, v39
	v_fmac_f32_dpp v52, v23, v122 quad_perm:[1,0,3,2] row_mask:0xf bank_mask:0xf
	v_fmac_f32_dpp v68, v39, v123 quad_perm:[1,0,3,2] row_mask:0xf bank_mask:0xf
	v_cvt_pk_bf16_f32 v148, v52, v68
	ds_write_b32 v151, v148 offset:3264
	v_fmac_f32_e32 v53, v116, v52
	v_fmac_f32_e32 v69, v118, v68
	v_fmac_f32_dpp v53, v52, v122 quad_perm:[1,0,3,2] row_mask:0xf bank_mask:0xf
	v_fmac_f32_dpp v69, v68, v123 quad_perm:[1,0,3,2] row_mask:0xf bank_mask:0xf
	v_cvt_pk_bf16_f32 v149, v53, v69
	ds_write_b32 v151, v149 offset:3536
	v_fmac_f32_e32 v54, v116, v53
	v_fmac_f32_e32 v70, v118, v69
	v_fmac_f32_dpp v54, v53, v122 quad_perm:[1,0,3,2] row_mask:0xf bank_mask:0xf
	v_fmac_f32_dpp v70, v69, v123 quad_perm:[1,0,3,2] row_mask:0xf bank_mask:0xf
	v_cvt_pk_bf16_f32 v148, v54, v70
	ds_write_b32 v151, v148 offset:3808
	v_fmac_f32_e32 v55, v116, v54
	v_fmac_f32_e32 v71, v118, v70
	v_fmac_f32_dpp v55, v54, v122 quad_perm:[1,0,3,2] row_mask:0xf bank_mask:0xf
	v_fmac_f32_dpp v71, v70, v123 quad_perm:[1,0,3,2] row_mask:0xf bank_mask:0xf
	v_cvt_pk_bf16_f32 v149, v55, v71
	ds_write_b32 v151, v149 offset:4080
	v_fmac_f32_e32 v24, v116, v55
	v_fmac_f32_e32 v40, v118, v71
	v_fmac_f32_dpp v24, v55, v122 quad_perm:[1,0,3,2] row_mask:0xf bank_mask:0xf
	v_fmac_f32_dpp v40, v71, v123 quad_perm:[1,0,3,2] row_mask:0xf bank_mask:0xf
	v_cvt_pk_bf16_f32 v148, v24, v40
	ds_write_b32 v151, v148 offset:4352
	v_fmac_f32_e32 v25, v116, v24
	v_fmac_f32_e32 v41, v118, v40
	v_fmac_f32_dpp v25, v24, v122 quad_perm:[1,0,3,2] row_mask:0xf bank_mask:0xf
	v_fmac_f32_dpp v41, v40, v123 quad_perm:[1,0,3,2] row_mask:0xf bank_mask:0xf
	v_cvt_pk_bf16_f32 v149, v25, v41
	ds_write_b32 v151, v149 offset:4624
	v_fmac_f32_e32 v26, v116, v25
	v_fmac_f32_e32 v42, v118, v41
	v_fmac_f32_dpp v26, v25, v122 quad_perm:[1,0,3,2] row_mask:0xf bank_mask:0xf
	v_fmac_f32_dpp v42, v41, v123 quad_perm:[1,0,3,2] row_mask:0xf bank_mask:0xf
	v_cvt_pk_bf16_f32 v148, v26, v42
	ds_write_b32 v151, v148 offset:4896
	v_fmac_f32_e32 v27, v116, v26
	v_fmac_f32_e32 v43, v118, v42
	v_fmac_f32_dpp v27, v26, v122 quad_perm:[1,0,3,2] row_mask:0xf bank_mask:0xf
	v_fmac_f32_dpp v43, v42, v123 quad_perm:[1,0,3,2] row_mask:0xf bank_mask:0xf
	v_cvt_pk_bf16_f32 v149, v27, v43
	ds_write_b32 v151, v149 offset:5168
	v_fmac_f32_e32 v56, v116, v27
	v_fmac_f32_e32 v72, v118, v43
	v_fmac_f32_dpp v56, v27, v122 quad_perm:[1,0,3,2] row_mask:0xf bank_mask:0xf
	v_fmac_f32_dpp v72, v43, v123 quad_perm:[1,0,3,2] row_mask:0xf bank_mask:0xf
	v_cvt_pk_bf16_f32 v148, v56, v72
	ds_write_b32 v151, v148 offset:5440
	v_fmac_f32_e32 v57, v116, v56
	v_fmac_f32_e32 v73, v118, v72
	v_fmac_f32_dpp v57, v56, v122 quad_perm:[1,0,3,2] row_mask:0xf bank_mask:0xf
	v_fmac_f32_dpp v73, v72, v123 quad_perm:[1,0,3,2] row_mask:0xf bank_mask:0xf
	v_cvt_pk_bf16_f32 v149, v57, v73
	ds_write_b32 v151, v149 offset:5712
	v_fmac_f32_e32 v58, v116, v57
	v_fmac_f32_e32 v74, v118, v73
	v_fmac_f32_dpp v58, v57, v122 quad_perm:[1,0,3,2] row_mask:0xf bank_mask:0xf
	v_fmac_f32_dpp v74, v73, v123 quad_perm:[1,0,3,2] row_mask:0xf bank_mask:0xf
	v_cvt_pk_bf16_f32 v148, v58, v74
	ds_write_b32 v151, v148 offset:5984
	v_fmac_f32_e32 v59, v116, v58
	v_fmac_f32_e32 v75, v118, v74
	v_fmac_f32_dpp v59, v58, v122 quad_perm:[1,0,3,2] row_mask:0xf bank_mask:0xf
	v_fmac_f32_dpp v75, v74, v123 quad_perm:[1,0,3,2] row_mask:0xf bank_mask:0xf
	v_cvt_pk_bf16_f32 v149, v59, v75
	ds_write_b32 v151, v149 offset:6256
	v_fmac_f32_e32 v28, v116, v59
	v_fmac_f32_e32 v44, v118, v75
	v_fmac_f32_dpp v28, v59, v122 quad_perm:[1,0,3,2] row_mask:0xf bank_mask:0xf
	v_fmac_f32_dpp v44, v75, v123 quad_perm:[1,0,3,2] row_mask:0xf bank_mask:0xf
	v_cvt_pk_bf16_f32 v148, v28, v44
	ds_write_b32 v151, v148 offset:6528
	v_fmac_f32_e32 v29, v116, v28
	v_fmac_f32_e32 v45, v118, v44
	v_fmac_f32_dpp v29, v28, v122 quad_perm:[1,0,3,2] row_mask:0xf bank_mask:0xf
	v_fmac_f32_dpp v45, v44, v123 quad_perm:[1,0,3,2] row_mask:0xf bank_mask:0xf
	v_cvt_pk_bf16_f32 v149, v29, v45
	ds_write_b32 v151, v149 offset:6800
	v_fmac_f32_e32 v30, v116, v29
	v_fmac_f32_e32 v46, v118, v45
	v_fmac_f32_dpp v30, v29, v122 quad_perm:[1,0,3,2] row_mask:0xf bank_mask:0xf
	v_fmac_f32_dpp v46, v45, v123 quad_perm:[1,0,3,2] row_mask:0xf bank_mask:0xf
	v_cvt_pk_bf16_f32 v148, v30, v46
	ds_write_b32 v151, v148 offset:7072
	v_fmac_f32_e32 v31, v116, v30
	v_fmac_f32_e32 v47, v118, v46
	v_fmac_f32_dpp v31, v30, v122 quad_perm:[1,0,3,2] row_mask:0xf bank_mask:0xf
	v_fmac_f32_dpp v47, v46, v123 quad_perm:[1,0,3,2] row_mask:0xf bank_mask:0xf
	v_cvt_pk_bf16_f32 v149, v31, v47
	ds_write_b32 v151, v149 offset:7344
	v_fmac_f32_e32 v60, v116, v31
	v_fmac_f32_e32 v76, v118, v47
	v_fmac_f32_dpp v60, v31, v122 quad_perm:[1,0,3,2] row_mask:0xf bank_mask:0xf
	v_fmac_f32_dpp v76, v47, v123 quad_perm:[1,0,3,2] row_mask:0xf bank_mask:0xf
	v_cvt_pk_bf16_f32 v148, v60, v76
	ds_write_b32 v151, v148 offset:7616
	v_fmac_f32_e32 v61, v116, v60
	v_fmac_f32_e32 v77, v118, v76
	v_fmac_f32_dpp v61, v60, v122 quad_perm:[1,0,3,2] row_mask:0xf bank_mask:0xf
	v_fmac_f32_dpp v77, v76, v123 quad_perm:[1,0,3,2] row_mask:0xf bank_mask:0xf
	v_cvt_pk_bf16_f32 v149, v61, v77
	ds_write_b32 v151, v149 offset:7888
	v_fmac_f32_e32 v62, v116, v61
	v_fmac_f32_e32 v78, v118, v77
	v_fmac_f32_dpp v62, v61, v122 quad_perm:[1,0,3,2] row_mask:0xf bank_mask:0xf
	v_fmac_f32_dpp v78, v77, v123 quad_perm:[1,0,3,2] row_mask:0xf bank_mask:0xf
	v_cvt_pk_bf16_f32 v148, v62, v78
	ds_write_b32 v151, v148 offset:8160
	v_fmac_f32_e32 v63, v116, v62
	v_fmac_f32_e32 v79, v118, v78
	v_fmac_f32_dpp v63, v62, v122 quad_perm:[1,0,3,2] row_mask:0xf bank_mask:0xf
	v_fmac_f32_dpp v79, v78, v123 quad_perm:[1,0,3,2] row_mask:0xf bank_mask:0xf
	v_cvt_pk_bf16_f32 v149, v63, v79
	ds_write_b32 v151, v149 offset:8432
	v_mov_b32_e32 v120, v63
	v_mov_b32_e32 v121, v79
	ds_read_b128 v[124:127], v152
	ds_read_b128 v[128:131], v152 offset:64
	ds_read_b128 v[132:135], v152 offset:128
	ds_read_b128 v[136:139], v152 offset:192
	ds_read_b64 v[160:161], v163
	s_waitcnt lgkmcnt(4)
	v_mfma_f32_16x16x32_bf16 v[140:143], v[100:103], v[124:127], 0
	s_waitcnt lgkmcnt(3)
	v_mfma_f32_16x16x32_bf16 v[140:143], v[104:107], v[128:131], v[140:143]
	s_waitcnt lgkmcnt(2)
	v_mfma_f32_16x16x32_bf16 v[140:143], v[108:111], v[132:135], v[140:143]
	s_waitcnt lgkmcnt(1)
	v_mfma_f32_16x16x32_bf16 v[140:143], v[112:115], v[136:139], v[140:143]
	s_nop 9
	s_waitcnt vmcnt(7) lgkmcnt(0)
	v_add_f32_e32 v182, v6, v140
	v_add_f32_e32 v183, v7, v141
	v_add_f32_e32 v184, v8, v142
	v_add_f32_e32 v185, v9, v143
	v_lshlrev_b32_e32 v186, 16, v160
	v_and_b32_e32 v187, 0xffff0000, v160
	v_lshlrev_b32_e32 v188, 16, v161
	v_and_b32_e32 v189, 0xffff0000, v161
	v_fmac_f32_e32 v182, v164, v186
	v_fmac_f32_e32 v183, v165, v187
	v_fmac_f32_e32 v184, v166, v188
	v_fmac_f32_e32 v185, v167, v189
	v_mul_f32_e32 v186, 0x3d372713, v182
	v_mul_f32_e32 v187, 0x3d372713, v183
	v_mul_f32_e32 v188, 0x3d372713, v184
	v_mul_f32_e32 v189, 0x3d372713, v185
	v_mul_f32_e32 v186, v182, v186
	v_mul_f32_e32 v187, v183, v187
	v_mul_f32_e32 v188, v184, v188
	v_mul_f32_e32 v189, v185, v189
	v_fma_f32 v186, v182, v186, v182
	v_fma_f32 v187, v183, v187, v183
	v_fma_f32 v188, v184, v188, v184
	v_fma_f32 v189, v185, v189, v185
	v_mul_f32_e32 v186, 0xbfcc422a, v186
	v_mul_f32_e32 v187, 0xbfcc422a, v187
	v_mul_f32_e32 v188, 0xbfcc422a, v188
	v_mul_f32_e32 v189, 0xbfcc422a, v189
	v_mul_f32_e32 v186, 0x3fb8aa3b, v186
	v_mul_f32_e32 v187, 0x3fb8aa3b, v187
	v_mul_f32_e32 v188, 0x3fb8aa3b, v188
	v_mul_f32_e32 v189, 0x3fb8aa3b, v189
	v_exp_f32_e32 v186, v186
	v_exp_f32_e32 v187, v187
	v_exp_f32_e32 v188, v188
	v_exp_f32_e32 v189, v189
	v_add_f32_e32 v186, 1.0, v186
	v_add_f32_e32 v187, 1.0, v187
	v_add_f32_e32 v188, 1.0, v188
	v_add_f32_e32 v189, 1.0, v189
	v_rcp_f32_e32 v186, v186
	v_rcp_f32_e32 v187, v187
	v_rcp_f32_e32 v188, v188
	v_rcp_f32_e32 v189, v189
	v_mul_f32_e32 v182, v182, v186
	v_mul_f32_e32 v183, v183, v187
	v_mul_f32_e32 v184, v184, v188
	v_mul_f32_e32 v185, v185, v189
	v_cvt_pk_bf16_f32 v148, v182, v183
	v_cvt_pk_bf16_f32 v149, v184, v185
	global_store_dwordx2 v156, v[148:149], s[12:13]
	ds_read_b128 v[124:127], v152 offset:4352
	ds_read_b128 v[128:131], v152 offset:4416
	ds_read_b128 v[132:135], v152 offset:4480
	ds_read_b128 v[136:139], v152 offset:4544
	ds_read_b64 v[160:161], v163 offset:512
	s_waitcnt lgkmcnt(4)
	v_mfma_f32_16x16x32_bf16 v[140:143], v[100:103], v[124:127], 0
	s_waitcnt lgkmcnt(3)
	v_mfma_f32_16x16x32_bf16 v[140:143], v[104:107], v[128:131], v[140:143]
	s_waitcnt lgkmcnt(2)
	v_mfma_f32_16x16x32_bf16 v[140:143], v[108:111], v[132:135], v[140:143]
	s_waitcnt lgkmcnt(1)
	v_mfma_f32_16x16x32_bf16 v[140:143], v[112:115], v[136:139], v[140:143]
	s_nop 9
	s_waitcnt vmcnt(7) lgkmcnt(0)
	v_add_f32_e32 v182, v10, v140
	v_add_f32_e32 v183, v11, v141
	v_add_f32_e32 v184, v12, v142
	v_add_f32_e32 v185, v13, v143
	v_lshlrev_b32_e32 v186, 16, v160
	v_and_b32_e32 v187, 0xffff0000, v160
	v_lshlrev_b32_e32 v188, 16, v161
	v_and_b32_e32 v189, 0xffff0000, v161
	v_fmac_f32_e32 v182, v164, v186
	v_fmac_f32_e32 v183, v165, v187
	v_fmac_f32_e32 v184, v166, v188
	v_fmac_f32_e32 v185, v167, v189
	v_mul_f32_e32 v186, 0x3d372713, v182
	v_mul_f32_e32 v187, 0x3d372713, v183
	v_mul_f32_e32 v188, 0x3d372713, v184
	v_mul_f32_e32 v189, 0x3d372713, v185
	v_mul_f32_e32 v186, v182, v186
	v_mul_f32_e32 v187, v183, v187
	v_mul_f32_e32 v188, v184, v188
	v_mul_f32_e32 v189, v185, v189
	v_fma_f32 v186, v182, v186, v182
	v_fma_f32 v187, v183, v187, v183
	v_fma_f32 v188, v184, v188, v184
	v_fma_f32 v189, v185, v189, v185
	v_mul_f32_e32 v186, 0xbfcc422a, v186
	v_mul_f32_e32 v187, 0xbfcc422a, v187
	v_mul_f32_e32 v188, 0xbfcc422a, v188
	v_mul_f32_e32 v189, 0xbfcc422a, v189
	v_mul_f32_e32 v186, 0x3fb8aa3b, v186
	v_mul_f32_e32 v187, 0x3fb8aa3b, v187
	v_mul_f32_e32 v188, 0x3fb8aa3b, v188
	v_mul_f32_e32 v189, 0x3fb8aa3b, v189
	v_exp_f32_e32 v186, v186
	v_exp_f32_e32 v187, v187
	v_exp_f32_e32 v188, v188
	v_exp_f32_e32 v189, v189
	v_add_f32_e32 v186, 1.0, v186
	v_add_f32_e32 v187, 1.0, v187
	v_add_f32_e32 v188, 1.0, v188
	v_add_f32_e32 v189, 1.0, v189
	v_rcp_f32_e32 v186, v186
	v_rcp_f32_e32 v187, v187
	v_rcp_f32_e32 v188, v188
	v_rcp_f32_e32 v189, v189
	v_mul_f32_e32 v182, v182, v186
	v_mul_f32_e32 v183, v183, v187
	v_mul_f32_e32 v184, v184, v188
	v_mul_f32_e32 v185, v185, v189
	v_cvt_pk_bf16_f32 v148, v182, v183
	v_cvt_pk_bf16_f32 v149, v184, v185
	global_store_dwordx2 v159, v[148:149], s[12:13]
	s_add_u32 s12, s12, 65536
	s_addc_u32 s13, s13, 0
	s_waitcnt vmcnt(7)
	v_mfma_f32_32x32x16_bf16 v[16:31], v[144:147], v[84:87], 0
	v_mfma_f32_32x32x16_bf16 v[32:47], v[144:147], v[88:91], 0
	v_mfma_f32_32x32x16_bf16 v[48:63], v[144:147], v[92:95], 0
	v_mfma_f32_32x32x16_bf16 v[64:79], v[144:147], v[96:99], 0
	ds_write_b128 v162, v[144:147]
	global_load_dwordx4 v[6:9], v153, s[42:43]
	global_load_dwordx4 v[10:13], v157, s[42:43]
	s_add_u32 s42, s42, 131072
	s_addc_u32 s43, s43, 0
	s_nop 11
	global_load_dwordx4 v[144:147], v150, s[10:11]
	s_add_u32 s34, s34, 196608
	s_addc_u32 s35, s35, 0
	s_add_u32 s10, s10, 196608
	s_addc_u32 s11, s11, 0
	v_permlane32_swap_b32_e32 v16, v48
	v_permlane32_swap_b32_e32 v17, v49
	v_permlane32_swap_b32_e32 v18, v50
	v_permlane32_swap_b32_e32 v19, v51
	v_permlane32_swap_b32_e32 v20, v52
	v_permlane32_swap_b32_e32 v21, v53
	v_permlane32_swap_b32_e32 v22, v54
	v_permlane32_swap_b32_e32 v23, v55
	v_permlane32_swap_b32_e32 v24, v56
	v_permlane32_swap_b32_e32 v25, v57
	v_permlane32_swap_b32_e32 v26, v58
	v_permlane32_swap_b32_e32 v27, v59
	v_permlane32_swap_b32_e32 v28, v60
	v_permlane32_swap_b32_e32 v29, v61
	v_permlane32_swap_b32_e32 v30, v62
	v_permlane32_swap_b32_e32 v31, v63
	v_permlane32_swap_b32_e32 v32, v64
	v_permlane32_swap_b32_e32 v33, v65
	v_permlane32_swap_b32_e32 v34, v66
	v_permlane32_swap_b32_e32 v35, v67
	v_permlane32_swap_b32_e32 v36, v68
	v_permlane32_swap_b32_e32 v37, v69
	v_permlane32_swap_b32_e32 v38, v70
	v_permlane32_swap_b32_e32 v39, v71
	v_permlane32_swap_b32_e32 v40, v72
	v_permlane32_swap_b32_e32 v41, v73
	v_permlane32_swap_b32_e32 v42, v74
	v_permlane32_swap_b32_e32 v43, v75
	v_permlane32_swap_b32_e32 v44, v76
	v_permlane32_swap_b32_e32 v45, v77
	v_permlane32_swap_b32_e32 v46, v78
	v_permlane32_swap_b32_e32 v47, v79
	v_fmac_f32_e32 v16, v116, v120
	v_fmac_f32_e32 v32, v118, v121
	v_fmac_f32_dpp v16, v120, v122 quad_perm:[1,0,3,2] row_mask:0xf bank_mask:0xf
	v_fmac_f32_dpp v32, v121, v123 quad_perm:[1,0,3,2] row_mask:0xf bank_mask:0xf
	v_cvt_pk_bf16_f32 v148, v16, v32
	ds_write_b32 v151, v148
	v_fmac_f32_e32 v17, v116, v16
	v_fmac_f32_e32 v33, v118, v32
	v_fmac_f32_dpp v17, v16, v122 quad_perm:[1,0,3,2] row_mask:0xf bank_mask:0xf
	v_fmac_f32_dpp v33, v32, v123 quad_perm:[1,0,3,2] row_mask:0xf bank_mask:0xf
	v_cvt_pk_bf16_f32 v149, v17, v33
	ds_write_b32 v151, v149 offset:272
	v_fmac_f32_e32 v18, v116, v17
	v_fmac_f32_e32 v34, v118, v33
	v_fmac_f32_dpp v18, v17, v122 quad_perm:[1,0,3,2] row_mask:0xf bank_mask:0xf
	v_fmac_f32_dpp v34, v33, v123 quad_perm:[1,0,3,2] row_mask:0xf bank_mask:0xf
	v_cvt_pk_bf16_f32 v148, v18, v34
	ds_write_b32 v151, v148 offset:544
	v_fmac_f32_e32 v19, v116, v18
	v_fmac_f32_e32 v35, v118, v34
	v_fmac_f32_dpp v19, v18, v122 quad_perm:[1,0,3,2] row_mask:0xf bank_mask:0xf
	v_fmac_f32_dpp v35, v34, v123 quad_perm:[1,0,3,2] row_mask:0xf bank_mask:0xf
	v_cvt_pk_bf16_f32 v149, v19, v35
	ds_write_b32 v151, v149 offset:816
	v_fmac_f32_e32 v48, v116, v19
	v_fmac_f32_e32 v64, v118, v35
	v_fmac_f32_dpp v48, v19, v122 quad_perm:[1,0,3,2] row_mask:0xf bank_mask:0xf
	v_fmac_f32_dpp v64, v35, v123 quad_perm:[1,0,3,2] row_mask:0xf bank_mask:0xf
	v_cvt_pk_bf16_f32 v148, v48, v64
	ds_write_b32 v151, v148 offset:1088
	v_fmac_f32_e32 v49, v116, v48
	v_fmac_f32_e32 v65, v118, v64
	v_fmac_f32_dpp v49, v48, v122 quad_perm:[1,0,3,2] row_mask:0xf bank_mask:0xf
	v_fmac_f32_dpp v65, v64, v123 quad_perm:[1,0,3,2] row_mask:0xf bank_mask:0xf
	v_cvt_pk_bf16_f32 v149, v49, v65
	ds_write_b32 v151, v149 offset:1360
	v_fmac_f32_e32 v50, v116, v49
	v_fmac_f32_e32 v66, v118, v65
	v_fmac_f32_dpp v50, v49, v122 quad_perm:[1,0,3,2] row_mask:0xf bank_mask:0xf
	v_fmac_f32_dpp v66, v65, v123 quad_perm:[1,0,3,2] row_mask:0xf bank_mask:0xf
	v_cvt_pk_bf16_f32 v148, v50, v66
	ds_write_b32 v151, v148 offset:1632
	v_fmac_f32_e32 v51, v116, v50
	v_fmac_f32_e32 v67, v118, v66
	v_fmac_f32_dpp v51, v50, v122 quad_perm:[1,0,3,2] row_mask:0xf bank_mask:0xf
	v_fmac_f32_dpp v67, v66, v123 quad_perm:[1,0,3,2] row_mask:0xf bank_mask:0xf
	v_cvt_pk_bf16_f32 v149, v51, v67
	ds_write_b32 v151, v149 offset:1904
	v_fmac_f32_e32 v20, v116, v51
	v_fmac_f32_e32 v36, v118, v67
	v_fmac_f32_dpp v20, v51, v122 quad_perm:[1,0,3,2] row_mask:0xf bank_mask:0xf
	v_fmac_f32_dpp v36, v67, v123 quad_perm:[1,0,3,2] row_mask:0xf bank_mask:0xf
	v_cvt_pk_bf16_f32 v148, v20, v36
	ds_write_b32 v151, v148 offset:2176
	v_fmac_f32_e32 v21, v116, v20
	v_fmac_f32_e32 v37, v118, v36
	v_fmac_f32_dpp v21, v20, v122 quad_perm:[1,0,3,2] row_mask:0xf bank_mask:0xf
	v_fmac_f32_dpp v37, v36, v123 quad_perm:[1,0,3,2] row_mask:0xf bank_mask:0xf
	v_cvt_pk_bf16_f32 v149, v21, v37
	ds_write_b32 v151, v149 offset:2448
	v_fmac_f32_e32 v22, v116, v21
	v_fmac_f32_e32 v38, v118, v37
	v_fmac_f32_dpp v22, v21, v122 quad_perm:[1,0,3,2] row_mask:0xf bank_mask:0xf
	v_fmac_f32_dpp v38, v37, v123 quad_perm:[1,0,3,2] row_mask:0xf bank_mask:0xf
	v_cvt_pk_bf16_f32 v148, v22, v38
	ds_write_b32 v151, v148 offset:2720
	v_fmac_f32_e32 v23, v116, v22
	v_fmac_f32_e32 v39, v118, v38
	v_fmac_f32_dpp v23, v22, v122 quad_perm:[1,0,3,2] row_mask:0xf bank_mask:0xf
	v_fmac_f32_dpp v39, v38, v123 quad_perm:[1,0,3,2] row_mask:0xf bank_mask:0xf
	v_cvt_pk_bf16_f32 v149, v23, v39
	ds_write_b32 v151, v149 offset:2992
	v_fmac_f32_e32 v52, v116, v23
	v_fmac_f32_e32 v68, v118, v39
	v_fmac_f32_dpp v52, v23, v122 quad_perm:[1,0,3,2] row_mask:0xf bank_mask:0xf
	v_fmac_f32_dpp v68, v39, v123 quad_perm:[1,0,3,2] row_mask:0xf bank_mask:0xf
	v_cvt_pk_bf16_f32 v148, v52, v68
	ds_write_b32 v151, v148 offset:3264
	v_fmac_f32_e32 v53, v116, v52
	v_fmac_f32_e32 v69, v118, v68
	v_fmac_f32_dpp v53, v52, v122 quad_perm:[1,0,3,2] row_mask:0xf bank_mask:0xf
	v_fmac_f32_dpp v69, v68, v123 quad_perm:[1,0,3,2] row_mask:0xf bank_mask:0xf
	v_cvt_pk_bf16_f32 v149, v53, v69
	ds_write_b32 v151, v149 offset:3536
	v_fmac_f32_e32 v54, v116, v53
	v_fmac_f32_e32 v70, v118, v69
	v_fmac_f32_dpp v54, v53, v122 quad_perm:[1,0,3,2] row_mask:0xf bank_mask:0xf
	v_fmac_f32_dpp v70, v69, v123 quad_perm:[1,0,3,2] row_mask:0xf bank_mask:0xf
	v_cvt_pk_bf16_f32 v148, v54, v70
	ds_write_b32 v151, v148 offset:3808
	v_fmac_f32_e32 v55, v116, v54
	v_fmac_f32_e32 v71, v118, v70
	v_fmac_f32_dpp v55, v54, v122 quad_perm:[1,0,3,2] row_mask:0xf bank_mask:0xf
	v_fmac_f32_dpp v71, v70, v123 quad_perm:[1,0,3,2] row_mask:0xf bank_mask:0xf
	v_cvt_pk_bf16_f32 v149, v55, v71
	ds_write_b32 v151, v149 offset:4080
	v_fmac_f32_e32 v24, v116, v55
	v_fmac_f32_e32 v40, v118, v71
	v_fmac_f32_dpp v24, v55, v122 quad_perm:[1,0,3,2] row_mask:0xf bank_mask:0xf
	v_fmac_f32_dpp v40, v71, v123 quad_perm:[1,0,3,2] row_mask:0xf bank_mask:0xf
	v_cvt_pk_bf16_f32 v148, v24, v40
	ds_write_b32 v151, v148 offset:4352
	v_fmac_f32_e32 v25, v116, v24
	v_fmac_f32_e32 v41, v118, v40
	v_fmac_f32_dpp v25, v24, v122 quad_perm:[1,0,3,2] row_mask:0xf bank_mask:0xf
	v_fmac_f32_dpp v41, v40, v123 quad_perm:[1,0,3,2] row_mask:0xf bank_mask:0xf
	v_cvt_pk_bf16_f32 v149, v25, v41
	ds_write_b32 v151, v149 offset:4624
	v_fmac_f32_e32 v26, v116, v25
	v_fmac_f32_e32 v42, v118, v41
	v_fmac_f32_dpp v26, v25, v122 quad_perm:[1,0,3,2] row_mask:0xf bank_mask:0xf
	v_fmac_f32_dpp v42, v41, v123 quad_perm:[1,0,3,2] row_mask:0xf bank_mask:0xf
	v_cvt_pk_bf16_f32 v148, v26, v42
	ds_write_b32 v151, v148 offset:4896
	v_fmac_f32_e32 v27, v116, v26
	v_fmac_f32_e32 v43, v118, v42
	v_fmac_f32_dpp v27, v26, v122 quad_perm:[1,0,3,2] row_mask:0xf bank_mask:0xf
	v_fmac_f32_dpp v43, v42, v123 quad_perm:[1,0,3,2] row_mask:0xf bank_mask:0xf
	v_cvt_pk_bf16_f32 v149, v27, v43
	ds_write_b32 v151, v149 offset:5168
	v_fmac_f32_e32 v56, v116, v27
	v_fmac_f32_e32 v72, v118, v43
	v_fmac_f32_dpp v56, v27, v122 quad_perm:[1,0,3,2] row_mask:0xf bank_mask:0xf
	v_fmac_f32_dpp v72, v43, v123 quad_perm:[1,0,3,2] row_mask:0xf bank_mask:0xf
	v_cvt_pk_bf16_f32 v148, v56, v72
	ds_write_b32 v151, v148 offset:5440
	v_fmac_f32_e32 v57, v116, v56
	v_fmac_f32_e32 v73, v118, v72
	v_fmac_f32_dpp v57, v56, v122 quad_perm:[1,0,3,2] row_mask:0xf bank_mask:0xf
	v_fmac_f32_dpp v73, v72, v123 quad_perm:[1,0,3,2] row_mask:0xf bank_mask:0xf
	v_cvt_pk_bf16_f32 v149, v57, v73
	ds_write_b32 v151, v149 offset:5712
	v_fmac_f32_e32 v58, v116, v57
	v_fmac_f32_e32 v74, v118, v73
	v_fmac_f32_dpp v58, v57, v122 quad_perm:[1,0,3,2] row_mask:0xf bank_mask:0xf
	v_fmac_f32_dpp v74, v73, v123 quad_perm:[1,0,3,2] row_mask:0xf bank_mask:0xf
	v_cvt_pk_bf16_f32 v148, v58, v74
	ds_write_b32 v151, v148 offset:5984
	v_fmac_f32_e32 v59, v116, v58
	v_fmac_f32_e32 v75, v118, v74
	v_fmac_f32_dpp v59, v58, v122 quad_perm:[1,0,3,2] row_mask:0xf bank_mask:0xf
	v_fmac_f32_dpp v75, v74, v123 quad_perm:[1,0,3,2] row_mask:0xf bank_mask:0xf
	v_cvt_pk_bf16_f32 v149, v59, v75
	ds_write_b32 v151, v149 offset:6256
	v_fmac_f32_e32 v28, v116, v59
	v_fmac_f32_e32 v44, v118, v75
	v_fmac_f32_dpp v28, v59, v122 quad_perm:[1,0,3,2] row_mask:0xf bank_mask:0xf
	v_fmac_f32_dpp v44, v75, v123 quad_perm:[1,0,3,2] row_mask:0xf bank_mask:0xf
	v_cvt_pk_bf16_f32 v148, v28, v44
	ds_write_b32 v151, v148 offset:6528
	v_fmac_f32_e32 v29, v116, v28
	v_fmac_f32_e32 v45, v118, v44
	v_fmac_f32_dpp v29, v28, v122 quad_perm:[1,0,3,2] row_mask:0xf bank_mask:0xf
	v_fmac_f32_dpp v45, v44, v123 quad_perm:[1,0,3,2] row_mask:0xf bank_mask:0xf
	v_cvt_pk_bf16_f32 v149, v29, v45
	ds_write_b32 v151, v149 offset:6800
	v_fmac_f32_e32 v30, v116, v29
	v_fmac_f32_e32 v46, v118, v45
	v_fmac_f32_dpp v30, v29, v122 quad_perm:[1,0,3,2] row_mask:0xf bank_mask:0xf
	v_fmac_f32_dpp v46, v45, v123 quad_perm:[1,0,3,2] row_mask:0xf bank_mask:0xf
	v_cvt_pk_bf16_f32 v148, v30, v46
	ds_write_b32 v151, v148 offset:7072
	v_fmac_f32_e32 v31, v116, v30
	v_fmac_f32_e32 v47, v118, v46
	v_fmac_f32_dpp v31, v30, v122 quad_perm:[1,0,3,2] row_mask:0xf bank_mask:0xf
	v_fmac_f32_dpp v47, v46, v123 quad_perm:[1,0,3,2] row_mask:0xf bank_mask:0xf
	v_cvt_pk_bf16_f32 v149, v31, v47
	ds_write_b32 v151, v149 offset:7344
	v_fmac_f32_e32 v60, v116, v31
	v_fmac_f32_e32 v76, v118, v47
	v_fmac_f32_dpp v60, v31, v122 quad_perm:[1,0,3,2] row_mask:0xf bank_mask:0xf
	v_fmac_f32_dpp v76, v47, v123 quad_perm:[1,0,3,2] row_mask:0xf bank_mask:0xf
	v_cvt_pk_bf16_f32 v148, v60, v76
	ds_write_b32 v151, v148 offset:7616
	v_fmac_f32_e32 v61, v116, v60
	v_fmac_f32_e32 v77, v118, v76
	v_fmac_f32_dpp v61, v60, v122 quad_perm:[1,0,3,2] row_mask:0xf bank_mask:0xf
	v_fmac_f32_dpp v77, v76, v123 quad_perm:[1,0,3,2] row_mask:0xf bank_mask:0xf
	v_cvt_pk_bf16_f32 v149, v61, v77
	ds_write_b32 v151, v149 offset:7888
	v_fmac_f32_e32 v62, v116, v61
	v_fmac_f32_e32 v78, v118, v77
	v_fmac_f32_dpp v62, v61, v122 quad_perm:[1,0,3,2] row_mask:0xf bank_mask:0xf
	v_fmac_f32_dpp v78, v77, v123 quad_perm:[1,0,3,2] row_mask:0xf bank_mask:0xf
	v_cvt_pk_bf16_f32 v148, v62, v78
	ds_write_b32 v151, v148 offset:8160
	v_fmac_f32_e32 v63, v116, v62
	v_fmac_f32_e32 v79, v118, v78
	v_fmac_f32_dpp v63, v62, v122 quad_perm:[1,0,3,2] row_mask:0xf bank_mask:0xf
	v_fmac_f32_dpp v79, v78, v123 quad_perm:[1,0,3,2] row_mask:0xf bank_mask:0xf
	v_cvt_pk_bf16_f32 v149, v63, v79
	ds_write_b32 v151, v149 offset:8432
	v_mov_b32_e32 v120, v63
	v_mov_b32_e32 v121, v79
	ds_read_b128 v[124:127], v152
	ds_read_b128 v[128:131], v152 offset:64
	ds_read_b128 v[132:135], v152 offset:128
	ds_read_b128 v[136:139], v152 offset:192
	ds_read_b64 v[160:161], v163
	s_waitcnt lgkmcnt(4)
	v_mfma_f32_16x16x32_bf16 v[140:143], v[100:103], v[124:127], 0
	s_waitcnt lgkmcnt(3)
	v_mfma_f32_16x16x32_bf16 v[140:143], v[104:107], v[128:131], v[140:143]
	s_waitcnt lgkmcnt(2)
	v_mfma_f32_16x16x32_bf16 v[140:143], v[108:111], v[132:135], v[140:143]
	s_waitcnt lgkmcnt(1)
	v_mfma_f32_16x16x32_bf16 v[140:143], v[112:115], v[136:139], v[140:143]
	s_nop 9
	s_waitcnt vmcnt(7) lgkmcnt(0)
	v_add_f32_e32 v182, v172, v140
	v_add_f32_e32 v183, v173, v141
	v_add_f32_e32 v184, v174, v142
	v_add_f32_e32 v185, v175, v143
	v_lshlrev_b32_e32 v186, 16, v160
	v_and_b32_e32 v187, 0xffff0000, v160
	v_lshlrev_b32_e32 v188, 16, v161
	v_and_b32_e32 v189, 0xffff0000, v161
	v_fmac_f32_e32 v182, v164, v186
	v_fmac_f32_e32 v183, v165, v187
	v_fmac_f32_e32 v184, v166, v188
	v_fmac_f32_e32 v185, v167, v189
	v_mul_f32_e32 v186, 0x3d372713, v182
	v_mul_f32_e32 v187, 0x3d372713, v183
	v_mul_f32_e32 v188, 0x3d372713, v184
	v_mul_f32_e32 v189, 0x3d372713, v185
	v_mul_f32_e32 v186, v182, v186
	v_mul_f32_e32 v187, v183, v187
	v_mul_f32_e32 v188, v184, v188
	v_mul_f32_e32 v189, v185, v189
	v_fma_f32 v186, v182, v186, v182
	v_fma_f32 v187, v183, v187, v183
	v_fma_f32 v188, v184, v188, v184
	v_fma_f32 v189, v185, v189, v185
	v_mul_f32_e32 v186, 0xbfcc422a, v186
	v_mul_f32_e32 v187, 0xbfcc422a, v187
	v_mul_f32_e32 v188, 0xbfcc422a, v188
	v_mul_f32_e32 v189, 0xbfcc422a, v189
	v_mul_f32_e32 v186, 0x3fb8aa3b, v186
	v_mul_f32_e32 v187, 0x3fb8aa3b, v187
	v_mul_f32_e32 v188, 0x3fb8aa3b, v188
	v_mul_f32_e32 v189, 0x3fb8aa3b, v189
	v_exp_f32_e32 v186, v186
	v_exp_f32_e32 v187, v187
	v_exp_f32_e32 v188, v188
	v_exp_f32_e32 v189, v189
	v_add_f32_e32 v186, 1.0, v186
	v_add_f32_e32 v187, 1.0, v187
	v_add_f32_e32 v188, 1.0, v188
	v_add_f32_e32 v189, 1.0, v189
	v_rcp_f32_e32 v186, v186
	v_rcp_f32_e32 v187, v187
	v_rcp_f32_e32 v188, v188
	v_rcp_f32_e32 v189, v189
	v_mul_f32_e32 v182, v182, v186
	v_mul_f32_e32 v183, v183, v187
	v_mul_f32_e32 v184, v184, v188
	v_mul_f32_e32 v185, v185, v189
	v_cvt_pk_bf16_f32 v148, v182, v183
	v_cvt_pk_bf16_f32 v149, v184, v185
	global_store_dwordx2 v156, v[148:149], s[12:13]
	ds_read_b128 v[124:127], v152 offset:4352
	ds_read_b128 v[128:131], v152 offset:4416
	ds_read_b128 v[132:135], v152 offset:4480
	ds_read_b128 v[136:139], v152 offset:4544
	ds_read_b64 v[160:161], v163 offset:512
	s_waitcnt lgkmcnt(4)
	v_mfma_f32_16x16x32_bf16 v[140:143], v[100:103], v[124:127], 0
	s_waitcnt lgkmcnt(3)
	v_mfma_f32_16x16x32_bf16 v[140:143], v[104:107], v[128:131], v[140:143]
	s_waitcnt lgkmcnt(2)
	v_mfma_f32_16x16x32_bf16 v[140:143], v[108:111], v[132:135], v[140:143]
	s_waitcnt lgkmcnt(1)
	v_mfma_f32_16x16x32_bf16 v[140:143], v[112:115], v[136:139], v[140:143]
	s_nop 9
	s_waitcnt vmcnt(7) lgkmcnt(0)
	v_add_f32_e32 v182, v176, v140
	v_add_f32_e32 v183, v177, v141
	v_add_f32_e32 v184, v178, v142
	v_add_f32_e32 v185, v179, v143
	v_lshlrev_b32_e32 v186, 16, v160
	v_and_b32_e32 v187, 0xffff0000, v160
	v_lshlrev_b32_e32 v188, 16, v161
	v_and_b32_e32 v189, 0xffff0000, v161
	v_fmac_f32_e32 v182, v164, v186
	v_fmac_f32_e32 v183, v165, v187
	v_fmac_f32_e32 v184, v166, v188
	v_fmac_f32_e32 v185, v167, v189
	v_mul_f32_e32 v186, 0x3d372713, v182
	v_mul_f32_e32 v187, 0x3d372713, v183
	v_mul_f32_e32 v188, 0x3d372713, v184
	v_mul_f32_e32 v189, 0x3d372713, v185
	v_mul_f32_e32 v186, v182, v186
	v_mul_f32_e32 v187, v183, v187
	v_mul_f32_e32 v188, v184, v188
	v_mul_f32_e32 v189, v185, v189
	v_fma_f32 v186, v182, v186, v182
	v_fma_f32 v187, v183, v187, v183
	v_fma_f32 v188, v184, v188, v184
	v_fma_f32 v189, v185, v189, v185
	v_mul_f32_e32 v186, 0xbfcc422a, v186
	v_mul_f32_e32 v187, 0xbfcc422a, v187
	v_mul_f32_e32 v188, 0xbfcc422a, v188
	v_mul_f32_e32 v189, 0xbfcc422a, v189
	v_mul_f32_e32 v186, 0x3fb8aa3b, v186
	v_mul_f32_e32 v187, 0x3fb8aa3b, v187
	v_mul_f32_e32 v188, 0x3fb8aa3b, v188
	v_mul_f32_e32 v189, 0x3fb8aa3b, v189
	v_exp_f32_e32 v186, v186
	v_exp_f32_e32 v187, v187
	v_exp_f32_e32 v188, v188
	v_exp_f32_e32 v189, v189
	v_add_f32_e32 v186, 1.0, v186
	v_add_f32_e32 v187, 1.0, v187
	v_add_f32_e32 v188, 1.0, v188
	v_add_f32_e32 v189, 1.0, v189
	v_rcp_f32_e32 v186, v186
	v_rcp_f32_e32 v187, v187
	v_rcp_f32_e32 v188, v188
	v_rcp_f32_e32 v189, v189
	v_mul_f32_e32 v182, v182, v186
	v_mul_f32_e32 v183, v183, v187
	v_mul_f32_e32 v184, v184, v188
	v_mul_f32_e32 v185, v185, v189
	v_cvt_pk_bf16_f32 v148, v182, v183
	v_cvt_pk_bf16_f32 v149, v184, v185
	global_store_dwordx2 v159, v[148:149], s[12:13]
	s_add_u32 s12, s12, 65536
	s_addc_u32 s13, s13, 0
	s_add_u32 s14, s14, 2
	s_cmp_lt_u32 s14, 32
	s_cbranch_scc1 .Lssm_tileB_d0m0
	s_waitcnt vmcnt(0) lgkmcnt(0)
	s_branch .Lssm_lat_join

.Lssm_spin_done_d1m0:
	s_mov_b64 s[42:43], s[12:13]
	s_sub_u32 s42, s42, 67108864
	s_subb_u32 s43, s43, 0
	s_lshl_b32 s31, s25, 11
	s_lshl_b32 s29, s24, 5
	s_add_u32 s31, s31, s29
	s_add_u32 s31, s31, 344915968
	s_add_u32 s12, s62, s31
	s_addc_u32 s13, s63, 0
	s_mov_b64 s[64:65], s[34:35]
	s_add_u32 s64, s64, 196608
	s_addc_u32 s65, s65, 0
	global_load_dwordx4 v[6:9], v153, s[42:43]
	global_load_dwordx4 v[10:13], v157, s[42:43]
	s_sub_u32 s42, s42, 131072
	s_subb_u32 s43, s43, 0
	s_waitcnt vmcnt(0)
.Lssm_tileB_d1m0:
	s_waitcnt vmcnt(7)
	v_mfma_f32_32x32x16_bf16 v[16:31], v[80:83], v[84:87], 0
	v_mfma_f32_32x32x16_bf16 v[32:47], v[80:83], v[88:91], 0
	v_mfma_f32_32x32x16_bf16 v[48:63], v[80:83], v[92:95], 0
	v_mfma_f32_32x32x16_bf16 v[64:79], v[80:83], v[96:99], 0
	ds_write_b128 v162, v[80:83]
	global_load_dwordx4 v[172:175], v153, s[42:43]
	global_load_dwordx4 v[176:179], v157, s[42:43]
	s_sub_u32 s42, s42, 131072
	s_subb_u32 s43, s43, 0
	s_nop 11
	global_load_dwordx4 v[80:83], v150, s[10:11]
	s_sub_u32 s34, s34, 196608
	s_subb_u32 s35, s35, 0
	s_sub_u32 s10, s10, 196608
	s_subb_u32 s11, s11, 0
	v_permlane32_swap_b32_e32 v16, v48
	v_permlane32_swap_b32_e32 v17, v49
	v_permlane32_swap_b32_e32 v18, v50
	v_permlane32_swap_b32_e32 v19, v51
	v_permlane32_swap_b32_e32 v20, v52
	v_permlane32_swap_b32_e32 v21, v53
	v_permlane32_swap_b32_e32 v22, v54
	v_permlane32_swap_b32_e32 v23, v55
	v_permlane32_swap_b32_e32 v24, v56
	v_permlane32_swap_b32_e32 v25, v57
	v_permlane32_swap_b32_e32 v26, v58
	v_permlane32_swap_b32_e32 v27, v59
	v_permlane32_swap_b32_e32 v28, v60
	v_permlane32_swap_b32_e32 v29, v61
	v_permlane32_swap_b32_e32 v30, v62
	v_permlane32_swap_b32_e32 v31, v63
	v_permlane32_swap_b32_e32 v32, v64
	v_permlane32_swap_b32_e32 v33, v65
	v_permlane32_swap_b32_e32 v34, v66
	v_permlane32_swap_b32_e32 v35, v67
	v_permlane32_swap_b32_e32 v36, v68
	v_permlane32_swap_b32_e32 v37, v69
	v_permlane32_swap_b32_e32 v38, v70
	v_permlane32_swap_b32_e32 v39, v71
	v_permlane32_swap_b32_e32 v40, v72
	v_permlane32_swap_b32_e32 v41, v73
	v_permlane32_swap_b32_e32 v42, v74
	v_permlane32_swap_b32_e32 v43, v75
	v_permlane32_swap_b32_e32 v44, v76
	v_permlane32_swap_b32_e32 v45, v77
	v_permlane32_swap_b32_e32 v46, v78
	v_permlane32_swap_b32_e32 v47, v79
	v_fmac_f32_e32 v63, v116, v120
	v_fmac_f32_e32 v79, v118, v121
	v_fmac_f32_dpp v63, v120, v122 quad_perm:[1,0,3,2] row_mask:0xf bank_mask:0xf
	v_fmac_f32_dpp v79, v121, v123 quad_perm:[1,0,3,2] row_mask:0xf bank_mask:0xf
	v_cvt_pk_bf16_f32 v148, v63, v79
	ds_write_b32 v151, v148 offset:8432
	v_fmac_f32_e32 v62, v116, v63
	v_fmac_f32_e32 v78, v118, v79
	v_fmac_f32_dpp v62, v63, v122 quad_perm:[1,0,3,2] row_mask:0xf bank_mask:0xf
	v_fmac_f32_dpp v78, v79, v123 quad_perm:[1,0,3,2] row_mask:0xf bank_mask:0xf
	v_cvt_pk_bf16_f32 v149, v62, v78
	ds_write_b32 v151, v149 offset:8160
	v_fmac_f32_e32 v61, v116, v62
	v_fmac_f32_e32 v77, v118, v78
	v_fmac_f32_dpp v61, v62, v122 quad_perm:[1,0,3,2] row_mask:0xf bank_mask:0xf
	v_fmac_f32_dpp v77, v78, v123 quad_perm:[1,0,3,2] row_mask:0xf bank_mask:0xf
	v_cvt_pk_bf16_f32 v148, v61, v77
	ds_write_b32 v151, v148 offset:7888
	v_fmac_f32_e32 v60, v116, v61
	v_fmac_f32_e32 v76, v118, v77
	v_fmac_f32_dpp v60, v61, v122 quad_perm:[1,0,3,2] row_mask:0xf bank_mask:0xf
	v_fmac_f32_dpp v76, v77, v123 quad_perm:[1,0,3,2] row_mask:0xf bank_mask:0xf
	v_cvt_pk_bf16_f32 v149, v60, v76
	ds_write_b32 v151, v149 offset:7616
	v_fmac_f32_e32 v31, v116, v60
	v_fmac_f32_e32 v47, v118, v76
	v_fmac_f32_dpp v31, v60, v122 quad_perm:[1,0,3,2] row_mask:0xf bank_mask:0xf
	v_fmac_f32_dpp v47, v76, v123 quad_perm:[1,0,3,2] row_mask:0xf bank_mask:0xf
	v_cvt_pk_bf16_f32 v148, v31, v47
	ds_write_b32 v151, v148 offset:7344
	v_fmac_f32_e32 v30, v116, v31
	v_fmac_f32_e32 v46, v118, v47
	v_fmac_f32_dpp v30, v31, v122 quad_perm:[1,0,3,2] row_mask:0xf bank_mask:0xf
	v_fmac_f32_dpp v46, v47, v123 quad_perm:[1,0,3,2] row_mask:0xf bank_mask:0xf
	v_cvt_pk_bf16_f32 v149, v30, v46
	ds_write_b32 v151, v149 offset:7072
	v_fmac_f32_e32 v29, v116, v30
	v_fmac_f32_e32 v45, v118, v46
	v_fmac_f32_dpp v29, v30, v122 quad_perm:[1,0,3,2] row_mask:0xf bank_mask:0xf
	v_fmac_f32_dpp v45, v46, v123 quad_perm:[1,0,3,2] row_mask:0xf bank_mask:0xf
	v_cvt_pk_bf16_f32 v148, v29, v45
	ds_write_b32 v151, v148 offset:6800
	v_fmac_f32_e32 v28, v116, v29
	v_fmac_f32_e32 v44, v118, v45
	v_fmac_f32_dpp v28, v29, v122 quad_perm:[1,0,3,2] row_mask:0xf bank_mask:0xf
	v_fmac_f32_dpp v44, v45, v123 quad_perm:[1,0,3,2] row_mask:0xf bank_mask:0xf
	v_cvt_pk_bf16_f32 v149, v28, v44
	ds_write_b32 v151, v149 offset:6528
	v_fmac_f32_e32 v59, v116, v28
	v_fmac_f32_e32 v75, v118, v44
	v_fmac_f32_dpp v59, v28, v122 quad_perm:[1,0,3,2] row_mask:0xf bank_mask:0xf
	v_fmac_f32_dpp v75, v44, v123 quad_perm:[1,0,3,2] row_mask:0xf bank_mask:0xf
	v_cvt_pk_bf16_f32 v148, v59, v75
	ds_write_b32 v151, v148 offset:6256
	v_fmac_f32_e32 v58, v116, v59
	v_fmac_f32_e32 v74, v118, v75
	v_fmac_f32_dpp v58, v59, v122 quad_perm:[1,0,3,2] row_mask:0xf bank_mask:0xf
	v_fmac_f32_dpp v74, v75, v123 quad_perm:[1,0,3,2] row_mask:0xf bank_mask:0xf
	v_cvt_pk_bf16_f32 v149, v58, v74
	ds_write_b32 v151, v149 offset:5984
	v_fmac_f32_e32 v57, v116, v58
	v_fmac_f32_e32 v73, v118, v74
	v_fmac_f32_dpp v57, v58, v122 quad_perm:[1,0,3,2] row_mask:0xf bank_mask:0xf
	v_fmac_f32_dpp v73, v74, v123 quad_perm:[1,0,3,2] row_mask:0xf bank_mask:0xf
	v_cvt_pk_bf16_f32 v148, v57, v73
	ds_write_b32 v151, v148 offset:5712
	v_fmac_f32_e32 v56, v116, v57
	v_fmac_f32_e32 v72, v118, v73
	v_fmac_f32_dpp v56, v57, v122 quad_perm:[1,0,3,2] row_mask:0xf bank_mask:0xf
	v_fmac_f32_dpp v72, v73, v123 quad_perm:[1,0,3,2] row_mask:0xf bank_mask:0xf
	v_cvt_pk_bf16_f32 v149, v56, v72
	ds_write_b32 v151, v149 offset:5440
	v_fmac_f32_e32 v27, v116, v56
	v_fmac_f32_e32 v43, v118, v72
	v_fmac_f32_dpp v27, v56, v122 quad_perm:[1,0,3,2] row_mask:0xf bank_mask:0xf
	v_fmac_f32_dpp v43, v72, v123 quad_perm:[1,0,3,2] row_mask:0xf bank_mask:0xf
	v_cvt_pk_bf16_f32 v148, v27, v43
	ds_write_b32 v151, v148 offset:5168
	v_fmac_f32_e32 v26, v116, v27
	v_fmac_f32_e32 v42, v118, v43
	v_fmac_f32_dpp v26, v27, v122 quad_perm:[1,0,3,2] row_mask:0xf bank_mask:0xf
	v_fmac_f32_dpp v42, v43, v123 quad_perm:[1,0,3,2] row_mask:0xf bank_mask:0xf
	v_cvt_pk_bf16_f32 v149, v26, v42
	ds_write_b32 v151, v149 offset:4896
	v_fmac_f32_e32 v25, v116, v26
	v_fmac_f32_e32 v41, v118, v42
	v_fmac_f32_dpp v25, v26, v122 quad_perm:[1,0,3,2] row_mask:0xf bank_mask:0xf
	v_fmac_f32_dpp v41, v42, v123 quad_perm:[1,0,3,2] row_mask:0xf bank_mask:0xf
	v_cvt_pk_bf16_f32 v148, v25, v41
	ds_write_b32 v151, v148 offset:4624
	v_fmac_f32_e32 v24, v116, v25
	v_fmac_f32_e32 v40, v118, v41
	v_fmac_f32_dpp v24, v25, v122 quad_perm:[1,0,3,2] row_mask:0xf bank_mask:0xf
	v_fmac_f32_dpp v40, v41, v123 quad_perm:[1,0,3,2] row_mask:0xf bank_mask:0xf
	v_cvt_pk_bf16_f32 v149, v24, v40
	ds_write_b32 v151, v149 offset:4352
	v_fmac_f32_e32 v55, v116, v24
	v_fmac_f32_e32 v71, v118, v40
	v_fmac_f32_dpp v55, v24, v122 quad_perm:[1,0,3,2] row_mask:0xf bank_mask:0xf
	v_fmac_f32_dpp v71, v40, v123 quad_perm:[1,0,3,2] row_mask:0xf bank_mask:0xf
	v_cvt_pk_bf16_f32 v148, v55, v71
	ds_write_b32 v151, v148 offset:4080
	v_fmac_f32_e32 v54, v116, v55
	v_fmac_f32_e32 v70, v118, v71
	v_fmac_f32_dpp v54, v55, v122 quad_perm:[1,0,3,2] row_mask:0xf bank_mask:0xf
	v_fmac_f32_dpp v70, v71, v123 quad_perm:[1,0,3,2] row_mask:0xf bank_mask:0xf
	v_cvt_pk_bf16_f32 v149, v54, v70
	ds_write_b32 v151, v149 offset:3808
	v_fmac_f32_e32 v53, v116, v54
	v_fmac_f32_e32 v69, v118, v70
	v_fmac_f32_dpp v53, v54, v122 quad_perm:[1,0,3,2] row_mask:0xf bank_mask:0xf
	v_fmac_f32_dpp v69, v70, v123 quad_perm:[1,0,3,2] row_mask:0xf bank_mask:0xf
	v_cvt_pk_bf16_f32 v148, v53, v69
	ds_write_b32 v151, v148 offset:3536
	v_fmac_f32_e32 v52, v116, v53
	v_fmac_f32_e32 v68, v118, v69
	v_fmac_f32_dpp v52, v53, v122 quad_perm:[1,0,3,2] row_mask:0xf bank_mask:0xf
	v_fmac_f32_dpp v68, v69, v123 quad_perm:[1,0,3,2] row_mask:0xf bank_mask:0xf
	v_cvt_pk_bf16_f32 v149, v52, v68
	ds_write_b32 v151, v149 offset:3264
	v_fmac_f32_e32 v23, v116, v52
	v_fmac_f32_e32 v39, v118, v68
	v_fmac_f32_dpp v23, v52, v122 quad_perm:[1,0,3,2] row_mask:0xf bank_mask:0xf
	v_fmac_f32_dpp v39, v68, v123 quad_perm:[1,0,3,2] row_mask:0xf bank_mask:0xf
	v_cvt_pk_bf16_f32 v148, v23, v39
	ds_write_b32 v151, v148 offset:2992
	v_fmac_f32_e32 v22, v116, v23
	v_fmac_f32_e32 v38, v118, v39
	v_fmac_f32_dpp v22, v23, v122 quad_perm:[1,0,3,2] row_mask:0xf bank_mask:0xf
	v_fmac_f32_dpp v38, v39, v123 quad_perm:[1,0,3,2] row_mask:0xf bank_mask:0xf
	v_cvt_pk_bf16_f32 v149, v22, v38
	ds_write_b32 v151, v149 offset:2720
	v_fmac_f32_e32 v21, v116, v22
	v_fmac_f32_e32 v37, v118, v38
	v_fmac_f32_dpp v21, v22, v122 quad_perm:[1,0,3,2] row_mask:0xf bank_mask:0xf
	v_fmac_f32_dpp v37, v38, v123 quad_perm:[1,0,3,2] row_mask:0xf bank_mask:0xf
	v_cvt_pk_bf16_f32 v148, v21, v37
	ds_write_b32 v151, v148 offset:2448
	v_fmac_f32_e32 v20, v116, v21
	v_fmac_f32_e32 v36, v118, v37
	v_fmac_f32_dpp v20, v21, v122 quad_perm:[1,0,3,2] row_mask:0xf bank_mask:0xf
	v_fmac_f32_dpp v36, v37, v123 quad_perm:[1,0,3,2] row_mask:0xf bank_mask:0xf
	v_cvt_pk_bf16_f32 v149, v20, v36
	ds_write_b32 v151, v149 offset:2176
	v_fmac_f32_e32 v51, v116, v20
	v_fmac_f32_e32 v67, v118, v36
	v_fmac_f32_dpp v51, v20, v122 quad_perm:[1,0,3,2] row_mask:0xf bank_mask:0xf
	v_fmac_f32_dpp v67, v36, v123 quad_perm:[1,0,3,2] row_mask:0xf bank_mask:0xf
	v_cvt_pk_bf16_f32 v148, v51, v67
	ds_write_b32 v151, v148 offset:1904
	v_fmac_f32_e32 v50, v116, v51
	v_fmac_f32_e32 v66, v118, v67
	v_fmac_f32_dpp v50, v51, v122 quad_perm:[1,0,3,2] row_mask:0xf bank_mask:0xf
	v_fmac_f32_dpp v66, v67, v123 quad_perm:[1,0,3,2] row_mask:0xf bank_mask:0xf
	v_cvt_pk_bf16_f32 v149, v50, v66
	ds_write_b32 v151, v149 offset:1632
	v_fmac_f32_e32 v49, v116, v50
	v_fmac_f32_e32 v65, v118, v66
	v_fmac_f32_dpp v49, v50, v122 quad_perm:[1,0,3,2] row_mask:0xf bank_mask:0xf
	v_fmac_f32_dpp v65, v66, v123 quad_perm:[1,0,3,2] row_mask:0xf bank_mask:0xf
	v_cvt_pk_bf16_f32 v148, v49, v65
	ds_write_b32 v151, v148 offset:1360
	v_fmac_f32_e32 v48, v116, v49
	v_fmac_f32_e32 v64, v118, v65
	v_fmac_f32_dpp v48, v49, v122 quad_perm:[1,0,3,2] row_mask:0xf bank_mask:0xf
	v_fmac_f32_dpp v64, v65, v123 quad_perm:[1,0,3,2] row_mask:0xf bank_mask:0xf
	v_cvt_pk_bf16_f32 v149, v48, v64
	ds_write_b32 v151, v149 offset:1088
	v_fmac_f32_e32 v19, v116, v48
	v_fmac_f32_e32 v35, v118, v64
	v_fmac_f32_dpp v19, v48, v122 quad_perm:[1,0,3,2] row_mask:0xf bank_mask:0xf
	v_fmac_f32_dpp v35, v64, v123 quad_perm:[1,0,3,2] row_mask:0xf bank_mask:0xf
	v_cvt_pk_bf16_f32 v148, v19, v35
	ds_write_b32 v151, v148 offset:816
	v_fmac_f32_e32 v18, v116, v19
	v_fmac_f32_e32 v34, v118, v35
	v_fmac_f32_dpp v18, v19, v122 quad_perm:[1,0,3,2] row_mask:0xf bank_mask:0xf
	v_fmac_f32_dpp v34, v35, v123 quad_perm:[1,0,3,2] row_mask:0xf bank_mask:0xf
	v_cvt_pk_bf16_f32 v149, v18, v34
	ds_write_b32 v151, v149 offset:544
	v_fmac_f32_e32 v17, v116, v18
	v_fmac_f32_e32 v33, v118, v34
	v_fmac_f32_dpp v17, v18, v122 quad_perm:[1,0,3,2] row_mask:0xf bank_mask:0xf
	v_fmac_f32_dpp v33, v34, v123 quad_perm:[1,0,3,2] row_mask:0xf bank_mask:0xf
	v_cvt_pk_bf16_f32 v148, v17, v33
	ds_write_b32 v151, v148 offset:272
	v_fmac_f32_e32 v16, v116, v17
	v_fmac_f32_e32 v32, v118, v33
	v_fmac_f32_dpp v16, v17, v122 quad_perm:[1,0,3,2] row_mask:0xf bank_mask:0xf
	v_fmac_f32_dpp v32, v33, v123 quad_perm:[1,0,3,2] row_mask:0xf bank_mask:0xf
	v_cvt_pk_bf16_f32 v149, v16, v32
	ds_write_b32 v151, v149
	v_mov_b32_e32 v120, v16
	v_mov_b32_e32 v121, v32
	ds_read_b128 v[124:127], v152
	ds_read_b128 v[128:131], v152 offset:64
	ds_read_b128 v[132:135], v152 offset:128
	ds_read_b128 v[136:139], v152 offset:192
	ds_read_b64 v[160:161], v163
	s_waitcnt lgkmcnt(4)
	v_mfma_f32_16x16x32_bf16 v[140:143], v[100:103], v[124:127], 0
	s_waitcnt lgkmcnt(3)
	v_mfma_f32_16x16x32_bf16 v[140:143], v[104:107], v[128:131], v[140:143]
	s_waitcnt lgkmcnt(2)
	v_mfma_f32_16x16x32_bf16 v[140:143], v[108:111], v[132:135], v[140:143]
	s_waitcnt lgkmcnt(1)
	v_mfma_f32_16x16x32_bf16 v[140:143], v[112:115], v[136:139], v[140:143]
	s_nop 9
	s_waitcnt vmcnt(7) lgkmcnt(0)
	v_add_f32_e32 v182, v6, v140
	v_add_f32_e32 v183, v7, v141
	v_add_f32_e32 v184, v8, v142
	v_add_f32_e32 v185, v9, v143
	v_lshlrev_b32_e32 v186, 16, v160
	v_and_b32_e32 v187, 0xffff0000, v160
	v_lshlrev_b32_e32 v188, 16, v161
	v_and_b32_e32 v189, 0xffff0000, v161
	v_fmac_f32_e32 v182, v164, v186
	v_fmac_f32_e32 v183, v165, v187
	v_fmac_f32_e32 v184, v166, v188
	v_fmac_f32_e32 v185, v167, v189
	v_mul_f32_e32 v186, 0x3d372713, v182
	v_mul_f32_e32 v187, 0x3d372713, v183
	v_mul_f32_e32 v188, 0x3d372713, v184
	v_mul_f32_e32 v189, 0x3d372713, v185
	v_mul_f32_e32 v186, v182, v186
	v_mul_f32_e32 v187, v183, v187
	v_mul_f32_e32 v188, v184, v188
	v_mul_f32_e32 v189, v185, v189
	v_fma_f32 v186, v182, v186, v182
	v_fma_f32 v187, v183, v187, v183
	v_fma_f32 v188, v184, v188, v184
	v_fma_f32 v189, v185, v189, v185
	v_mul_f32_e32 v186, 0xbfcc422a, v186
	v_mul_f32_e32 v187, 0xbfcc422a, v187
	v_mul_f32_e32 v188, 0xbfcc422a, v188
	v_mul_f32_e32 v189, 0xbfcc422a, v189
	v_mul_f32_e32 v186, 0x3fb8aa3b, v186
	v_mul_f32_e32 v187, 0x3fb8aa3b, v187
	v_mul_f32_e32 v188, 0x3fb8aa3b, v188
	v_mul_f32_e32 v189, 0x3fb8aa3b, v189
	v_exp_f32_e32 v186, v186
	v_exp_f32_e32 v187, v187
	v_exp_f32_e32 v188, v188
	v_exp_f32_e32 v189, v189
	v_add_f32_e32 v186, 1.0, v186
	v_add_f32_e32 v187, 1.0, v187
	v_add_f32_e32 v188, 1.0, v188
	v_add_f32_e32 v189, 1.0, v189
	v_rcp_f32_e32 v186, v186
	v_rcp_f32_e32 v187, v187
	v_rcp_f32_e32 v188, v188
	v_rcp_f32_e32 v189, v189
	v_mul_f32_e32 v182, v182, v186
	v_mul_f32_e32 v183, v183, v187
	v_mul_f32_e32 v184, v184, v188
	v_mul_f32_e32 v185, v185, v189
	v_cvt_pk_bf16_f32 v148, v182, v183
	v_cvt_pk_bf16_f32 v149, v184, v185
	global_store_dwordx2 v156, v[148:149], s[12:13]
	ds_read_b128 v[124:127], v152 offset:4352
	ds_read_b128 v[128:131], v152 offset:4416
	ds_read_b128 v[132:135], v152 offset:4480
	ds_read_b128 v[136:139], v152 offset:4544
	ds_read_b64 v[160:161], v163 offset:512
	s_waitcnt lgkmcnt(4)
	v_mfma_f32_16x16x32_bf16 v[140:143], v[100:103], v[124:127], 0
	s_waitcnt lgkmcnt(3)
	v_mfma_f32_16x16x32_bf16 v[140:143], v[104:107], v[128:131], v[140:143]
	s_waitcnt lgkmcnt(2)
	v_mfma_f32_16x16x32_bf16 v[140:143], v[108:111], v[132:135], v[140:143]
	s_waitcnt lgkmcnt(1)
	v_mfma_f32_16x16x32_bf16 v[140:143], v[112:115], v[136:139], v[140:143]
	s_nop 9
	s_waitcnt vmcnt(7) lgkmcnt(0)
	v_add_f32_e32 v182, v10, v140
	v_add_f32_e32 v183, v11, v141
	v_add_f32_e32 v184, v12, v142
	v_add_f32_e32 v185, v13, v143
	v_lshlrev_b32_e32 v186, 16, v160
	v_and_b32_e32 v187, 0xffff0000, v160
	v_lshlrev_b32_e32 v188, 16, v161
	v_and_b32_e32 v189, 0xffff0000, v161
	v_fmac_f32_e32 v182, v164, v186
	v_fmac_f32_e32 v183, v165, v187
	v_fmac_f32_e32 v184, v166, v188
	v_fmac_f32_e32 v185, v167, v189
	v_mul_f32_e32 v186, 0x3d372713, v182
	v_mul_f32_e32 v187, 0x3d372713, v183
	v_mul_f32_e32 v188, 0x3d372713, v184
	v_mul_f32_e32 v189, 0x3d372713, v185
	v_mul_f32_e32 v186, v182, v186
	v_mul_f32_e32 v187, v183, v187
	v_mul_f32_e32 v188, v184, v188
	v_mul_f32_e32 v189, v185, v189
	v_fma_f32 v186, v182, v186, v182
	v_fma_f32 v187, v183, v187, v183
	v_fma_f32 v188, v184, v188, v184
	v_fma_f32 v189, v185, v189, v185
	v_mul_f32_e32 v186, 0xbfcc422a, v186
	v_mul_f32_e32 v187, 0xbfcc422a, v187
	v_mul_f32_e32 v188, 0xbfcc422a, v188
	v_mul_f32_e32 v189, 0xbfcc422a, v189
	v_mul_f32_e32 v186, 0x3fb8aa3b, v186
	v_mul_f32_e32 v187, 0x3fb8aa3b, v187
	v_mul_f32_e32 v188, 0x3fb8aa3b, v188
	v_mul_f32_e32 v189, 0x3fb8aa3b, v189
	v_exp_f32_e32 v186, v186
	v_exp_f32_e32 v187, v187
	v_exp_f32_e32 v188, v188
	v_exp_f32_e32 v189, v189
	v_add_f32_e32 v186, 1.0, v186
	v_add_f32_e32 v187, 1.0, v187
	v_add_f32_e32 v188, 1.0, v188
	v_add_f32_e32 v189, 1.0, v189
	v_rcp_f32_e32 v186, v186
	v_rcp_f32_e32 v187, v187
	v_rcp_f32_e32 v188, v188
	v_rcp_f32_e32 v189, v189
	v_mul_f32_e32 v182, v182, v186
	v_mul_f32_e32 v183, v183, v187
	v_mul_f32_e32 v184, v184, v188
	v_mul_f32_e32 v185, v185, v189
	v_cvt_pk_bf16_f32 v148, v182, v183
	v_cvt_pk_bf16_f32 v149, v184, v185
	global_store_dwordx2 v159, v[148:149], s[12:13]
	s_sub_u32 s12, s12, 65536
	s_subb_u32 s13, s13, 0
	s_waitcnt vmcnt(7)
	v_mfma_f32_32x32x16_bf16 v[16:31], v[144:147], v[84:87], 0
	v_mfma_f32_32x32x16_bf16 v[32:47], v[144:147], v[88:91], 0
	v_mfma_f32_32x32x16_bf16 v[48:63], v[144:147], v[92:95], 0
	v_mfma_f32_32x32x16_bf16 v[64:79], v[144:147], v[96:99], 0
	ds_write_b128 v162, v[144:147]
	global_load_dwordx4 v[6:9], v153, s[42:43]
	global_load_dwordx4 v[10:13], v157, s[42:43]
	s_sub_u32 s42, s42, 131072
	s_subb_u32 s43, s43, 0
	s_nop 11
	global_load_dwordx4 v[144:147], v150, s[10:11]
	s_sub_u32 s34, s34, 196608
	s_subb_u32 s35, s35, 0
	s_sub_u32 s10, s10, 196608
	s_subb_u32 s11, s11, 0
	v_permlane32_swap_b32_e32 v16, v48
	v_permlane32_swap_b32_e32 v17, v49
	v_permlane32_swap_b32_e32 v18, v50
	v_permlane32_swap_b32_e32 v19, v51
	v_permlane32_swap_b32_e32 v20, v52
	v_permlane32_swap_b32_e32 v21, v53
	v_permlane32_swap_b32_e32 v22, v54
	v_permlane32_swap_b32_e32 v23, v55
	v_permlane32_swap_b32_e32 v24, v56
	v_permlane32_swap_b32_e32 v25, v57
	v_permlane32_swap_b32_e32 v26, v58
	v_permlane32_swap_b32_e32 v27, v59
	v_permlane32_swap_b32_e32 v28, v60
	v_permlane32_swap_b32_e32 v29, v61
	v_permlane32_swap_b32_e32 v30, v62
	v_permlane32_swap_b32_e32 v31, v63
	v_permlane32_swap_b32_e32 v32, v64
	v_permlane32_swap_b32_e32 v33, v65
	v_permlane32_swap_b32_e32 v34, v66
	v_permlane32_swap_b32_e32 v35, v67
	v_permlane32_swap_b32_e32 v36, v68
	v_permlane32_swap_b32_e32 v37, v69
	v_permlane32_swap_b32_e32 v38, v70
	v_permlane32_swap_b32_e32 v39, v71
	v_permlane32_swap_b32_e32 v40, v72
	v_permlane32_swap_b32_e32 v41, v73
	v_permlane32_swap_b32_e32 v42, v74
	v_permlane32_swap_b32_e32 v43, v75
	v_permlane32_swap_b32_e32 v44, v76
	v_permlane32_swap_b32_e32 v45, v77
	v_permlane32_swap_b32_e32 v46, v78
	v_permlane32_swap_b32_e32 v47, v79
	v_fmac_f32_e32 v63, v116, v120
	v_fmac_f32_e32 v79, v118, v121
	v_fmac_f32_dpp v63, v120, v122 quad_perm:[1,0,3,2] row_mask:0xf bank_mask:0xf
	v_fmac_f32_dpp v79, v121, v123 quad_perm:[1,0,3,2] row_mask:0xf bank_mask:0xf
	v_cvt_pk_bf16_f32 v148, v63, v79
	ds_write_b32 v151, v148 offset:8432
	v_fmac_f32_e32 v62, v116, v63
	v_fmac_f32_e32 v78, v118, v79
	v_fmac_f32_dpp v62, v63, v122 quad_perm:[1,0,3,2] row_mask:0xf bank_mask:0xf
	v_fmac_f32_dpp v78, v79, v123 quad_perm:[1,0,3,2] row_mask:0xf bank_mask:0xf
	v_cvt_pk_bf16_f32 v149, v62, v78
	ds_write_b32 v151, v149 offset:8160
	v_fmac_f32_e32 v61, v116, v62
	v_fmac_f32_e32 v77, v118, v78
	v_fmac_f32_dpp v61, v62, v122 quad_perm:[1,0,3,2] row_mask:0xf bank_mask:0xf
	v_fmac_f32_dpp v77, v78, v123 quad_perm:[1,0,3,2] row_mask:0xf bank_mask:0xf
	v_cvt_pk_bf16_f32 v148, v61, v77
	ds_write_b32 v151, v148 offset:7888
	v_fmac_f32_e32 v60, v116, v61
	v_fmac_f32_e32 v76, v118, v77
	v_fmac_f32_dpp v60, v61, v122 quad_perm:[1,0,3,2] row_mask:0xf bank_mask:0xf
	v_fmac_f32_dpp v76, v77, v123 quad_perm:[1,0,3,2] row_mask:0xf bank_mask:0xf
	v_cvt_pk_bf16_f32 v149, v60, v76
	ds_write_b32 v151, v149 offset:7616
	v_fmac_f32_e32 v31, v116, v60
	v_fmac_f32_e32 v47, v118, v76
	v_fmac_f32_dpp v31, v60, v122 quad_perm:[1,0,3,2] row_mask:0xf bank_mask:0xf
	v_fmac_f32_dpp v47, v76, v123 quad_perm:[1,0,3,2] row_mask:0xf bank_mask:0xf
	v_cvt_pk_bf16_f32 v148, v31, v47
	ds_write_b32 v151, v148 offset:7344
	v_fmac_f32_e32 v30, v116, v31
	v_fmac_f32_e32 v46, v118, v47
	v_fmac_f32_dpp v30, v31, v122 quad_perm:[1,0,3,2] row_mask:0xf bank_mask:0xf
	v_fmac_f32_dpp v46, v47, v123 quad_perm:[1,0,3,2] row_mask:0xf bank_mask:0xf
	v_cvt_pk_bf16_f32 v149, v30, v46
	ds_write_b32 v151, v149 offset:7072
	v_fmac_f32_e32 v29, v116, v30
	v_fmac_f32_e32 v45, v118, v46
	v_fmac_f32_dpp v29, v30, v122 quad_perm:[1,0,3,2] row_mask:0xf bank_mask:0xf
	v_fmac_f32_dpp v45, v46, v123 quad_perm:[1,0,3,2] row_mask:0xf bank_mask:0xf
	v_cvt_pk_bf16_f32 v148, v29, v45
	ds_write_b32 v151, v148 offset:6800
	v_fmac_f32_e32 v28, v116, v29
	v_fmac_f32_e32 v44, v118, v45
	v_fmac_f32_dpp v28, v29, v122 quad_perm:[1,0,3,2] row_mask:0xf bank_mask:0xf
	v_fmac_f32_dpp v44, v45, v123 quad_perm:[1,0,3,2] row_mask:0xf bank_mask:0xf
	v_cvt_pk_bf16_f32 v149, v28, v44
	ds_write_b32 v151, v149 offset:6528
	v_fmac_f32_e32 v59, v116, v28
	v_fmac_f32_e32 v75, v118, v44
	v_fmac_f32_dpp v59, v28, v122 quad_perm:[1,0,3,2] row_mask:0xf bank_mask:0xf
	v_fmac_f32_dpp v75, v44, v123 quad_perm:[1,0,3,2] row_mask:0xf bank_mask:0xf
	v_cvt_pk_bf16_f32 v148, v59, v75
	ds_write_b32 v151, v148 offset:6256
	v_fmac_f32_e32 v58, v116, v59
	v_fmac_f32_e32 v74, v118, v75
	v_fmac_f32_dpp v58, v59, v122 quad_perm:[1,0,3,2] row_mask:0xf bank_mask:0xf
	v_fmac_f32_dpp v74, v75, v123 quad_perm:[1,0,3,2] row_mask:0xf bank_mask:0xf
	v_cvt_pk_bf16_f32 v149, v58, v74
	ds_write_b32 v151, v149 offset:5984
	v_fmac_f32_e32 v57, v116, v58
	v_fmac_f32_e32 v73, v118, v74
	v_fmac_f32_dpp v57, v58, v122 quad_perm:[1,0,3,2] row_mask:0xf bank_mask:0xf
	v_fmac_f32_dpp v73, v74, v123 quad_perm:[1,0,3,2] row_mask:0xf bank_mask:0xf
	v_cvt_pk_bf16_f32 v148, v57, v73
	ds_write_b32 v151, v148 offset:5712
	v_fmac_f32_e32 v56, v116, v57
	v_fmac_f32_e32 v72, v118, v73
	v_fmac_f32_dpp v56, v57, v122 quad_perm:[1,0,3,2] row_mask:0xf bank_mask:0xf
	v_fmac_f32_dpp v72, v73, v123 quad_perm:[1,0,3,2] row_mask:0xf bank_mask:0xf
	v_cvt_pk_bf16_f32 v149, v56, v72
	ds_write_b32 v151, v149 offset:5440
	v_fmac_f32_e32 v27, v116, v56
	v_fmac_f32_e32 v43, v118, v72
	v_fmac_f32_dpp v27, v56, v122 quad_perm:[1,0,3,2] row_mask:0xf bank_mask:0xf
	v_fmac_f32_dpp v43, v72, v123 quad_perm:[1,0,3,2] row_mask:0xf bank_mask:0xf
	v_cvt_pk_bf16_f32 v148, v27, v43
	ds_write_b32 v151, v148 offset:5168
	v_fmac_f32_e32 v26, v116, v27
	v_fmac_f32_e32 v42, v118, v43
	v_fmac_f32_dpp v26, v27, v122 quad_perm:[1,0,3,2] row_mask:0xf bank_mask:0xf
	v_fmac_f32_dpp v42, v43, v123 quad_perm:[1,0,3,2] row_mask:0xf bank_mask:0xf
	v_cvt_pk_bf16_f32 v149, v26, v42
	ds_write_b32 v151, v149 offset:4896
	v_fmac_f32_e32 v25, v116, v26
	v_fmac_f32_e32 v41, v118, v42
	v_fmac_f32_dpp v25, v26, v122 quad_perm:[1,0,3,2] row_mask:0xf bank_mask:0xf
	v_fmac_f32_dpp v41, v42, v123 quad_perm:[1,0,3,2] row_mask:0xf bank_mask:0xf
	v_cvt_pk_bf16_f32 v148, v25, v41
	ds_write_b32 v151, v148 offset:4624
	v_fmac_f32_e32 v24, v116, v25
	v_fmac_f32_e32 v40, v118, v41
	v_fmac_f32_dpp v24, v25, v122 quad_perm:[1,0,3,2] row_mask:0xf bank_mask:0xf
	v_fmac_f32_dpp v40, v41, v123 quad_perm:[1,0,3,2] row_mask:0xf bank_mask:0xf
	v_cvt_pk_bf16_f32 v149, v24, v40
	ds_write_b32 v151, v149 offset:4352
	v_fmac_f32_e32 v55, v116, v24
	v_fmac_f32_e32 v71, v118, v40
	v_fmac_f32_dpp v55, v24, v122 quad_perm:[1,0,3,2] row_mask:0xf bank_mask:0xf
	v_fmac_f32_dpp v71, v40, v123 quad_perm:[1,0,3,2] row_mask:0xf bank_mask:0xf
	v_cvt_pk_bf16_f32 v148, v55, v71
	ds_write_b32 v151, v148 offset:4080
	v_fmac_f32_e32 v54, v116, v55
	v_fmac_f32_e32 v70, v118, v71
	v_fmac_f32_dpp v54, v55, v122 quad_perm:[1,0,3,2] row_mask:0xf bank_mask:0xf
	v_fmac_f32_dpp v70, v71, v123 quad_perm:[1,0,3,2] row_mask:0xf bank_mask:0xf
	v_cvt_pk_bf16_f32 v149, v54, v70
	ds_write_b32 v151, v149 offset:3808
	v_fmac_f32_e32 v53, v116, v54
	v_fmac_f32_e32 v69, v118, v70
	v_fmac_f32_dpp v53, v54, v122 quad_perm:[1,0,3,2] row_mask:0xf bank_mask:0xf
	v_fmac_f32_dpp v69, v70, v123 quad_perm:[1,0,3,2] row_mask:0xf bank_mask:0xf
	v_cvt_pk_bf16_f32 v148, v53, v69
	ds_write_b32 v151, v148 offset:3536
	v_fmac_f32_e32 v52, v116, v53
	v_fmac_f32_e32 v68, v118, v69
	v_fmac_f32_dpp v52, v53, v122 quad_perm:[1,0,3,2] row_mask:0xf bank_mask:0xf
	v_fmac_f32_dpp v68, v69, v123 quad_perm:[1,0,3,2] row_mask:0xf bank_mask:0xf
	v_cvt_pk_bf16_f32 v149, v52, v68
	ds_write_b32 v151, v149 offset:3264
	v_fmac_f32_e32 v23, v116, v52
	v_fmac_f32_e32 v39, v118, v68
	v_fmac_f32_dpp v23, v52, v122 quad_perm:[1,0,3,2] row_mask:0xf bank_mask:0xf
	v_fmac_f32_dpp v39, v68, v123 quad_perm:[1,0,3,2] row_mask:0xf bank_mask:0xf
	v_cvt_pk_bf16_f32 v148, v23, v39
	ds_write_b32 v151, v148 offset:2992
	v_fmac_f32_e32 v22, v116, v23
	v_fmac_f32_e32 v38, v118, v39
	v_fmac_f32_dpp v22, v23, v122 quad_perm:[1,0,3,2] row_mask:0xf bank_mask:0xf
	v_fmac_f32_dpp v38, v39, v123 quad_perm:[1,0,3,2] row_mask:0xf bank_mask:0xf
	v_cvt_pk_bf16_f32 v149, v22, v38
	ds_write_b32 v151, v149 offset:2720
	v_fmac_f32_e32 v21, v116, v22
	v_fmac_f32_e32 v37, v118, v38
	v_fmac_f32_dpp v21, v22, v122 quad_perm:[1,0,3,2] row_mask:0xf bank_mask:0xf
	v_fmac_f32_dpp v37, v38, v123 quad_perm:[1,0,3,2] row_mask:0xf bank_mask:0xf
	v_cvt_pk_bf16_f32 v148, v21, v37
	ds_write_b32 v151, v148 offset:2448
	v_fmac_f32_e32 v20, v116, v21
	v_fmac_f32_e32 v36, v118, v37
	v_fmac_f32_dpp v20, v21, v122 quad_perm:[1,0,3,2] row_mask:0xf bank_mask:0xf
	v_fmac_f32_dpp v36, v37, v123 quad_perm:[1,0,3,2] row_mask:0xf bank_mask:0xf
	v_cvt_pk_bf16_f32 v149, v20, v36
	ds_write_b32 v151, v149 offset:2176
	v_fmac_f32_e32 v51, v116, v20
	v_fmac_f32_e32 v67, v118, v36
	v_fmac_f32_dpp v51, v20, v122 quad_perm:[1,0,3,2] row_mask:0xf bank_mask:0xf
	v_fmac_f32_dpp v67, v36, v123 quad_perm:[1,0,3,2] row_mask:0xf bank_mask:0xf
	v_cvt_pk_bf16_f32 v148, v51, v67
	ds_write_b32 v151, v148 offset:1904
	v_fmac_f32_e32 v50, v116, v51
	v_fmac_f32_e32 v66, v118, v67
	v_fmac_f32_dpp v50, v51, v122 quad_perm:[1,0,3,2] row_mask:0xf bank_mask:0xf
	v_fmac_f32_dpp v66, v67, v123 quad_perm:[1,0,3,2] row_mask:0xf bank_mask:0xf
	v_cvt_pk_bf16_f32 v149, v50, v66
	ds_write_b32 v151, v149 offset:1632
	v_fmac_f32_e32 v49, v116, v50
	v_fmac_f32_e32 v65, v118, v66
	v_fmac_f32_dpp v49, v50, v122 quad_perm:[1,0,3,2] row_mask:0xf bank_mask:0xf
	v_fmac_f32_dpp v65, v66, v123 quad_perm:[1,0,3,2] row_mask:0xf bank_mask:0xf
	v_cvt_pk_bf16_f32 v148, v49, v65
	ds_write_b32 v151, v148 offset:1360
	v_fmac_f32_e32 v48, v116, v49
	v_fmac_f32_e32 v64, v118, v65
	v_fmac_f32_dpp v48, v49, v122 quad_perm:[1,0,3,2] row_mask:0xf bank_mask:0xf
	v_fmac_f32_dpp v64, v65, v123 quad_perm:[1,0,3,2] row_mask:0xf bank_mask:0xf
	v_cvt_pk_bf16_f32 v149, v48, v64
	ds_write_b32 v151, v149 offset:1088
	v_fmac_f32_e32 v19, v116, v48
	v_fmac_f32_e32 v35, v118, v64
	v_fmac_f32_dpp v19, v48, v122 quad_perm:[1,0,3,2] row_mask:0xf bank_mask:0xf
	v_fmac_f32_dpp v35, v64, v123 quad_perm:[1,0,3,2] row_mask:0xf bank_mask:0xf
	v_cvt_pk_bf16_f32 v148, v19, v35
	ds_write_b32 v151, v148 offset:816
	v_fmac_f32_e32 v18, v116, v19
	v_fmac_f32_e32 v34, v118, v35
	v_fmac_f32_dpp v18, v19, v122 quad_perm:[1,0,3,2] row_mask:0xf bank_mask:0xf
	v_fmac_f32_dpp v34, v35, v123 quad_perm:[1,0,3,2] row_mask:0xf bank_mask:0xf
	v_cvt_pk_bf16_f32 v149, v18, v34
	ds_write_b32 v151, v149 offset:544
	v_fmac_f32_e32 v17, v116, v18
	v_fmac_f32_e32 v33, v118, v34
	v_fmac_f32_dpp v17, v18, v122 quad_perm:[1,0,3,2] row_mask:0xf bank_mask:0xf
	v_fmac_f32_dpp v33, v34, v123 quad_perm:[1,0,3,2] row_mask:0xf bank_mask:0xf
	v_cvt_pk_bf16_f32 v148, v17, v33
	ds_write_b32 v151, v148 offset:272
	v_fmac_f32_e32 v16, v116, v17
	v_fmac_f32_e32 v32, v118, v33
	v_fmac_f32_dpp v16, v17, v122 quad_perm:[1,0,3,2] row_mask:0xf bank_mask:0xf
	v_fmac_f32_dpp v32, v33, v123 quad_perm:[1,0,3,2] row_mask:0xf bank_mask:0xf
	v_cvt_pk_bf16_f32 v149, v16, v32
	ds_write_b32 v151, v149
	v_mov_b32_e32 v120, v16
	v_mov_b32_e32 v121, v32
	ds_read_b128 v[124:127], v152
	ds_read_b128 v[128:131], v152 offset:64
	ds_read_b128 v[132:135], v152 offset:128
	ds_read_b128 v[136:139], v152 offset:192
	ds_read_b64 v[160:161], v163
	s_waitcnt lgkmcnt(4)
	v_mfma_f32_16x16x32_bf16 v[140:143], v[100:103], v[124:127], 0
	s_waitcnt lgkmcnt(3)
	v_mfma_f32_16x16x32_bf16 v[140:143], v[104:107], v[128:131], v[140:143]
	s_waitcnt lgkmcnt(2)
	v_mfma_f32_16x16x32_bf16 v[140:143], v[108:111], v[132:135], v[140:143]
	s_waitcnt lgkmcnt(1)
	v_mfma_f32_16x16x32_bf16 v[140:143], v[112:115], v[136:139], v[140:143]
	s_nop 9
	s_waitcnt vmcnt(7) lgkmcnt(0)
	v_add_f32_e32 v182, v172, v140
	v_add_f32_e32 v183, v173, v141
	v_add_f32_e32 v184, v174, v142
	v_add_f32_e32 v185, v175, v143
	v_lshlrev_b32_e32 v186, 16, v160
	v_and_b32_e32 v187, 0xffff0000, v160
	v_lshlrev_b32_e32 v188, 16, v161
	v_and_b32_e32 v189, 0xffff0000, v161
	v_fmac_f32_e32 v182, v164, v186
	v_fmac_f32_e32 v183, v165, v187
	v_fmac_f32_e32 v184, v166, v188
	v_fmac_f32_e32 v185, v167, v189
	v_mul_f32_e32 v186, 0x3d372713, v182
	v_mul_f32_e32 v187, 0x3d372713, v183
	v_mul_f32_e32 v188, 0x3d372713, v184
	v_mul_f32_e32 v189, 0x3d372713, v185
	v_mul_f32_e32 v186, v182, v186
	v_mul_f32_e32 v187, v183, v187
	v_mul_f32_e32 v188, v184, v188
	v_mul_f32_e32 v189, v185, v189
	v_fma_f32 v186, v182, v186, v182
	v_fma_f32 v187, v183, v187, v183
	v_fma_f32 v188, v184, v188, v184
	v_fma_f32 v189, v185, v189, v185
	v_mul_f32_e32 v186, 0xbfcc422a, v186
	v_mul_f32_e32 v187, 0xbfcc422a, v187
	v_mul_f32_e32 v188, 0xbfcc422a, v188
	v_mul_f32_e32 v189, 0xbfcc422a, v189
	v_mul_f32_e32 v186, 0x3fb8aa3b, v186
	v_mul_f32_e32 v187, 0x3fb8aa3b, v187
	v_mul_f32_e32 v188, 0x3fb8aa3b, v188
	v_mul_f32_e32 v189, 0x3fb8aa3b, v189
	v_exp_f32_e32 v186, v186
	v_exp_f32_e32 v187, v187
	v_exp_f32_e32 v188, v188
	v_exp_f32_e32 v189, v189
	v_add_f32_e32 v186, 1.0, v186
	v_add_f32_e32 v187, 1.0, v187
	v_add_f32_e32 v188, 1.0, v188
	v_add_f32_e32 v189, 1.0, v189
	v_rcp_f32_e32 v186, v186
	v_rcp_f32_e32 v187, v187
	v_rcp_f32_e32 v188, v188
	v_rcp_f32_e32 v189, v189
	v_mul_f32_e32 v182, v182, v186
	v_mul_f32_e32 v183, v183, v187
	v_mul_f32_e32 v184, v184, v188
	v_mul_f32_e32 v185, v185, v189
	v_cvt_pk_bf16_f32 v148, v182, v183
	v_cvt_pk_bf16_f32 v149, v184, v185
	global_store_dwordx2 v156, v[148:149], s[12:13]
	ds_read_b128 v[124:127], v152 offset:4352
	ds_read_b128 v[128:131], v152 offset:4416
	ds_read_b128 v[132:135], v152 offset:4480
	ds_read_b128 v[136:139], v152 offset:4544
	ds_read_b64 v[160:161], v163 offset:512
	s_waitcnt lgkmcnt(4)
	v_mfma_f32_16x16x32_bf16 v[140:143], v[100:103], v[124:127], 0
	s_waitcnt lgkmcnt(3)
	v_mfma_f32_16x16x32_bf16 v[140:143], v[104:107], v[128:131], v[140:143]
	s_waitcnt lgkmcnt(2)
	v_mfma_f32_16x16x32_bf16 v[140:143], v[108:111], v[132:135], v[140:143]
	s_waitcnt lgkmcnt(1)
	v_mfma_f32_16x16x32_bf16 v[140:143], v[112:115], v[136:139], v[140:143]
	s_nop 9
	s_waitcnt vmcnt(7) lgkmcnt(0)
	v_add_f32_e32 v182, v176, v140
	v_add_f32_e32 v183, v177, v141
	v_add_f32_e32 v184, v178, v142
	v_add_f32_e32 v185, v179, v143
	v_lshlrev_b32_e32 v186, 16, v160
	v_and_b32_e32 v187, 0xffff0000, v160
	v_lshlrev_b32_e32 v188, 16, v161
	v_and_b32_e32 v189, 0xffff0000, v161
	v_fmac_f32_e32 v182, v164, v186
	v_fmac_f32_e32 v183, v165, v187
	v_fmac_f32_e32 v184, v166, v188
	v_fmac_f32_e32 v185, v167, v189
	v_mul_f32_e32 v186, 0x3d372713, v182
	v_mul_f32_e32 v187, 0x3d372713, v183
	v_mul_f32_e32 v188, 0x3d372713, v184
	v_mul_f32_e32 v189, 0x3d372713, v185
	v_mul_f32_e32 v186, v182, v186
	v_mul_f32_e32 v187, v183, v187
	v_mul_f32_e32 v188, v184, v188
	v_mul_f32_e32 v189, v185, v189
	v_fma_f32 v186, v182, v186, v182
	v_fma_f32 v187, v183, v187, v183
	v_fma_f32 v188, v184, v188, v184
	v_fma_f32 v189, v185, v189, v185
	v_mul_f32_e32 v186, 0xbfcc422a, v186
	v_mul_f32_e32 v187, 0xbfcc422a, v187
	v_mul_f32_e32 v188, 0xbfcc422a, v188
	v_mul_f32_e32 v189, 0xbfcc422a, v189
	v_mul_f32_e32 v186, 0x3fb8aa3b, v186
	v_mul_f32_e32 v187, 0x3fb8aa3b, v187
	v_mul_f32_e32 v188, 0x3fb8aa3b, v188
	v_mul_f32_e32 v189, 0x3fb8aa3b, v189
	v_exp_f32_e32 v186, v186
	v_exp_f32_e32 v187, v187
	v_exp_f32_e32 v188, v188
	v_exp_f32_e32 v189, v189
	v_add_f32_e32 v186, 1.0, v186
	v_add_f32_e32 v187, 1.0, v187
	v_add_f32_e32 v188, 1.0, v188
	v_add_f32_e32 v189, 1.0, v189
	v_rcp_f32_e32 v186, v186
	v_rcp_f32_e32 v187, v187
	v_rcp_f32_e32 v188, v188
	v_rcp_f32_e32 v189, v189
	v_mul_f32_e32 v182, v182, v186
	v_mul_f32_e32 v183, v183, v187
	v_mul_f32_e32 v184, v184, v188
	v_mul_f32_e32 v185, v185, v189
	v_cvt_pk_bf16_f32 v148, v182, v183
	v_cvt_pk_bf16_f32 v149, v184, v185
	global_store_dwordx2 v159, v[148:149], s[12:13]
	s_sub_u32 s12, s12, 65536
	s_subb_u32 s13, s13, 0
	s_add_u32 s14, s14, 2
	s_cmp_lt_u32 s14, 32
	s_cbranch_scc1 .Lssm_tileB_d1m0
	s_waitcnt vmcnt(0) lgkmcnt(0)

.Lssm_tile_d0m1:
	s_waitcnt vmcnt(1)
	v_mfma_f32_32x32x16_bf16 v[16:31], v[80:83], v[84:87], 0
	v_mfma_f32_32x32x16_bf16 v[32:47], v[80:83], v[88:91], 0
	v_mfma_f32_32x32x16_bf16 v[48:63], v[80:83], v[92:95], 0
	v_mfma_f32_32x32x16_bf16 v[64:79], v[80:83], v[96:99], 0
	v_add_u32_e32 v171, s36, v155
	s_nop 11
	global_load_dwordx4 v[80:83], v150, s[10:11]
	s_add_u32 s34, s34, 196608
	s_addc_u32 s35, s35, 0
	s_add_u32 s10, s10, 196608
	s_addc_u32 s11, s11, 0
	v_permlane32_swap_b32_e32 v16, v48
	v_permlane32_swap_b32_e32 v17, v49
	v_permlane32_swap_b32_e32 v18, v50
	v_permlane32_swap_b32_e32 v19, v51
	v_permlane32_swap_b32_e32 v20, v52
	v_permlane32_swap_b32_e32 v21, v53
	v_permlane32_swap_b32_e32 v22, v54
	v_permlane32_swap_b32_e32 v23, v55
	v_permlane32_swap_b32_e32 v24, v56
	v_permlane32_swap_b32_e32 v25, v57
	v_permlane32_swap_b32_e32 v26, v58
	v_permlane32_swap_b32_e32 v27, v59
	v_permlane32_swap_b32_e32 v28, v60
	v_permlane32_swap_b32_e32 v29, v61
	v_permlane32_swap_b32_e32 v30, v62
	v_permlane32_swap_b32_e32 v31, v63
	v_permlane32_swap_b32_e32 v32, v64
	v_permlane32_swap_b32_e32 v33, v65
	v_permlane32_swap_b32_e32 v34, v66
	v_permlane32_swap_b32_e32 v35, v67
	v_permlane32_swap_b32_e32 v36, v68
	v_permlane32_swap_b32_e32 v37, v69
	v_permlane32_swap_b32_e32 v38, v70
	v_permlane32_swap_b32_e32 v39, v71
	v_permlane32_swap_b32_e32 v40, v72
	v_permlane32_swap_b32_e32 v41, v73
	v_permlane32_swap_b32_e32 v42, v74
	v_permlane32_swap_b32_e32 v43, v75
	v_permlane32_swap_b32_e32 v44, v76
	v_permlane32_swap_b32_e32 v45, v77
	v_permlane32_swap_b32_e32 v46, v78
	v_permlane32_swap_b32_e32 v47, v79
	v_fmac_f32_e32 v16, v116, v120
	v_fmac_f32_e32 v32, v118, v121
	v_fmac_f32_dpp v16, v120, v122 quad_perm:[1,0,3,2] row_mask:0xf bank_mask:0xf
	v_fmac_f32_dpp v32, v121, v123 quad_perm:[1,0,3,2] row_mask:0xf bank_mask:0xf
	v_cvt_pk_bf16_f32 v148, v16, v32
	ds_write_b32 v151, v148
	v_fmac_f32_e32 v17, v116, v16
	v_fmac_f32_e32 v33, v118, v32
	v_fmac_f32_dpp v17, v16, v122 quad_perm:[1,0,3,2] row_mask:0xf bank_mask:0xf
	v_fmac_f32_dpp v33, v32, v123 quad_perm:[1,0,3,2] row_mask:0xf bank_mask:0xf
	v_cvt_pk_bf16_f32 v149, v17, v33
	ds_write_b32 v151, v149 offset:272
	v_fmac_f32_e32 v18, v116, v17
	v_fmac_f32_e32 v34, v118, v33
	v_fmac_f32_dpp v18, v17, v122 quad_perm:[1,0,3,2] row_mask:0xf bank_mask:0xf
	v_fmac_f32_dpp v34, v33, v123 quad_perm:[1,0,3,2] row_mask:0xf bank_mask:0xf
	v_cvt_pk_bf16_f32 v148, v18, v34
	ds_write_b32 v151, v148 offset:544
	v_fmac_f32_e32 v19, v116, v18
	v_fmac_f32_e32 v35, v118, v34
	v_fmac_f32_dpp v19, v18, v122 quad_perm:[1,0,3,2] row_mask:0xf bank_mask:0xf
	v_fmac_f32_dpp v35, v34, v123 quad_perm:[1,0,3,2] row_mask:0xf bank_mask:0xf
	v_cvt_pk_bf16_f32 v149, v19, v35
	ds_write_b32 v151, v149 offset:816
	v_fmac_f32_e32 v48, v116, v19
	v_fmac_f32_e32 v64, v118, v35
	v_fmac_f32_dpp v48, v19, v122 quad_perm:[1,0,3,2] row_mask:0xf bank_mask:0xf
	v_fmac_f32_dpp v64, v35, v123 quad_perm:[1,0,3,2] row_mask:0xf bank_mask:0xf
	v_cvt_pk_bf16_f32 v148, v48, v64
	ds_write_b32 v151, v148 offset:1088
	v_fmac_f32_e32 v49, v116, v48
	v_fmac_f32_e32 v65, v118, v64
	v_fmac_f32_dpp v49, v48, v122 quad_perm:[1,0,3,2] row_mask:0xf bank_mask:0xf
	v_fmac_f32_dpp v65, v64, v123 quad_perm:[1,0,3,2] row_mask:0xf bank_mask:0xf
	v_cvt_pk_bf16_f32 v149, v49, v65
	ds_write_b32 v151, v149 offset:1360
	v_fmac_f32_e32 v50, v116, v49
	v_fmac_f32_e32 v66, v118, v65
	v_fmac_f32_dpp v50, v49, v122 quad_perm:[1,0,3,2] row_mask:0xf bank_mask:0xf
	v_fmac_f32_dpp v66, v65, v123 quad_perm:[1,0,3,2] row_mask:0xf bank_mask:0xf
	v_cvt_pk_bf16_f32 v148, v50, v66
	ds_write_b32 v151, v148 offset:1632
	v_fmac_f32_e32 v51, v116, v50
	v_fmac_f32_e32 v67, v118, v66
	v_fmac_f32_dpp v51, v50, v122 quad_perm:[1,0,3,2] row_mask:0xf bank_mask:0xf
	v_fmac_f32_dpp v67, v66, v123 quad_perm:[1,0,3,2] row_mask:0xf bank_mask:0xf
	v_cvt_pk_bf16_f32 v149, v51, v67
	ds_write_b32 v151, v149 offset:1904
	v_fmac_f32_e32 v20, v116, v51
	v_fmac_f32_e32 v36, v118, v67
	v_fmac_f32_dpp v20, v51, v122 quad_perm:[1,0,3,2] row_mask:0xf bank_mask:0xf
	v_fmac_f32_dpp v36, v67, v123 quad_perm:[1,0,3,2] row_mask:0xf bank_mask:0xf
	v_cvt_pk_bf16_f32 v148, v20, v36
	ds_write_b32 v151, v148 offset:2176
	v_fmac_f32_e32 v21, v116, v20
	v_fmac_f32_e32 v37, v118, v36
	v_fmac_f32_dpp v21, v20, v122 quad_perm:[1,0,3,2] row_mask:0xf bank_mask:0xf
	v_fmac_f32_dpp v37, v36, v123 quad_perm:[1,0,3,2] row_mask:0xf bank_mask:0xf
	v_cvt_pk_bf16_f32 v149, v21, v37
	ds_write_b32 v151, v149 offset:2448
	v_fmac_f32_e32 v22, v116, v21
	v_fmac_f32_e32 v38, v118, v37
	v_fmac_f32_dpp v22, v21, v122 quad_perm:[1,0,3,2] row_mask:0xf bank_mask:0xf
	v_fmac_f32_dpp v38, v37, v123 quad_perm:[1,0,3,2] row_mask:0xf bank_mask:0xf
	v_cvt_pk_bf16_f32 v148, v22, v38
	ds_write_b32 v151, v148 offset:2720
	v_fmac_f32_e32 v23, v116, v22
	v_fmac_f32_e32 v39, v118, v38
	v_fmac_f32_dpp v23, v22, v122 quad_perm:[1,0,3,2] row_mask:0xf bank_mask:0xf
	v_fmac_f32_dpp v39, v38, v123 quad_perm:[1,0,3,2] row_mask:0xf bank_mask:0xf
	v_cvt_pk_bf16_f32 v149, v23, v39
	ds_write_b32 v151, v149 offset:2992
	v_fmac_f32_e32 v52, v116, v23
	v_fmac_f32_e32 v68, v118, v39
	v_fmac_f32_dpp v52, v23, v122 quad_perm:[1,0,3,2] row_mask:0xf bank_mask:0xf
	v_fmac_f32_dpp v68, v39, v123 quad_perm:[1,0,3,2] row_mask:0xf bank_mask:0xf
	v_cvt_pk_bf16_f32 v148, v52, v68
	ds_write_b32 v151, v148 offset:3264
	v_fmac_f32_e32 v53, v116, v52
	v_fmac_f32_e32 v69, v118, v68
	v_fmac_f32_dpp v53, v52, v122 quad_perm:[1,0,3,2] row_mask:0xf bank_mask:0xf
	v_fmac_f32_dpp v69, v68, v123 quad_perm:[1,0,3,2] row_mask:0xf bank_mask:0xf
	v_cvt_pk_bf16_f32 v149, v53, v69
	ds_write_b32 v151, v149 offset:3536
	v_fmac_f32_e32 v54, v116, v53
	v_fmac_f32_e32 v70, v118, v69
	v_fmac_f32_dpp v54, v53, v122 quad_perm:[1,0,3,2] row_mask:0xf bank_mask:0xf
	v_fmac_f32_dpp v70, v69, v123 quad_perm:[1,0,3,2] row_mask:0xf bank_mask:0xf
	v_cvt_pk_bf16_f32 v148, v54, v70
	ds_write_b32 v151, v148 offset:3808
	v_fmac_f32_e32 v55, v116, v54
	v_fmac_f32_e32 v71, v118, v70
	v_fmac_f32_dpp v55, v54, v122 quad_perm:[1,0,3,2] row_mask:0xf bank_mask:0xf
	v_fmac_f32_dpp v71, v70, v123 quad_perm:[1,0,3,2] row_mask:0xf bank_mask:0xf
	v_cvt_pk_bf16_f32 v149, v55, v71
	ds_write_b32 v151, v149 offset:4080
	v_fmac_f32_e32 v24, v116, v55
	v_fmac_f32_e32 v40, v118, v71
	v_fmac_f32_dpp v24, v55, v122 quad_perm:[1,0,3,2] row_mask:0xf bank_mask:0xf
	v_fmac_f32_dpp v40, v71, v123 quad_perm:[1,0,3,2] row_mask:0xf bank_mask:0xf
	v_cvt_pk_bf16_f32 v148, v24, v40
	ds_write_b32 v151, v148 offset:4352
	v_fmac_f32_e32 v25, v116, v24
	v_fmac_f32_e32 v41, v118, v40
	v_fmac_f32_dpp v25, v24, v122 quad_perm:[1,0,3,2] row_mask:0xf bank_mask:0xf
	v_fmac_f32_dpp v41, v40, v123 quad_perm:[1,0,3,2] row_mask:0xf bank_mask:0xf
	v_cvt_pk_bf16_f32 v149, v25, v41
	ds_write_b32 v151, v149 offset:4624
	v_fmac_f32_e32 v26, v116, v25
	v_fmac_f32_e32 v42, v118, v41
	v_fmac_f32_dpp v26, v25, v122 quad_perm:[1,0,3,2] row_mask:0xf bank_mask:0xf
	v_fmac_f32_dpp v42, v41, v123 quad_perm:[1,0,3,2] row_mask:0xf bank_mask:0xf
	v_cvt_pk_bf16_f32 v148, v26, v42
	ds_write_b32 v151, v148 offset:4896
	v_fmac_f32_e32 v27, v116, v26
	v_fmac_f32_e32 v43, v118, v42
	v_fmac_f32_dpp v27, v26, v122 quad_perm:[1,0,3,2] row_mask:0xf bank_mask:0xf
	v_fmac_f32_dpp v43, v42, v123 quad_perm:[1,0,3,2] row_mask:0xf bank_mask:0xf
	v_cvt_pk_bf16_f32 v149, v27, v43
	ds_write_b32 v151, v149 offset:5168
	v_fmac_f32_e32 v56, v116, v27
	v_fmac_f32_e32 v72, v118, v43
	v_fmac_f32_dpp v56, v27, v122 quad_perm:[1,0,3,2] row_mask:0xf bank_mask:0xf
	v_fmac_f32_dpp v72, v43, v123 quad_perm:[1,0,3,2] row_mask:0xf bank_mask:0xf
	v_cvt_pk_bf16_f32 v148, v56, v72
	ds_write_b32 v151, v148 offset:5440
	v_fmac_f32_e32 v57, v116, v56
	v_fmac_f32_e32 v73, v118, v72
	v_fmac_f32_dpp v57, v56, v122 quad_perm:[1,0,3,2] row_mask:0xf bank_mask:0xf
	v_fmac_f32_dpp v73, v72, v123 quad_perm:[1,0,3,2] row_mask:0xf bank_mask:0xf
	v_cvt_pk_bf16_f32 v149, v57, v73
	ds_write_b32 v151, v149 offset:5712
	v_fmac_f32_e32 v58, v116, v57
	v_fmac_f32_e32 v74, v118, v73
	v_fmac_f32_dpp v58, v57, v122 quad_perm:[1,0,3,2] row_mask:0xf bank_mask:0xf
	v_fmac_f32_dpp v74, v73, v123 quad_perm:[1,0,3,2] row_mask:0xf bank_mask:0xf
	v_cvt_pk_bf16_f32 v148, v58, v74
	ds_write_b32 v151, v148 offset:5984
	v_fmac_f32_e32 v59, v116, v58
	v_fmac_f32_e32 v75, v118, v74
	v_fmac_f32_dpp v59, v58, v122 quad_perm:[1,0,3,2] row_mask:0xf bank_mask:0xf
	v_fmac_f32_dpp v75, v74, v123 quad_perm:[1,0,3,2] row_mask:0xf bank_mask:0xf
	v_cvt_pk_bf16_f32 v149, v59, v75
	ds_write_b32 v151, v149 offset:6256
	v_fmac_f32_e32 v28, v116, v59
	v_fmac_f32_e32 v44, v118, v75
	v_fmac_f32_dpp v28, v59, v122 quad_perm:[1,0,3,2] row_mask:0xf bank_mask:0xf
	v_fmac_f32_dpp v44, v75, v123 quad_perm:[1,0,3,2] row_mask:0xf bank_mask:0xf
	v_cvt_pk_bf16_f32 v148, v28, v44
	ds_write_b32 v151, v148 offset:6528
	v_fmac_f32_e32 v29, v116, v28
	v_fmac_f32_e32 v45, v118, v44
	v_fmac_f32_dpp v29, v28, v122 quad_perm:[1,0,3,2] row_mask:0xf bank_mask:0xf
	v_fmac_f32_dpp v45, v44, v123 quad_perm:[1,0,3,2] row_mask:0xf bank_mask:0xf
	v_cvt_pk_bf16_f32 v149, v29, v45
	ds_write_b32 v151, v149 offset:6800
	v_fmac_f32_e32 v30, v116, v29
	v_fmac_f32_e32 v46, v118, v45
	v_fmac_f32_dpp v30, v29, v122 quad_perm:[1,0,3,2] row_mask:0xf bank_mask:0xf
	v_fmac_f32_dpp v46, v45, v123 quad_perm:[1,0,3,2] row_mask:0xf bank_mask:0xf
	v_cvt_pk_bf16_f32 v148, v30, v46
	ds_write_b32 v151, v148 offset:7072
	v_fmac_f32_e32 v31, v116, v30
	v_fmac_f32_e32 v47, v118, v46
	v_fmac_f32_dpp v31, v30, v122 quad_perm:[1,0,3,2] row_mask:0xf bank_mask:0xf
	v_fmac_f32_dpp v47, v46, v123 quad_perm:[1,0,3,2] row_mask:0xf bank_mask:0xf
	v_cvt_pk_bf16_f32 v149, v31, v47
	ds_write_b32 v151, v149 offset:7344
	v_fmac_f32_e32 v60, v116, v31
	v_fmac_f32_e32 v76, v118, v47
	v_fmac_f32_dpp v60, v31, v122 quad_perm:[1,0,3,2] row_mask:0xf bank_mask:0xf
	v_fmac_f32_dpp v76, v47, v123 quad_perm:[1,0,3,2] row_mask:0xf bank_mask:0xf
	v_cvt_pk_bf16_f32 v148, v60, v76
	ds_write_b32 v151, v148 offset:7616
	v_fmac_f32_e32 v61, v116, v60
	v_fmac_f32_e32 v77, v118, v76
	v_fmac_f32_dpp v61, v60, v122 quad_perm:[1,0,3,2] row_mask:0xf bank_mask:0xf
	v_fmac_f32_dpp v77, v76, v123 quad_perm:[1,0,3,2] row_mask:0xf bank_mask:0xf
	v_cvt_pk_bf16_f32 v149, v61, v77
	ds_write_b32 v151, v149 offset:7888
	v_fmac_f32_e32 v62, v116, v61
	v_fmac_f32_e32 v78, v118, v77
	v_fmac_f32_dpp v62, v61, v122 quad_perm:[1,0,3,2] row_mask:0xf bank_mask:0xf
	v_fmac_f32_dpp v78, v77, v123 quad_perm:[1,0,3,2] row_mask:0xf bank_mask:0xf
	v_cvt_pk_bf16_f32 v148, v62, v78
	ds_write_b32 v151, v148 offset:8160
	v_fmac_f32_e32 v63, v116, v62
	v_fmac_f32_e32 v79, v118, v78
	v_fmac_f32_dpp v63, v62, v122 quad_perm:[1,0,3,2] row_mask:0xf bank_mask:0xf
	v_fmac_f32_dpp v79, v78, v123 quad_perm:[1,0,3,2] row_mask:0xf bank_mask:0xf
	v_cvt_pk_bf16_f32 v149, v63, v79
	ds_write_b32 v151, v149 offset:8432
	v_mov_b32_e32 v120, v63
	v_mov_b32_e32 v121, v79
	ds_read_b128 v[124:127], v152
	ds_read_b128 v[128:131], v152 offset:64
	ds_read_b128 v[132:135], v152 offset:128
	ds_read_b128 v[136:139], v152 offset:192
	s_waitcnt lgkmcnt(3)
	v_mfma_f32_16x16x32_bf16 v[140:143], v[100:103], v[124:127], 0
	s_waitcnt lgkmcnt(2)
	v_mfma_f32_16x16x32_bf16 v[140:143], v[104:107], v[128:131], v[140:143]
	s_waitcnt lgkmcnt(1)
	v_mfma_f32_16x16x32_bf16 v[140:143], v[108:111], v[132:135], v[140:143]
	s_waitcnt lgkmcnt(0)
	v_mfma_f32_16x16x32_bf16 v[140:143], v[112:115], v[136:139], v[140:143]
	s_nop 9
	v_cvt_pk_bf16_f32 v182, v140, v141
	v_cvt_pk_bf16_f32 v183, v142, v143
	ds_write_b64 v171, v[182:183]
	ds_read_b128 v[124:127], v152 offset:4352
	ds_read_b128 v[128:131], v152 offset:4416
	ds_read_b128 v[132:135], v152 offset:4480
	ds_read_b128 v[136:139], v152 offset:4544
	s_waitcnt lgkmcnt(3)
	v_mfma_f32_16x16x32_bf16 v[140:143], v[100:103], v[124:127], 0
	s_waitcnt lgkmcnt(2)
	v_mfma_f32_16x16x32_bf16 v[140:143], v[104:107], v[128:131], v[140:143]
	s_waitcnt lgkmcnt(1)
	v_mfma_f32_16x16x32_bf16 v[140:143], v[108:111], v[132:135], v[140:143]
	s_waitcnt lgkmcnt(0)
	v_mfma_f32_16x16x32_bf16 v[140:143], v[112:115], v[136:139], v[140:143]
	s_nop 9
	v_cvt_pk_bf16_f32 v182, v140, v141
	v_cvt_pk_bf16_f32 v183, v142, v143
	ds_write_b64 v171, v[182:183] offset:512
	s_add_u32 s36, s36, 1024
	s_waitcnt vmcnt(1)
	v_mfma_f32_32x32x16_bf16 v[16:31], v[144:147], v[84:87], 0
	v_mfma_f32_32x32x16_bf16 v[32:47], v[144:147], v[88:91], 0
	v_mfma_f32_32x32x16_bf16 v[48:63], v[144:147], v[92:95], 0
	v_mfma_f32_32x32x16_bf16 v[64:79], v[144:147], v[96:99], 0
	v_add_u32_e32 v171, s36, v155
	s_nop 11
	global_load_dwordx4 v[144:147], v150, s[10:11]
	s_add_u32 s34, s34, 196608
	s_addc_u32 s35, s35, 0
	s_add_u32 s10, s10, 196608
	s_addc_u32 s11, s11, 0
	v_permlane32_swap_b32_e32 v16, v48
	v_permlane32_swap_b32_e32 v17, v49
	v_permlane32_swap_b32_e32 v18, v50
	v_permlane32_swap_b32_e32 v19, v51
	v_permlane32_swap_b32_e32 v20, v52
	v_permlane32_swap_b32_e32 v21, v53
	v_permlane32_swap_b32_e32 v22, v54
	v_permlane32_swap_b32_e32 v23, v55
	v_permlane32_swap_b32_e32 v24, v56
	v_permlane32_swap_b32_e32 v25, v57
	v_permlane32_swap_b32_e32 v26, v58
	v_permlane32_swap_b32_e32 v27, v59
	v_permlane32_swap_b32_e32 v28, v60
	v_permlane32_swap_b32_e32 v29, v61
	v_permlane32_swap_b32_e32 v30, v62
	v_permlane32_swap_b32_e32 v31, v63
	v_permlane32_swap_b32_e32 v32, v64
	v_permlane32_swap_b32_e32 v33, v65
	v_permlane32_swap_b32_e32 v34, v66
	v_permlane32_swap_b32_e32 v35, v67
	v_permlane32_swap_b32_e32 v36, v68
	v_permlane32_swap_b32_e32 v37, v69
	v_permlane32_swap_b32_e32 v38, v70
	v_permlane32_swap_b32_e32 v39, v71
	v_permlane32_swap_b32_e32 v40, v72
	v_permlane32_swap_b32_e32 v41, v73
	v_permlane32_swap_b32_e32 v42, v74
	v_permlane32_swap_b32_e32 v43, v75
	v_permlane32_swap_b32_e32 v44, v76
	v_permlane32_swap_b32_e32 v45, v77
	v_permlane32_swap_b32_e32 v46, v78
	v_permlane32_swap_b32_e32 v47, v79
	v_fmac_f32_e32 v16, v116, v120
	v_fmac_f32_e32 v32, v118, v121
	v_fmac_f32_dpp v16, v120, v122 quad_perm:[1,0,3,2] row_mask:0xf bank_mask:0xf
	v_fmac_f32_dpp v32, v121, v123 quad_perm:[1,0,3,2] row_mask:0xf bank_mask:0xf
	v_cvt_pk_bf16_f32 v148, v16, v32
	ds_write_b32 v151, v148
	v_fmac_f32_e32 v17, v116, v16
	v_fmac_f32_e32 v33, v118, v32
	v_fmac_f32_dpp v17, v16, v122 quad_perm:[1,0,3,2] row_mask:0xf bank_mask:0xf
	v_fmac_f32_dpp v33, v32, v123 quad_perm:[1,0,3,2] row_mask:0xf bank_mask:0xf
	v_cvt_pk_bf16_f32 v149, v17, v33
	ds_write_b32 v151, v149 offset:272
	v_fmac_f32_e32 v18, v116, v17
	v_fmac_f32_e32 v34, v118, v33
	v_fmac_f32_dpp v18, v17, v122 quad_perm:[1,0,3,2] row_mask:0xf bank_mask:0xf
	v_fmac_f32_dpp v34, v33, v123 quad_perm:[1,0,3,2] row_mask:0xf bank_mask:0xf
	v_cvt_pk_bf16_f32 v148, v18, v34
	ds_write_b32 v151, v148 offset:544
	v_fmac_f32_e32 v19, v116, v18
	v_fmac_f32_e32 v35, v118, v34
	v_fmac_f32_dpp v19, v18, v122 quad_perm:[1,0,3,2] row_mask:0xf bank_mask:0xf
	v_fmac_f32_dpp v35, v34, v123 quad_perm:[1,0,3,2] row_mask:0xf bank_mask:0xf
	v_cvt_pk_bf16_f32 v149, v19, v35
	ds_write_b32 v151, v149 offset:816
	v_fmac_f32_e32 v48, v116, v19
	v_fmac_f32_e32 v64, v118, v35
	v_fmac_f32_dpp v48, v19, v122 quad_perm:[1,0,3,2] row_mask:0xf bank_mask:0xf
	v_fmac_f32_dpp v64, v35, v123 quad_perm:[1,0,3,2] row_mask:0xf bank_mask:0xf
	v_cvt_pk_bf16_f32 v148, v48, v64
	ds_write_b32 v151, v148 offset:1088
	v_fmac_f32_e32 v49, v116, v48
	v_fmac_f32_e32 v65, v118, v64
	v_fmac_f32_dpp v49, v48, v122 quad_perm:[1,0,3,2] row_mask:0xf bank_mask:0xf
	v_fmac_f32_dpp v65, v64, v123 quad_perm:[1,0,3,2] row_mask:0xf bank_mask:0xf
	v_cvt_pk_bf16_f32 v149, v49, v65
	ds_write_b32 v151, v149 offset:1360
	v_fmac_f32_e32 v50, v116, v49
	v_fmac_f32_e32 v66, v118, v65
	v_fmac_f32_dpp v50, v49, v122 quad_perm:[1,0,3,2] row_mask:0xf bank_mask:0xf
	v_fmac_f32_dpp v66, v65, v123 quad_perm:[1,0,3,2] row_mask:0xf bank_mask:0xf
	v_cvt_pk_bf16_f32 v148, v50, v66
	ds_write_b32 v151, v148 offset:1632
	v_fmac_f32_e32 v51, v116, v50
	v_fmac_f32_e32 v67, v118, v66
	v_fmac_f32_dpp v51, v50, v122 quad_perm:[1,0,3,2] row_mask:0xf bank_mask:0xf
	v_fmac_f32_dpp v67, v66, v123 quad_perm:[1,0,3,2] row_mask:0xf bank_mask:0xf
	v_cvt_pk_bf16_f32 v149, v51, v67
	ds_write_b32 v151, v149 offset:1904
	v_fmac_f32_e32 v20, v116, v51
	v_fmac_f32_e32 v36, v118, v67
	v_fmac_f32_dpp v20, v51, v122 quad_perm:[1,0,3,2] row_mask:0xf bank_mask:0xf
	v_fmac_f32_dpp v36, v67, v123 quad_perm:[1,0,3,2] row_mask:0xf bank_mask:0xf
	v_cvt_pk_bf16_f32 v148, v20, v36
	ds_write_b32 v151, v148 offset:2176
	v_fmac_f32_e32 v21, v116, v20
	v_fmac_f32_e32 v37, v118, v36
	v_fmac_f32_dpp v21, v20, v122 quad_perm:[1,0,3,2] row_mask:0xf bank_mask:0xf
	v_fmac_f32_dpp v37, v36, v123 quad_perm:[1,0,3,2] row_mask:0xf bank_mask:0xf
	v_cvt_pk_bf16_f32 v149, v21, v37
	ds_write_b32 v151, v149 offset:2448
	v_fmac_f32_e32 v22, v116, v21
	v_fmac_f32_e32 v38, v118, v37
	v_fmac_f32_dpp v22, v21, v122 quad_perm:[1,0,3,2] row_mask:0xf bank_mask:0xf
	v_fmac_f32_dpp v38, v37, v123 quad_perm:[1,0,3,2] row_mask:0xf bank_mask:0xf
	v_cvt_pk_bf16_f32 v148, v22, v38
	ds_write_b32 v151, v148 offset:2720
	v_fmac_f32_e32 v23, v116, v22
	v_fmac_f32_e32 v39, v118, v38
	v_fmac_f32_dpp v23, v22, v122 quad_perm:[1,0,3,2] row_mask:0xf bank_mask:0xf
	v_fmac_f32_dpp v39, v38, v123 quad_perm:[1,0,3,2] row_mask:0xf bank_mask:0xf
	v_cvt_pk_bf16_f32 v149, v23, v39
	ds_write_b32 v151, v149 offset:2992
	v_fmac_f32_e32 v52, v116, v23
	v_fmac_f32_e32 v68, v118, v39
	v_fmac_f32_dpp v52, v23, v122 quad_perm:[1,0,3,2] row_mask:0xf bank_mask:0xf
	v_fmac_f32_dpp v68, v39, v123 quad_perm:[1,0,3,2] row_mask:0xf bank_mask:0xf
	v_cvt_pk_bf16_f32 v148, v52, v68
	ds_write_b32 v151, v148 offset:3264
	v_fmac_f32_e32 v53, v116, v52
	v_fmac_f32_e32 v69, v118, v68
	v_fmac_f32_dpp v53, v52, v122 quad_perm:[1,0,3,2] row_mask:0xf bank_mask:0xf
	v_fmac_f32_dpp v69, v68, v123 quad_perm:[1,0,3,2] row_mask:0xf bank_mask:0xf
	v_cvt_pk_bf16_f32 v149, v53, v69
	ds_write_b32 v151, v149 offset:3536
	v_fmac_f32_e32 v54, v116, v53
	v_fmac_f32_e32 v70, v118, v69
	v_fmac_f32_dpp v54, v53, v122 quad_perm:[1,0,3,2] row_mask:0xf bank_mask:0xf
	v_fmac_f32_dpp v70, v69, v123 quad_perm:[1,0,3,2] row_mask:0xf bank_mask:0xf
	v_cvt_pk_bf16_f32 v148, v54, v70
	ds_write_b32 v151, v148 offset:3808
	v_fmac_f32_e32 v55, v116, v54
	v_fmac_f32_e32 v71, v118, v70
	v_fmac_f32_dpp v55, v54, v122 quad_perm:[1,0,3,2] row_mask:0xf bank_mask:0xf
	v_fmac_f32_dpp v71, v70, v123 quad_perm:[1,0,3,2] row_mask:0xf bank_mask:0xf
	v_cvt_pk_bf16_f32 v149, v55, v71
	ds_write_b32 v151, v149 offset:4080
	v_fmac_f32_e32 v24, v116, v55
	v_fmac_f32_e32 v40, v118, v71
	v_fmac_f32_dpp v24, v55, v122 quad_perm:[1,0,3,2] row_mask:0xf bank_mask:0xf
	v_fmac_f32_dpp v40, v71, v123 quad_perm:[1,0,3,2] row_mask:0xf bank_mask:0xf
	v_cvt_pk_bf16_f32 v148, v24, v40
	ds_write_b32 v151, v148 offset:4352
	v_fmac_f32_e32 v25, v116, v24
	v_fmac_f32_e32 v41, v118, v40
	v_fmac_f32_dpp v25, v24, v122 quad_perm:[1,0,3,2] row_mask:0xf bank_mask:0xf
	v_fmac_f32_dpp v41, v40, v123 quad_perm:[1,0,3,2] row_mask:0xf bank_mask:0xf
	v_cvt_pk_bf16_f32 v149, v25, v41
	ds_write_b32 v151, v149 offset:4624
	v_fmac_f32_e32 v26, v116, v25
	v_fmac_f32_e32 v42, v118, v41
	v_fmac_f32_dpp v26, v25, v122 quad_perm:[1,0,3,2] row_mask:0xf bank_mask:0xf
	v_fmac_f32_dpp v42, v41, v123 quad_perm:[1,0,3,2] row_mask:0xf bank_mask:0xf
	v_cvt_pk_bf16_f32 v148, v26, v42
	ds_write_b32 v151, v148 offset:4896
	v_fmac_f32_e32 v27, v116, v26
	v_fmac_f32_e32 v43, v118, v42
	v_fmac_f32_dpp v27, v26, v122 quad_perm:[1,0,3,2] row_mask:0xf bank_mask:0xf
	v_fmac_f32_dpp v43, v42, v123 quad_perm:[1,0,3,2] row_mask:0xf bank_mask:0xf
	v_cvt_pk_bf16_f32 v149, v27, v43
	ds_write_b32 v151, v149 offset:5168
	v_fmac_f32_e32 v56, v116, v27
	v_fmac_f32_e32 v72, v118, v43
	v_fmac_f32_dpp v56, v27, v122 quad_perm:[1,0,3,2] row_mask:0xf bank_mask:0xf
	v_fmac_f32_dpp v72, v43, v123 quad_perm:[1,0,3,2] row_mask:0xf bank_mask:0xf
	v_cvt_pk_bf16_f32 v148, v56, v72
	ds_write_b32 v151, v148 offset:5440
	v_fmac_f32_e32 v57, v116, v56
	v_fmac_f32_e32 v73, v118, v72
	v_fmac_f32_dpp v57, v56, v122 quad_perm:[1,0,3,2] row_mask:0xf bank_mask:0xf
	v_fmac_f32_dpp v73, v72, v123 quad_perm:[1,0,3,2] row_mask:0xf bank_mask:0xf
	v_cvt_pk_bf16_f32 v149, v57, v73
	ds_write_b32 v151, v149 offset:5712
	v_fmac_f32_e32 v58, v116, v57
	v_fmac_f32_e32 v74, v118, v73
	v_fmac_f32_dpp v58, v57, v122 quad_perm:[1,0,3,2] row_mask:0xf bank_mask:0xf
	v_fmac_f32_dpp v74, v73, v123 quad_perm:[1,0,3,2] row_mask:0xf bank_mask:0xf
	v_cvt_pk_bf16_f32 v148, v58, v74
	ds_write_b32 v151, v148 offset:5984
	v_fmac_f32_e32 v59, v116, v58
	v_fmac_f32_e32 v75, v118, v74
	v_fmac_f32_dpp v59, v58, v122 quad_perm:[1,0,3,2] row_mask:0xf bank_mask:0xf
	v_fmac_f32_dpp v75, v74, v123 quad_perm:[1,0,3,2] row_mask:0xf bank_mask:0xf
	v_cvt_pk_bf16_f32 v149, v59, v75
	ds_write_b32 v151, v149 offset:6256
	v_fmac_f32_e32 v28, v116, v59
	v_fmac_f32_e32 v44, v118, v75
	v_fmac_f32_dpp v28, v59, v122 quad_perm:[1,0,3,2] row_mask:0xf bank_mask:0xf
	v_fmac_f32_dpp v44, v75, v123 quad_perm:[1,0,3,2] row_mask:0xf bank_mask:0xf
	v_cvt_pk_bf16_f32 v148, v28, v44
	ds_write_b32 v151, v148 offset:6528
	v_fmac_f32_e32 v29, v116, v28
	v_fmac_f32_e32 v45, v118, v44
	v_fmac_f32_dpp v29, v28, v122 quad_perm:[1,0,3,2] row_mask:0xf bank_mask:0xf
	v_fmac_f32_dpp v45, v44, v123 quad_perm:[1,0,3,2] row_mask:0xf bank_mask:0xf
	v_cvt_pk_bf16_f32 v149, v29, v45
	ds_write_b32 v151, v149 offset:6800
	v_fmac_f32_e32 v30, v116, v29
	v_fmac_f32_e32 v46, v118, v45
	v_fmac_f32_dpp v30, v29, v122 quad_perm:[1,0,3,2] row_mask:0xf bank_mask:0xf
	v_fmac_f32_dpp v46, v45, v123 quad_perm:[1,0,3,2] row_mask:0xf bank_mask:0xf
	v_cvt_pk_bf16_f32 v148, v30, v46
	ds_write_b32 v151, v148 offset:7072
	v_fmac_f32_e32 v31, v116, v30
	v_fmac_f32_e32 v47, v118, v46
	v_fmac_f32_dpp v31, v30, v122 quad_perm:[1,0,3,2] row_mask:0xf bank_mask:0xf
	v_fmac_f32_dpp v47, v46, v123 quad_perm:[1,0,3,2] row_mask:0xf bank_mask:0xf
	v_cvt_pk_bf16_f32 v149, v31, v47
	ds_write_b32 v151, v149 offset:7344
	v_fmac_f32_e32 v60, v116, v31
	v_fmac_f32_e32 v76, v118, v47
	v_fmac_f32_dpp v60, v31, v122 quad_perm:[1,0,3,2] row_mask:0xf bank_mask:0xf
	v_fmac_f32_dpp v76, v47, v123 quad_perm:[1,0,3,2] row_mask:0xf bank_mask:0xf
	v_cvt_pk_bf16_f32 v148, v60, v76
	ds_write_b32 v151, v148 offset:7616
	v_fmac_f32_e32 v61, v116, v60
	v_fmac_f32_e32 v77, v118, v76
	v_fmac_f32_dpp v61, v60, v122 quad_perm:[1,0,3,2] row_mask:0xf bank_mask:0xf
	v_fmac_f32_dpp v77, v76, v123 quad_perm:[1,0,3,2] row_mask:0xf bank_mask:0xf
	v_cvt_pk_bf16_f32 v149, v61, v77
	ds_write_b32 v151, v149 offset:7888
	v_fmac_f32_e32 v62, v116, v61
	v_fmac_f32_e32 v78, v118, v77
	v_fmac_f32_dpp v62, v61, v122 quad_perm:[1,0,3,2] row_mask:0xf bank_mask:0xf
	v_fmac_f32_dpp v78, v77, v123 quad_perm:[1,0,3,2] row_mask:0xf bank_mask:0xf
	v_cvt_pk_bf16_f32 v148, v62, v78
	ds_write_b32 v151, v148 offset:8160
	v_fmac_f32_e32 v63, v116, v62
	v_fmac_f32_e32 v79, v118, v78
	v_fmac_f32_dpp v63, v62, v122 quad_perm:[1,0,3,2] row_mask:0xf bank_mask:0xf
	v_fmac_f32_dpp v79, v78, v123 quad_perm:[1,0,3,2] row_mask:0xf bank_mask:0xf
	v_cvt_pk_bf16_f32 v149, v63, v79
	ds_write_b32 v151, v149 offset:8432
	v_mov_b32_e32 v120, v63
	v_mov_b32_e32 v121, v79
	ds_read_b128 v[124:127], v152
	ds_read_b128 v[128:131], v152 offset:64
	ds_read_b128 v[132:135], v152 offset:128
	ds_read_b128 v[136:139], v152 offset:192
	s_waitcnt lgkmcnt(3)
	v_mfma_f32_16x16x32_bf16 v[140:143], v[100:103], v[124:127], 0
	s_waitcnt lgkmcnt(2)
	v_mfma_f32_16x16x32_bf16 v[140:143], v[104:107], v[128:131], v[140:143]
	s_waitcnt lgkmcnt(1)
	v_mfma_f32_16x16x32_bf16 v[140:143], v[108:111], v[132:135], v[140:143]
	s_waitcnt lgkmcnt(0)
	v_mfma_f32_16x16x32_bf16 v[140:143], v[112:115], v[136:139], v[140:143]
	s_nop 9
	v_cvt_pk_bf16_f32 v182, v140, v141
	v_cvt_pk_bf16_f32 v183, v142, v143
	ds_write_b64 v171, v[182:183]
	ds_read_b128 v[124:127], v152 offset:4352
	ds_read_b128 v[128:131], v152 offset:4416
	ds_read_b128 v[132:135], v152 offset:4480
	ds_read_b128 v[136:139], v152 offset:4544
	s_waitcnt lgkmcnt(3)
	v_mfma_f32_16x16x32_bf16 v[140:143], v[100:103], v[124:127], 0
	s_waitcnt lgkmcnt(2)
	v_mfma_f32_16x16x32_bf16 v[140:143], v[104:107], v[128:131], v[140:143]
	s_waitcnt lgkmcnt(1)
	v_mfma_f32_16x16x32_bf16 v[140:143], v[108:111], v[132:135], v[140:143]
	s_waitcnt lgkmcnt(0)
	v_mfma_f32_16x16x32_bf16 v[140:143], v[112:115], v[136:139], v[140:143]
	s_nop 9
	v_cvt_pk_bf16_f32 v182, v140, v141
	v_cvt_pk_bf16_f32 v183, v142, v143
	ds_write_b64 v171, v[182:183] offset:512
	s_add_u32 s36, s36, 1024
	s_add_u32 s14, s14, 2
	s_cmp_lt_u32 s14, 8
	s_cbranch_scc1 .Lssm_tile_d0m1
	s_add_u32 s30, s30, 0x8000000
	s_add_u32 s16, s60, s30
	s_addc_u32 s17, s61, 0
	global_store_dword v180, v120, s[16:17]
	global_store_dword v180, v121, s[16:17] offset:64
	s_waitcnt vmcnt(0) lgkmcnt(0)
	s_add_u32 s28, s24, 64
	s_lshl_b32 s29, s28, 13
	s_add_u32 s29, s29, 0x200000
	s_add_u32 s10, s62, s29
	s_addc_u32 s11, s63, 0
	global_load_dwordx4 v[84:87], v177, s[10:11]
	global_load_dwordx4 v[88:91], v177, s[10:11] offset:2048
	s_add_u32 s12, s10, 0x1000
	s_addc_u32 s13, s11, 0
	global_load_dwordx4 v[92:95], v177, s[12:13]
	global_load_dwordx4 v[96:99], v177, s[12:13] offset:2048
	s_lshl_b32 s29, s28, 12
	s_add_u32 s29, s29, 0x300000
	s_add_u32 s16, s62, s29
	s_addc_u32 s17, s63, 0
	global_load_dwordx2 v[2:3], v178, s[16:17]
	global_load_dwordx2 v[4:5], v178, s[16:17] offset:1024
	global_load_dwordx2 v[6:7], v178, s[16:17] offset:512
	global_load_dwordx2 v[8:9], v178, s[16:17] offset:1536
	global_load_dwordx2 v[10:11], v178, s[16:17] offset:2048
	global_load_dwordx2 v[12:13], v178, s[16:17] offset:3072
	global_load_dwordx2 v[14:15], v178, s[16:17] offset:2560
	global_load_dwordx2 v[16:17], v178, s[16:17] offset:3584
	s_lshl_b32 s29, s28, 9
	s_add_u32 s29, s29, 0x100000
	s_add_u32 s18, s62, s29
	s_addc_u32 s19, s63, 0
	global_load_dwordx2 v[116:117], v179, s[18:19]
	global_load_dwordx2 v[118:119], v179, s[18:19] offset:128
	s_lshl_b32 s30, s23, 1
	s_add_u32 s30, s30, 1
	s_lshl_b32 s30, s30, 15
	s_lshl_b32 s31, s24, 8
	s_add_u32 s30, s30, s31
	v_mov_b32_e32 v120, 0
	v_mov_b32_e32 v121, 0
	v_readlane_b32 s34, v254, 28
	v_readlane_b32 s35, v254, 29
	s_nop 3
	s_lshl_b32 s31, s24, 6
	s_add_u32 s34, s34, s31
	s_addc_u32 s35, s35, 0
	global_load_dwordx4 v[164:167], v181, s[34:35]
	s_mul_i32 s31, s25, 0x1800
	s_lshl_b32 s29, s24, 5
	s_add_u32 s31, s31, s29
	s_add_u32 s31, s31, 0x8801000
	s_add_u32 s4, s62, s31
	s_addc_u32 s5, s63, 0
	s_lshl_b32 s31, s25, 11
	s_lshl_b32 s29, s24, 5
	s_add_u32 s31, s31, s29
	s_add_u32 s31, s31, 0x14800000
	s_add_u32 s6, s62, s31
	s_addc_u32 s7, s63, 0
	s_add_u32 s34, s4, 1376256
	s_addc_u32 s35, s5, 0
	global_load_dwordx4 v[80:83], v150, s[34:35]
	s_mov_b64 s[10:11], s[34:35]
	s_sub_u32 s10, s10, 196608
	s_subb_u32 s11, s11, 0
	global_load_dwordx4 v[144:147], v150, s[10:11]
	s_mov_b64 s[34:35], s[10:11]
	s_sub_u32 s10, s10, 196608
	s_subb_u32 s11, s11, 0
	s_add_u32 s12, s6, 458752
	s_addc_u32 s13, s7, 0
	s_mov_b32 s36, 7168
	s_mov_b32 s14, 0
	s_mov_b32 s40, 0xffff0000
	s_waitcnt vmcnt(0)
	v_and_b32_e32 v182, 0xffff, v2
	v_lshrrev_b32_e32 v183, 16, v2
	v_and_b32_e32 v184, 0xffff, v3
	v_lshrrev_b32_e32 v185, 16, v3
	v_lshl_or_b32 v100, v4, 16, v182
	v_and_or_b32 v101, v4, s40, v183
	v_lshl_or_b32 v102, v5, 16, v184
	v_and_or_b32 v103, v5, s40, v185
	v_and_b32_e32 v182, 0xffff, v6
	v_lshrrev_b32_e32 v183, 16, v6
	v_and_b32_e32 v184, 0xffff, v7
	v_lshrrev_b32_e32 v185, 16, v7
	v_lshl_or_b32 v104, v8, 16, v182
	v_and_or_b32 v105, v8, s40, v183
	v_lshl_or_b32 v106, v9, 16, v184
	v_and_or_b32 v107, v9, s40, v185
	v_and_b32_e32 v182, 0xffff, v10
	v_lshrrev_b32_e32 v183, 16, v10
	v_and_b32_e32 v184, 0xffff, v11
	v_lshrrev_b32_e32 v185, 16, v11
	v_lshl_or_b32 v108, v12, 16, v182
	v_and_or_b32 v109, v12, s40, v183
	v_lshl_or_b32 v110, v13, 16, v184
	v_and_or_b32 v111, v13, s40, v185
	v_and_b32_e32 v182, 0xffff, v14
	v_lshrrev_b32_e32 v183, 16, v14
	v_and_b32_e32 v184, 0xffff, v15
	v_lshrrev_b32_e32 v185, 16, v15
	v_lshl_or_b32 v112, v16, 16, v182
	v_and_or_b32 v113, v16, s40, v183
	v_lshl_or_b32 v114, v17, 16, v184
	v_and_or_b32 v115, v17, s40, v185
	v_cmp_eq_u32_e32 vcc, 1, v174
	v_xor_b32_e32 v182, 0x80000000, v117
	v_xor_b32_e32 v183, 0x80000000, v119
	s_nop 1
	v_cndmask_b32_e32 v122, v182, v117, vcc
	v_cndmask_b32_e32 v123, v183, v119, vcc
.Lssm_tile_d1m2:
	s_waitcnt vmcnt(5)
	v_mfma_f32_32x32x16_bf16 v[16:31], v[80:83], v[84:87], 0
	v_mfma_f32_32x32x16_bf16 v[32:47], v[80:83], v[88:91], 0
	v_mfma_f32_32x32x16_bf16 v[48:63], v[80:83], v[92:95], 0
	v_mfma_f32_32x32x16_bf16 v[64:79], v[80:83], v[96:99], 0
	v_add_u32_e32 v171, s36, v155
	ds_write_b128 v162, v[80:83]
	s_nop 11
	global_load_dwordx4 v[80:83], v150, s[10:11]
	s_sub_u32 s34, s34, 196608
	s_subb_u32 s35, s35, 0
	s_sub_u32 s10, s10, 196608
	s_subb_u32 s11, s11, 0
	v_permlane32_swap_b32_e32 v16, v48
	v_permlane32_swap_b32_e32 v17, v49
	v_permlane32_swap_b32_e32 v18, v50
	v_permlane32_swap_b32_e32 v19, v51
	v_permlane32_swap_b32_e32 v20, v52
	v_permlane32_swap_b32_e32 v21, v53
	v_permlane32_swap_b32_e32 v22, v54
	v_permlane32_swap_b32_e32 v23, v55
	v_permlane32_swap_b32_e32 v24, v56
	v_permlane32_swap_b32_e32 v25, v57
	v_permlane32_swap_b32_e32 v26, v58
	v_permlane32_swap_b32_e32 v27, v59
	v_permlane32_swap_b32_e32 v28, v60
	v_permlane32_swap_b32_e32 v29, v61
	v_permlane32_swap_b32_e32 v30, v62
	v_permlane32_swap_b32_e32 v31, v63
	v_permlane32_swap_b32_e32 v32, v64
	v_permlane32_swap_b32_e32 v33, v65
	v_permlane32_swap_b32_e32 v34, v66
	v_permlane32_swap_b32_e32 v35, v67
	v_permlane32_swap_b32_e32 v36, v68
	v_permlane32_swap_b32_e32 v37, v69
	v_permlane32_swap_b32_e32 v38, v70
	v_permlane32_swap_b32_e32 v39, v71
	v_permlane32_swap_b32_e32 v40, v72
	v_permlane32_swap_b32_e32 v41, v73
	v_permlane32_swap_b32_e32 v42, v74
	v_permlane32_swap_b32_e32 v43, v75
	v_permlane32_swap_b32_e32 v44, v76
	v_permlane32_swap_b32_e32 v45, v77
	v_permlane32_swap_b32_e32 v46, v78
	v_permlane32_swap_b32_e32 v47, v79
	v_fmac_f32_e32 v63, v116, v120
	v_fmac_f32_e32 v79, v118, v121
	v_fmac_f32_dpp v63, v120, v122 quad_perm:[1,0,3,2] row_mask:0xf bank_mask:0xf
	v_fmac_f32_dpp v79, v121, v123 quad_perm:[1,0,3,2] row_mask:0xf bank_mask:0xf
	v_cvt_pk_bf16_f32 v148, v63, v79
	ds_write_b32 v151, v148 offset:8432
	v_fmac_f32_e32 v62, v116, v63
	v_fmac_f32_e32 v78, v118, v79
	v_fmac_f32_dpp v62, v63, v122 quad_perm:[1,0,3,2] row_mask:0xf bank_mask:0xf
	v_fmac_f32_dpp v78, v79, v123 quad_perm:[1,0,3,2] row_mask:0xf bank_mask:0xf
	v_cvt_pk_bf16_f32 v149, v62, v78
	ds_write_b32 v151, v149 offset:8160
	v_fmac_f32_e32 v61, v116, v62
	v_fmac_f32_e32 v77, v118, v78
	v_fmac_f32_dpp v61, v62, v122 quad_perm:[1,0,3,2] row_mask:0xf bank_mask:0xf
	v_fmac_f32_dpp v77, v78, v123 quad_perm:[1,0,3,2] row_mask:0xf bank_mask:0xf
	v_cvt_pk_bf16_f32 v148, v61, v77
	ds_write_b32 v151, v148 offset:7888
	v_fmac_f32_e32 v60, v116, v61
	v_fmac_f32_e32 v76, v118, v77
	v_fmac_f32_dpp v60, v61, v122 quad_perm:[1,0,3,2] row_mask:0xf bank_mask:0xf
	v_fmac_f32_dpp v76, v77, v123 quad_perm:[1,0,3,2] row_mask:0xf bank_mask:0xf
	v_cvt_pk_bf16_f32 v149, v60, v76
	ds_write_b32 v151, v149 offset:7616
	v_fmac_f32_e32 v31, v116, v60
	v_fmac_f32_e32 v47, v118, v76
	v_fmac_f32_dpp v31, v60, v122 quad_perm:[1,0,3,2] row_mask:0xf bank_mask:0xf
	v_fmac_f32_dpp v47, v76, v123 quad_perm:[1,0,3,2] row_mask:0xf bank_mask:0xf
	v_cvt_pk_bf16_f32 v148, v31, v47
	ds_write_b32 v151, v148 offset:7344
	v_fmac_f32_e32 v30, v116, v31
	v_fmac_f32_e32 v46, v118, v47
	v_fmac_f32_dpp v30, v31, v122 quad_perm:[1,0,3,2] row_mask:0xf bank_mask:0xf
	v_fmac_f32_dpp v46, v47, v123 quad_perm:[1,0,3,2] row_mask:0xf bank_mask:0xf
	v_cvt_pk_bf16_f32 v149, v30, v46
	ds_write_b32 v151, v149 offset:7072
	v_fmac_f32_e32 v29, v116, v30
	v_fmac_f32_e32 v45, v118, v46
	v_fmac_f32_dpp v29, v30, v122 quad_perm:[1,0,3,2] row_mask:0xf bank_mask:0xf
	v_fmac_f32_dpp v45, v46, v123 quad_perm:[1,0,3,2] row_mask:0xf bank_mask:0xf
	v_cvt_pk_bf16_f32 v148, v29, v45
	ds_write_b32 v151, v148 offset:6800
	v_fmac_f32_e32 v28, v116, v29
	v_fmac_f32_e32 v44, v118, v45
	v_fmac_f32_dpp v28, v29, v122 quad_perm:[1,0,3,2] row_mask:0xf bank_mask:0xf
	v_fmac_f32_dpp v44, v45, v123 quad_perm:[1,0,3,2] row_mask:0xf bank_mask:0xf
	v_cvt_pk_bf16_f32 v149, v28, v44
	ds_write_b32 v151, v149 offset:6528
	v_fmac_f32_e32 v59, v116, v28
	v_fmac_f32_e32 v75, v118, v44
	v_fmac_f32_dpp v59, v28, v122 quad_perm:[1,0,3,2] row_mask:0xf bank_mask:0xf
	v_fmac_f32_dpp v75, v44, v123 quad_perm:[1,0,3,2] row_mask:0xf bank_mask:0xf
	v_cvt_pk_bf16_f32 v148, v59, v75
	ds_write_b32 v151, v148 offset:6256
	v_fmac_f32_e32 v58, v116, v59
	v_fmac_f32_e32 v74, v118, v75
	v_fmac_f32_dpp v58, v59, v122 quad_perm:[1,0,3,2] row_mask:0xf bank_mask:0xf
	v_fmac_f32_dpp v74, v75, v123 quad_perm:[1,0,3,2] row_mask:0xf bank_mask:0xf
	v_cvt_pk_bf16_f32 v149, v58, v74
	ds_write_b32 v151, v149 offset:5984
	v_fmac_f32_e32 v57, v116, v58
	v_fmac_f32_e32 v73, v118, v74
	v_fmac_f32_dpp v57, v58, v122 quad_perm:[1,0,3,2] row_mask:0xf bank_mask:0xf
	v_fmac_f32_dpp v73, v74, v123 quad_perm:[1,0,3,2] row_mask:0xf bank_mask:0xf
	v_cvt_pk_bf16_f32 v148, v57, v73
	ds_write_b32 v151, v148 offset:5712
	v_fmac_f32_e32 v56, v116, v57
	v_fmac_f32_e32 v72, v118, v73
	v_fmac_f32_dpp v56, v57, v122 quad_perm:[1,0,3,2] row_mask:0xf bank_mask:0xf
	v_fmac_f32_dpp v72, v73, v123 quad_perm:[1,0,3,2] row_mask:0xf bank_mask:0xf
	v_cvt_pk_bf16_f32 v149, v56, v72
	ds_write_b32 v151, v149 offset:5440
	v_fmac_f32_e32 v27, v116, v56
	v_fmac_f32_e32 v43, v118, v72
	v_fmac_f32_dpp v27, v56, v122 quad_perm:[1,0,3,2] row_mask:0xf bank_mask:0xf
	v_fmac_f32_dpp v43, v72, v123 quad_perm:[1,0,3,2] row_mask:0xf bank_mask:0xf
	v_cvt_pk_bf16_f32 v148, v27, v43
	ds_write_b32 v151, v148 offset:5168
	v_fmac_f32_e32 v26, v116, v27
	v_fmac_f32_e32 v42, v118, v43
	v_fmac_f32_dpp v26, v27, v122 quad_perm:[1,0,3,2] row_mask:0xf bank_mask:0xf
	v_fmac_f32_dpp v42, v43, v123 quad_perm:[1,0,3,2] row_mask:0xf bank_mask:0xf
	v_cvt_pk_bf16_f32 v149, v26, v42
	ds_write_b32 v151, v149 offset:4896
	v_fmac_f32_e32 v25, v116, v26
	v_fmac_f32_e32 v41, v118, v42
	v_fmac_f32_dpp v25, v26, v122 quad_perm:[1,0,3,2] row_mask:0xf bank_mask:0xf
	v_fmac_f32_dpp v41, v42, v123 quad_perm:[1,0,3,2] row_mask:0xf bank_mask:0xf
	v_cvt_pk_bf16_f32 v148, v25, v41
	ds_write_b32 v151, v148 offset:4624
	v_fmac_f32_e32 v24, v116, v25
	v_fmac_f32_e32 v40, v118, v41
	v_fmac_f32_dpp v24, v25, v122 quad_perm:[1,0,3,2] row_mask:0xf bank_mask:0xf
	v_fmac_f32_dpp v40, v41, v123 quad_perm:[1,0,3,2] row_mask:0xf bank_mask:0xf
	v_cvt_pk_bf16_f32 v149, v24, v40
	ds_write_b32 v151, v149 offset:4352
	v_fmac_f32_e32 v55, v116, v24
	v_fmac_f32_e32 v71, v118, v40
	v_fmac_f32_dpp v55, v24, v122 quad_perm:[1,0,3,2] row_mask:0xf bank_mask:0xf
	v_fmac_f32_dpp v71, v40, v123 quad_perm:[1,0,3,2] row_mask:0xf bank_mask:0xf
	v_cvt_pk_bf16_f32 v148, v55, v71
	ds_write_b32 v151, v148 offset:4080
	v_fmac_f32_e32 v54, v116, v55
	v_fmac_f32_e32 v70, v118, v71
	v_fmac_f32_dpp v54, v55, v122 quad_perm:[1,0,3,2] row_mask:0xf bank_mask:0xf
	v_fmac_f32_dpp v70, v71, v123 quad_perm:[1,0,3,2] row_mask:0xf bank_mask:0xf
	v_cvt_pk_bf16_f32 v149, v54, v70
	ds_write_b32 v151, v149 offset:3808
	v_fmac_f32_e32 v53, v116, v54
	v_fmac_f32_e32 v69, v118, v70
	v_fmac_f32_dpp v53, v54, v122 quad_perm:[1,0,3,2] row_mask:0xf bank_mask:0xf
	v_fmac_f32_dpp v69, v70, v123 quad_perm:[1,0,3,2] row_mask:0xf bank_mask:0xf
	v_cvt_pk_bf16_f32 v148, v53, v69
	ds_write_b32 v151, v148 offset:3536
	v_fmac_f32_e32 v52, v116, v53
	v_fmac_f32_e32 v68, v118, v69
	v_fmac_f32_dpp v52, v53, v122 quad_perm:[1,0,3,2] row_mask:0xf bank_mask:0xf
	v_fmac_f32_dpp v68, v69, v123 quad_perm:[1,0,3,2] row_mask:0xf bank_mask:0xf
	v_cvt_pk_bf16_f32 v149, v52, v68
	ds_write_b32 v151, v149 offset:3264
	v_fmac_f32_e32 v23, v116, v52
	v_fmac_f32_e32 v39, v118, v68
	v_fmac_f32_dpp v23, v52, v122 quad_perm:[1,0,3,2] row_mask:0xf bank_mask:0xf
	v_fmac_f32_dpp v39, v68, v123 quad_perm:[1,0,3,2] row_mask:0xf bank_mask:0xf
	v_cvt_pk_bf16_f32 v148, v23, v39
	ds_write_b32 v151, v148 offset:2992
	v_fmac_f32_e32 v22, v116, v23
	v_fmac_f32_e32 v38, v118, v39
	v_fmac_f32_dpp v22, v23, v122 quad_perm:[1,0,3,2] row_mask:0xf bank_mask:0xf
	v_fmac_f32_dpp v38, v39, v123 quad_perm:[1,0,3,2] row_mask:0xf bank_mask:0xf
	v_cvt_pk_bf16_f32 v149, v22, v38
	ds_write_b32 v151, v149 offset:2720
	v_fmac_f32_e32 v21, v116, v22
	v_fmac_f32_e32 v37, v118, v38
	v_fmac_f32_dpp v21, v22, v122 quad_perm:[1,0,3,2] row_mask:0xf bank_mask:0xf
	v_fmac_f32_dpp v37, v38, v123 quad_perm:[1,0,3,2] row_mask:0xf bank_mask:0xf
	v_cvt_pk_bf16_f32 v148, v21, v37
	ds_write_b32 v151, v148 offset:2448
	v_fmac_f32_e32 v20, v116, v21
	v_fmac_f32_e32 v36, v118, v37
	v_fmac_f32_dpp v20, v21, v122 quad_perm:[1,0,3,2] row_mask:0xf bank_mask:0xf
	v_fmac_f32_dpp v36, v37, v123 quad_perm:[1,0,3,2] row_mask:0xf bank_mask:0xf
	v_cvt_pk_bf16_f32 v149, v20, v36
	ds_write_b32 v151, v149 offset:2176
	v_fmac_f32_e32 v51, v116, v20
	v_fmac_f32_e32 v67, v118, v36
	v_fmac_f32_dpp v51, v20, v122 quad_perm:[1,0,3,2] row_mask:0xf bank_mask:0xf
	v_fmac_f32_dpp v67, v36, v123 quad_perm:[1,0,3,2] row_mask:0xf bank_mask:0xf
	v_cvt_pk_bf16_f32 v148, v51, v67
	ds_write_b32 v151, v148 offset:1904
	v_fmac_f32_e32 v50, v116, v51
	v_fmac_f32_e32 v66, v118, v67
	v_fmac_f32_dpp v50, v51, v122 quad_perm:[1,0,3,2] row_mask:0xf bank_mask:0xf
	v_fmac_f32_dpp v66, v67, v123 quad_perm:[1,0,3,2] row_mask:0xf bank_mask:0xf
	v_cvt_pk_bf16_f32 v149, v50, v66
	ds_write_b32 v151, v149 offset:1632
	v_fmac_f32_e32 v49, v116, v50
	v_fmac_f32_e32 v65, v118, v66
	v_fmac_f32_dpp v49, v50, v122 quad_perm:[1,0,3,2] row_mask:0xf bank_mask:0xf
	v_fmac_f32_dpp v65, v66, v123 quad_perm:[1,0,3,2] row_mask:0xf bank_mask:0xf
	v_cvt_pk_bf16_f32 v148, v49, v65
	ds_write_b32 v151, v148 offset:1360
	v_fmac_f32_e32 v48, v116, v49
	v_fmac_f32_e32 v64, v118, v65
	v_fmac_f32_dpp v48, v49, v122 quad_perm:[1,0,3,2] row_mask:0xf bank_mask:0xf
	v_fmac_f32_dpp v64, v65, v123 quad_perm:[1,0,3,2] row_mask:0xf bank_mask:0xf
	v_cvt_pk_bf16_f32 v149, v48, v64
	ds_write_b32 v151, v149 offset:1088
	v_fmac_f32_e32 v19, v116, v48
	v_fmac_f32_e32 v35, v118, v64
	v_fmac_f32_dpp v19, v48, v122 quad_perm:[1,0,3,2] row_mask:0xf bank_mask:0xf
	v_fmac_f32_dpp v35, v64, v123 quad_perm:[1,0,3,2] row_mask:0xf bank_mask:0xf
	v_cvt_pk_bf16_f32 v148, v19, v35
	ds_write_b32 v151, v148 offset:816
	v_fmac_f32_e32 v18, v116, v19
	v_fmac_f32_e32 v34, v118, v35
	v_fmac_f32_dpp v18, v19, v122 quad_perm:[1,0,3,2] row_mask:0xf bank_mask:0xf
	v_fmac_f32_dpp v34, v35, v123 quad_perm:[1,0,3,2] row_mask:0xf bank_mask:0xf
	v_cvt_pk_bf16_f32 v149, v18, v34
	ds_write_b32 v151, v149 offset:544
	v_fmac_f32_e32 v17, v116, v18
	v_fmac_f32_e32 v33, v118, v34
	v_fmac_f32_dpp v17, v18, v122 quad_perm:[1,0,3,2] row_mask:0xf bank_mask:0xf
	v_fmac_f32_dpp v33, v34, v123 quad_perm:[1,0,3,2] row_mask:0xf bank_mask:0xf
	v_cvt_pk_bf16_f32 v148, v17, v33
	ds_write_b32 v151, v148 offset:272
	v_fmac_f32_e32 v16, v116, v17
	v_fmac_f32_e32 v32, v118, v33
	v_fmac_f32_dpp v16, v17, v122 quad_perm:[1,0,3,2] row_mask:0xf bank_mask:0xf
	v_fmac_f32_dpp v32, v33, v123 quad_perm:[1,0,3,2] row_mask:0xf bank_mask:0xf
	v_cvt_pk_bf16_f32 v149, v16, v32
	ds_write_b32 v151, v149
	v_mov_b32_e32 v120, v16
	v_mov_b32_e32 v121, v32
	ds_read_b128 v[124:127], v152
	ds_read_b128 v[128:131], v152 offset:64
	ds_read_b128 v[132:135], v152 offset:128
	ds_read_b128 v[136:139], v152 offset:192
	ds_read_b64 v[168:169], v171
	ds_read_b64 v[160:161], v163
	s_waitcnt lgkmcnt(5)
	v_mfma_f32_16x16x32_bf16 v[140:143], v[100:103], v[124:127], 0
	s_waitcnt lgkmcnt(4)
	v_mfma_f32_16x16x32_bf16 v[140:143], v[104:107], v[128:131], v[140:143]
	s_waitcnt lgkmcnt(3)
	v_mfma_f32_16x16x32_bf16 v[140:143], v[108:111], v[132:135], v[140:143]
	s_waitcnt lgkmcnt(2)
	v_mfma_f32_16x16x32_bf16 v[140:143], v[112:115], v[136:139], v[140:143]
	s_nop 9
	s_waitcnt lgkmcnt(0)
	v_lshlrev_b32_e32 v182, 16, v168
	v_and_b32_e32 v183, 0xffff0000, v168
	v_lshlrev_b32_e32 v184, 16, v169
	v_and_b32_e32 v185, 0xffff0000, v169
	v_add_f32_e32 v182, v182, v140
	v_add_f32_e32 v183, v183, v141
	v_add_f32_e32 v184, v184, v142
	v_add_f32_e32 v185, v185, v143
	v_lshlrev_b32_e32 v186, 16, v160
	v_and_b32_e32 v187, 0xffff0000, v160
	v_lshlrev_b32_e32 v188, 16, v161
	v_and_b32_e32 v189, 0xffff0000, v161
	v_fmac_f32_e32 v182, v164, v186
	v_fmac_f32_e32 v183, v165, v187
	v_fmac_f32_e32 v184, v166, v188
	v_fmac_f32_e32 v185, v167, v189
	v_mul_f32_e32 v186, 0x3d372713, v182
	v_mul_f32_e32 v187, 0x3d372713, v183
	v_mul_f32_e32 v188, 0x3d372713, v184
	v_mul_f32_e32 v189, 0x3d372713, v185
	v_mul_f32_e32 v186, v182, v186
	v_mul_f32_e32 v187, v183, v187
	v_mul_f32_e32 v188, v184, v188
	v_mul_f32_e32 v189, v185, v189
	v_fma_f32 v186, v182, v186, v182
	v_fma_f32 v187, v183, v187, v183
	v_fma_f32 v188, v184, v188, v184
	v_fma_f32 v189, v185, v189, v185
	v_mul_f32_e32 v186, 0xbfcc422a, v186
	v_mul_f32_e32 v187, 0xbfcc422a, v187
	v_mul_f32_e32 v188, 0xbfcc422a, v188
	v_mul_f32_e32 v189, 0xbfcc422a, v189
	v_mul_f32_e32 v186, 0x3fb8aa3b, v186
	v_mul_f32_e32 v187, 0x3fb8aa3b, v187
	v_mul_f32_e32 v188, 0x3fb8aa3b, v188
	v_mul_f32_e32 v189, 0x3fb8aa3b, v189
	v_exp_f32_e32 v186, v186
	v_exp_f32_e32 v187, v187
	v_exp_f32_e32 v188, v188
	v_exp_f32_e32 v189, v189
	v_add_f32_e32 v186, 1.0, v186
	v_add_f32_e32 v187, 1.0, v187
	v_add_f32_e32 v188, 1.0, v188
	v_add_f32_e32 v189, 1.0, v189
	v_rcp_f32_e32 v186, v186
	v_rcp_f32_e32 v187, v187
	v_rcp_f32_e32 v188, v188
	v_rcp_f32_e32 v189, v189
	v_mul_f32_e32 v182, v182, v186
	v_mul_f32_e32 v183, v183, v187
	v_mul_f32_e32 v184, v184, v188
	v_mul_f32_e32 v185, v185, v189
	v_cvt_pk_bf16_f32 v148, v182, v183
	v_cvt_pk_bf16_f32 v149, v184, v185
	global_store_dwordx2 v156, v[148:149], s[12:13]
	ds_read_b128 v[124:127], v152 offset:4352
	ds_read_b128 v[128:131], v152 offset:4416
	ds_read_b128 v[132:135], v152 offset:4480
	ds_read_b128 v[136:139], v152 offset:4544
	ds_read_b64 v[168:169], v171 offset:512
	ds_read_b64 v[160:161], v163 offset:512
	s_waitcnt lgkmcnt(5)
	v_mfma_f32_16x16x32_bf16 v[140:143], v[100:103], v[124:127], 0
	s_waitcnt lgkmcnt(4)
	v_mfma_f32_16x16x32_bf16 v[140:143], v[104:107], v[128:131], v[140:143]
	s_waitcnt lgkmcnt(3)
	v_mfma_f32_16x16x32_bf16 v[140:143], v[108:111], v[132:135], v[140:143]
	s_waitcnt lgkmcnt(2)
	v_mfma_f32_16x16x32_bf16 v[140:143], v[112:115], v[136:139], v[140:143]
	s_nop 9
	s_waitcnt lgkmcnt(0)
	v_lshlrev_b32_e32 v182, 16, v168
	v_and_b32_e32 v183, 0xffff0000, v168
	v_lshlrev_b32_e32 v184, 16, v169
	v_and_b32_e32 v185, 0xffff0000, v169
	v_add_f32_e32 v182, v182, v140
	v_add_f32_e32 v183, v183, v141
	v_add_f32_e32 v184, v184, v142
	v_add_f32_e32 v185, v185, v143
	v_lshlrev_b32_e32 v186, 16, v160
	v_and_b32_e32 v187, 0xffff0000, v160
	v_lshlrev_b32_e32 v188, 16, v161
	v_and_b32_e32 v189, 0xffff0000, v161
	v_fmac_f32_e32 v182, v164, v186
	v_fmac_f32_e32 v183, v165, v187
	v_fmac_f32_e32 v184, v166, v188
	v_fmac_f32_e32 v185, v167, v189
	v_mul_f32_e32 v186, 0x3d372713, v182
	v_mul_f32_e32 v187, 0x3d372713, v183
	v_mul_f32_e32 v188, 0x3d372713, v184
	v_mul_f32_e32 v189, 0x3d372713, v185
	v_mul_f32_e32 v186, v182, v186
	v_mul_f32_e32 v187, v183, v187
	v_mul_f32_e32 v188, v184, v188
	v_mul_f32_e32 v189, v185, v189
	v_fma_f32 v186, v182, v186, v182
	v_fma_f32 v187, v183, v187, v183
	v_fma_f32 v188, v184, v188, v184
	v_fma_f32 v189, v185, v189, v185
	v_mul_f32_e32 v186, 0xbfcc422a, v186
	v_mul_f32_e32 v187, 0xbfcc422a, v187
	v_mul_f32_e32 v188, 0xbfcc422a, v188
	v_mul_f32_e32 v189, 0xbfcc422a, v189
	v_mul_f32_e32 v186, 0x3fb8aa3b, v186
	v_mul_f32_e32 v187, 0x3fb8aa3b, v187
	v_mul_f32_e32 v188, 0x3fb8aa3b, v188
	v_mul_f32_e32 v189, 0x3fb8aa3b, v189
	v_exp_f32_e32 v186, v186
	v_exp_f32_e32 v187, v187
	v_exp_f32_e32 v188, v188
	v_exp_f32_e32 v189, v189
	v_add_f32_e32 v186, 1.0, v186
	v_add_f32_e32 v187, 1.0, v187
	v_add_f32_e32 v188, 1.0, v188
	v_add_f32_e32 v189, 1.0, v189
	v_rcp_f32_e32 v186, v186
	v_rcp_f32_e32 v187, v187
	v_rcp_f32_e32 v188, v188
	v_rcp_f32_e32 v189, v189
	v_mul_f32_e32 v182, v182, v186
	v_mul_f32_e32 v183, v183, v187
	v_mul_f32_e32 v184, v184, v188
	v_mul_f32_e32 v185, v185, v189
	v_cvt_pk_bf16_f32 v148, v182, v183
	v_cvt_pk_bf16_f32 v149, v184, v185
	global_store_dwordx2 v159, v[148:149], s[12:13]
	s_sub_u32 s12, s12, 65536
	s_subb_u32 s13, s13, 0
	s_sub_u32 s36, s36, 1024
	s_waitcnt vmcnt(5)
	v_mfma_f32_32x32x16_bf16 v[16:31], v[144:147], v[84:87], 0
	v_mfma_f32_32x32x16_bf16 v[32:47], v[144:147], v[88:91], 0
	v_mfma_f32_32x32x16_bf16 v[48:63], v[144:147], v[92:95], 0
	v_mfma_f32_32x32x16_bf16 v[64:79], v[144:147], v[96:99], 0
	v_add_u32_e32 v171, s36, v155
	ds_write_b128 v162, v[144:147]
	s_nop 11
	global_load_dwordx4 v[144:147], v150, s[10:11]
	s_sub_u32 s34, s34, 196608
	s_subb_u32 s35, s35, 0
	s_sub_u32 s10, s10, 196608
	s_subb_u32 s11, s11, 0
	v_permlane32_swap_b32_e32 v16, v48
	v_permlane32_swap_b32_e32 v17, v49
	v_permlane32_swap_b32_e32 v18, v50
	v_permlane32_swap_b32_e32 v19, v51
	v_permlane32_swap_b32_e32 v20, v52
	v_permlane32_swap_b32_e32 v21, v53
	v_permlane32_swap_b32_e32 v22, v54
	v_permlane32_swap_b32_e32 v23, v55
	v_permlane32_swap_b32_e32 v24, v56
	v_permlane32_swap_b32_e32 v25, v57
	v_permlane32_swap_b32_e32 v26, v58
	v_permlane32_swap_b32_e32 v27, v59
	v_permlane32_swap_b32_e32 v28, v60
	v_permlane32_swap_b32_e32 v29, v61
	v_permlane32_swap_b32_e32 v30, v62
	v_permlane32_swap_b32_e32 v31, v63
	v_permlane32_swap_b32_e32 v32, v64
	v_permlane32_swap_b32_e32 v33, v65
	v_permlane32_swap_b32_e32 v34, v66
	v_permlane32_swap_b32_e32 v35, v67
	v_permlane32_swap_b32_e32 v36, v68
	v_permlane32_swap_b32_e32 v37, v69
	v_permlane32_swap_b32_e32 v38, v70
	v_permlane32_swap_b32_e32 v39, v71
	v_permlane32_swap_b32_e32 v40, v72
	v_permlane32_swap_b32_e32 v41, v73
	v_permlane32_swap_b32_e32 v42, v74
	v_permlane32_swap_b32_e32 v43, v75
	v_permlane32_swap_b32_e32 v44, v76
	v_permlane32_swap_b32_e32 v45, v77
	v_permlane32_swap_b32_e32 v46, v78
	v_permlane32_swap_b32_e32 v47, v79
	v_fmac_f32_e32 v63, v116, v120
	v_fmac_f32_e32 v79, v118, v121
	v_fmac_f32_dpp v63, v120, v122 quad_perm:[1,0,3,2] row_mask:0xf bank_mask:0xf
	v_fmac_f32_dpp v79, v121, v123 quad_perm:[1,0,3,2] row_mask:0xf bank_mask:0xf
	v_cvt_pk_bf16_f32 v148, v63, v79
	ds_write_b32 v151, v148 offset:8432
	v_fmac_f32_e32 v62, v116, v63
	v_fmac_f32_e32 v78, v118, v79
	v_fmac_f32_dpp v62, v63, v122 quad_perm:[1,0,3,2] row_mask:0xf bank_mask:0xf
	v_fmac_f32_dpp v78, v79, v123 quad_perm:[1,0,3,2] row_mask:0xf bank_mask:0xf
	v_cvt_pk_bf16_f32 v149, v62, v78
	ds_write_b32 v151, v149 offset:8160
	v_fmac_f32_e32 v61, v116, v62
	v_fmac_f32_e32 v77, v118, v78
	v_fmac_f32_dpp v61, v62, v122 quad_perm:[1,0,3,2] row_mask:0xf bank_mask:0xf
	v_fmac_f32_dpp v77, v78, v123 quad_perm:[1,0,3,2] row_mask:0xf bank_mask:0xf
	v_cvt_pk_bf16_f32 v148, v61, v77
	ds_write_b32 v151, v148 offset:7888
	v_fmac_f32_e32 v60, v116, v61
	v_fmac_f32_e32 v76, v118, v77
	v_fmac_f32_dpp v60, v61, v122 quad_perm:[1,0,3,2] row_mask:0xf bank_mask:0xf
	v_fmac_f32_dpp v76, v77, v123 quad_perm:[1,0,3,2] row_mask:0xf bank_mask:0xf
	v_cvt_pk_bf16_f32 v149, v60, v76
	ds_write_b32 v151, v149 offset:7616
	v_fmac_f32_e32 v31, v116, v60
	v_fmac_f32_e32 v47, v118, v76
	v_fmac_f32_dpp v31, v60, v122 quad_perm:[1,0,3,2] row_mask:0xf bank_mask:0xf
	v_fmac_f32_dpp v47, v76, v123 quad_perm:[1,0,3,2] row_mask:0xf bank_mask:0xf
	v_cvt_pk_bf16_f32 v148, v31, v47
	ds_write_b32 v151, v148 offset:7344
	v_fmac_f32_e32 v30, v116, v31
	v_fmac_f32_e32 v46, v118, v47
	v_fmac_f32_dpp v30, v31, v122 quad_perm:[1,0,3,2] row_mask:0xf bank_mask:0xf
	v_fmac_f32_dpp v46, v47, v123 quad_perm:[1,0,3,2] row_mask:0xf bank_mask:0xf
	v_cvt_pk_bf16_f32 v149, v30, v46
	ds_write_b32 v151, v149 offset:7072
	v_fmac_f32_e32 v29, v116, v30
	v_fmac_f32_e32 v45, v118, v46
	v_fmac_f32_dpp v29, v30, v122 quad_perm:[1,0,3,2] row_mask:0xf bank_mask:0xf
	v_fmac_f32_dpp v45, v46, v123 quad_perm:[1,0,3,2] row_mask:0xf bank_mask:0xf
	v_cvt_pk_bf16_f32 v148, v29, v45
	ds_write_b32 v151, v148 offset:6800
	v_fmac_f32_e32 v28, v116, v29
	v_fmac_f32_e32 v44, v118, v45
	v_fmac_f32_dpp v28, v29, v122 quad_perm:[1,0,3,2] row_mask:0xf bank_mask:0xf
	v_fmac_f32_dpp v44, v45, v123 quad_perm:[1,0,3,2] row_mask:0xf bank_mask:0xf
	v_cvt_pk_bf16_f32 v149, v28, v44
	ds_write_b32 v151, v149 offset:6528
	v_fmac_f32_e32 v59, v116, v28
	v_fmac_f32_e32 v75, v118, v44
	v_fmac_f32_dpp v59, v28, v122 quad_perm:[1,0,3,2] row_mask:0xf bank_mask:0xf
	v_fmac_f32_dpp v75, v44, v123 quad_perm:[1,0,3,2] row_mask:0xf bank_mask:0xf
	v_cvt_pk_bf16_f32 v148, v59, v75
	ds_write_b32 v151, v148 offset:6256
	v_fmac_f32_e32 v58, v116, v59
	v_fmac_f32_e32 v74, v118, v75
	v_fmac_f32_dpp v58, v59, v122 quad_perm:[1,0,3,2] row_mask:0xf bank_mask:0xf
	v_fmac_f32_dpp v74, v75, v123 quad_perm:[1,0,3,2] row_mask:0xf bank_mask:0xf
	v_cvt_pk_bf16_f32 v149, v58, v74
	ds_write_b32 v151, v149 offset:5984
	v_fmac_f32_e32 v57, v116, v58
	v_fmac_f32_e32 v73, v118, v74
	v_fmac_f32_dpp v57, v58, v122 quad_perm:[1,0,3,2] row_mask:0xf bank_mask:0xf
	v_fmac_f32_dpp v73, v74, v123 quad_perm:[1,0,3,2] row_mask:0xf bank_mask:0xf
	v_cvt_pk_bf16_f32 v148, v57, v73
	ds_write_b32 v151, v148 offset:5712
	v_fmac_f32_e32 v56, v116, v57
	v_fmac_f32_e32 v72, v118, v73
	v_fmac_f32_dpp v56, v57, v122 quad_perm:[1,0,3,2] row_mask:0xf bank_mask:0xf
	v_fmac_f32_dpp v72, v73, v123 quad_perm:[1,0,3,2] row_mask:0xf bank_mask:0xf
	v_cvt_pk_bf16_f32 v149, v56, v72
	ds_write_b32 v151, v149 offset:5440
	v_fmac_f32_e32 v27, v116, v56
	v_fmac_f32_e32 v43, v118, v72
	v_fmac_f32_dpp v27, v56, v122 quad_perm:[1,0,3,2] row_mask:0xf bank_mask:0xf
	v_fmac_f32_dpp v43, v72, v123 quad_perm:[1,0,3,2] row_mask:0xf bank_mask:0xf
	v_cvt_pk_bf16_f32 v148, v27, v43
	ds_write_b32 v151, v148 offset:5168
	v_fmac_f32_e32 v26, v116, v27
	v_fmac_f32_e32 v42, v118, v43
	v_fmac_f32_dpp v26, v27, v122 quad_perm:[1,0,3,2] row_mask:0xf bank_mask:0xf
	v_fmac_f32_dpp v42, v43, v123 quad_perm:[1,0,3,2] row_mask:0xf bank_mask:0xf
	v_cvt_pk_bf16_f32 v149, v26, v42
	ds_write_b32 v151, v149 offset:4896
	v_fmac_f32_e32 v25, v116, v26
	v_fmac_f32_e32 v41, v118, v42
	v_fmac_f32_dpp v25, v26, v122 quad_perm:[1,0,3,2] row_mask:0xf bank_mask:0xf
	v_fmac_f32_dpp v41, v42, v123 quad_perm:[1,0,3,2] row_mask:0xf bank_mask:0xf
	v_cvt_pk_bf16_f32 v148, v25, v41
	ds_write_b32 v151, v148 offset:4624
	v_fmac_f32_e32 v24, v116, v25
	v_fmac_f32_e32 v40, v118, v41
	v_fmac_f32_dpp v24, v25, v122 quad_perm:[1,0,3,2] row_mask:0xf bank_mask:0xf
	v_fmac_f32_dpp v40, v41, v123 quad_perm:[1,0,3,2] row_mask:0xf bank_mask:0xf
	v_cvt_pk_bf16_f32 v149, v24, v40
	ds_write_b32 v151, v149 offset:4352
	v_fmac_f32_e32 v55, v116, v24
	v_fmac_f32_e32 v71, v118, v40
	v_fmac_f32_dpp v55, v24, v122 quad_perm:[1,0,3,2] row_mask:0xf bank_mask:0xf
	v_fmac_f32_dpp v71, v40, v123 quad_perm:[1,0,3,2] row_mask:0xf bank_mask:0xf
	v_cvt_pk_bf16_f32 v148, v55, v71
	ds_write_b32 v151, v148 offset:4080
	v_fmac_f32_e32 v54, v116, v55
	v_fmac_f32_e32 v70, v118, v71
	v_fmac_f32_dpp v54, v55, v122 quad_perm:[1,0,3,2] row_mask:0xf bank_mask:0xf
	v_fmac_f32_dpp v70, v71, v123 quad_perm:[1,0,3,2] row_mask:0xf bank_mask:0xf
	v_cvt_pk_bf16_f32 v149, v54, v70
	ds_write_b32 v151, v149 offset:3808
	v_fmac_f32_e32 v53, v116, v54
	v_fmac_f32_e32 v69, v118, v70
	v_fmac_f32_dpp v53, v54, v122 quad_perm:[1,0,3,2] row_mask:0xf bank_mask:0xf
	v_fmac_f32_dpp v69, v70, v123 quad_perm:[1,0,3,2] row_mask:0xf bank_mask:0xf
	v_cvt_pk_bf16_f32 v148, v53, v69
	ds_write_b32 v151, v148 offset:3536
	v_fmac_f32_e32 v52, v116, v53
	v_fmac_f32_e32 v68, v118, v69
	v_fmac_f32_dpp v52, v53, v122 quad_perm:[1,0,3,2] row_mask:0xf bank_mask:0xf
	v_fmac_f32_dpp v68, v69, v123 quad_perm:[1,0,3,2] row_mask:0xf bank_mask:0xf
	v_cvt_pk_bf16_f32 v149, v52, v68
	ds_write_b32 v151, v149 offset:3264
	v_fmac_f32_e32 v23, v116, v52
	v_fmac_f32_e32 v39, v118, v68
	v_fmac_f32_dpp v23, v52, v122 quad_perm:[1,0,3,2] row_mask:0xf bank_mask:0xf
	v_fmac_f32_dpp v39, v68, v123 quad_perm:[1,0,3,2] row_mask:0xf bank_mask:0xf
	v_cvt_pk_bf16_f32 v148, v23, v39
	ds_write_b32 v151, v148 offset:2992
	v_fmac_f32_e32 v22, v116, v23
	v_fmac_f32_e32 v38, v118, v39
	v_fmac_f32_dpp v22, v23, v122 quad_perm:[1,0,3,2] row_mask:0xf bank_mask:0xf
	v_fmac_f32_dpp v38, v39, v123 quad_perm:[1,0,3,2] row_mask:0xf bank_mask:0xf
	v_cvt_pk_bf16_f32 v149, v22, v38
	ds_write_b32 v151, v149 offset:2720
	v_fmac_f32_e32 v21, v116, v22
	v_fmac_f32_e32 v37, v118, v38
	v_fmac_f32_dpp v21, v22, v122 quad_perm:[1,0,3,2] row_mask:0xf bank_mask:0xf
	v_fmac_f32_dpp v37, v38, v123 quad_perm:[1,0,3,2] row_mask:0xf bank_mask:0xf
	v_cvt_pk_bf16_f32 v148, v21, v37
	ds_write_b32 v151, v148 offset:2448
	v_fmac_f32_e32 v20, v116, v21
	v_fmac_f32_e32 v36, v118, v37
	v_fmac_f32_dpp v20, v21, v122 quad_perm:[1,0,3,2] row_mask:0xf bank_mask:0xf
	v_fmac_f32_dpp v36, v37, v123 quad_perm:[1,0,3,2] row_mask:0xf bank_mask:0xf
	v_cvt_pk_bf16_f32 v149, v20, v36
	ds_write_b32 v151, v149 offset:2176
	v_fmac_f32_e32 v51, v116, v20
	v_fmac_f32_e32 v67, v118, v36
	v_fmac_f32_dpp v51, v20, v122 quad_perm:[1,0,3,2] row_mask:0xf bank_mask:0xf
	v_fmac_f32_dpp v67, v36, v123 quad_perm:[1,0,3,2] row_mask:0xf bank_mask:0xf
	v_cvt_pk_bf16_f32 v148, v51, v67
	ds_write_b32 v151, v148 offset:1904
	v_fmac_f32_e32 v50, v116, v51
	v_fmac_f32_e32 v66, v118, v67
	v_fmac_f32_dpp v50, v51, v122 quad_perm:[1,0,3,2] row_mask:0xf bank_mask:0xf
	v_fmac_f32_dpp v66, v67, v123 quad_perm:[1,0,3,2] row_mask:0xf bank_mask:0xf
	v_cvt_pk_bf16_f32 v149, v50, v66
	ds_write_b32 v151, v149 offset:1632
	v_fmac_f32_e32 v49, v116, v50
	v_fmac_f32_e32 v65, v118, v66
	v_fmac_f32_dpp v49, v50, v122 quad_perm:[1,0,3,2] row_mask:0xf bank_mask:0xf
	v_fmac_f32_dpp v65, v66, v123 quad_perm:[1,0,3,2] row_mask:0xf bank_mask:0xf
	v_cvt_pk_bf16_f32 v148, v49, v65
	ds_write_b32 v151, v148 offset:1360
	v_fmac_f32_e32 v48, v116, v49
	v_fmac_f32_e32 v64, v118, v65
	v_fmac_f32_dpp v48, v49, v122 quad_perm:[1,0,3,2] row_mask:0xf bank_mask:0xf
	v_fmac_f32_dpp v64, v65, v123 quad_perm:[1,0,3,2] row_mask:0xf bank_mask:0xf
	v_cvt_pk_bf16_f32 v149, v48, v64
	ds_write_b32 v151, v149 offset:1088
	v_fmac_f32_e32 v19, v116, v48
	v_fmac_f32_e32 v35, v118, v64
	v_fmac_f32_dpp v19, v48, v122 quad_perm:[1,0,3,2] row_mask:0xf bank_mask:0xf
	v_fmac_f32_dpp v35, v64, v123 quad_perm:[1,0,3,2] row_mask:0xf bank_mask:0xf
	v_cvt_pk_bf16_f32 v148, v19, v35
	ds_write_b32 v151, v148 offset:816
	v_fmac_f32_e32 v18, v116, v19
	v_fmac_f32_e32 v34, v118, v35
	v_fmac_f32_dpp v18, v19, v122 quad_perm:[1,0,3,2] row_mask:0xf bank_mask:0xf
	v_fmac_f32_dpp v34, v35, v123 quad_perm:[1,0,3,2] row_mask:0xf bank_mask:0xf
	v_cvt_pk_bf16_f32 v149, v18, v34
	ds_write_b32 v151, v149 offset:544
	v_fmac_f32_e32 v17, v116, v18
	v_fmac_f32_e32 v33, v118, v34
	v_fmac_f32_dpp v17, v18, v122 quad_perm:[1,0,3,2] row_mask:0xf bank_mask:0xf
	v_fmac_f32_dpp v33, v34, v123 quad_perm:[1,0,3,2] row_mask:0xf bank_mask:0xf
	v_cvt_pk_bf16_f32 v148, v17, v33
	ds_write_b32 v151, v148 offset:272
	v_fmac_f32_e32 v16, v116, v17
	v_fmac_f32_e32 v32, v118, v33
	v_fmac_f32_dpp v16, v17, v122 quad_perm:[1,0,3,2] row_mask:0xf bank_mask:0xf
	v_fmac_f32_dpp v32, v33, v123 quad_perm:[1,0,3,2] row_mask:0xf bank_mask:0xf
	v_cvt_pk_bf16_f32 v149, v16, v32
	ds_write_b32 v151, v149
	v_mov_b32_e32 v120, v16
	v_mov_b32_e32 v121, v32
	ds_read_b128 v[124:127], v152
	ds_read_b128 v[128:131], v152 offset:64
	ds_read_b128 v[132:135], v152 offset:128
	ds_read_b128 v[136:139], v152 offset:192
	ds_read_b64 v[168:169], v171
	ds_read_b64 v[160:161], v163
	s_waitcnt lgkmcnt(5)
	v_mfma_f32_16x16x32_bf16 v[140:143], v[100:103], v[124:127], 0
	s_waitcnt lgkmcnt(4)
	v_mfma_f32_16x16x32_bf16 v[140:143], v[104:107], v[128:131], v[140:143]
	s_waitcnt lgkmcnt(3)
	v_mfma_f32_16x16x32_bf16 v[140:143], v[108:111], v[132:135], v[140:143]
	s_waitcnt lgkmcnt(2)
	v_mfma_f32_16x16x32_bf16 v[140:143], v[112:115], v[136:139], v[140:143]
	s_nop 9
	s_waitcnt lgkmcnt(0)
	v_lshlrev_b32_e32 v182, 16, v168
	v_and_b32_e32 v183, 0xffff0000, v168
	v_lshlrev_b32_e32 v184, 16, v169
	v_and_b32_e32 v185, 0xffff0000, v169
	v_add_f32_e32 v182, v182, v140
	v_add_f32_e32 v183, v183, v141
	v_add_f32_e32 v184, v184, v142
	v_add_f32_e32 v185, v185, v143
	v_lshlrev_b32_e32 v186, 16, v160
	v_and_b32_e32 v187, 0xffff0000, v160
	v_lshlrev_b32_e32 v188, 16, v161
	v_and_b32_e32 v189, 0xffff0000, v161
	v_fmac_f32_e32 v182, v164, v186
	v_fmac_f32_e32 v183, v165, v187
	v_fmac_f32_e32 v184, v166, v188
	v_fmac_f32_e32 v185, v167, v189
	v_mul_f32_e32 v186, 0x3d372713, v182
	v_mul_f32_e32 v187, 0x3d372713, v183
	v_mul_f32_e32 v188, 0x3d372713, v184
	v_mul_f32_e32 v189, 0x3d372713, v185
	v_mul_f32_e32 v186, v182, v186
	v_mul_f32_e32 v187, v183, v187
	v_mul_f32_e32 v188, v184, v188
	v_mul_f32_e32 v189, v185, v189
	v_fma_f32 v186, v182, v186, v182
	v_fma_f32 v187, v183, v187, v183
	v_fma_f32 v188, v184, v188, v184
	v_fma_f32 v189, v185, v189, v185
	v_mul_f32_e32 v186, 0xbfcc422a, v186
	v_mul_f32_e32 v187, 0xbfcc422a, v187
	v_mul_f32_e32 v188, 0xbfcc422a, v188
	v_mul_f32_e32 v189, 0xbfcc422a, v189
	v_mul_f32_e32 v186, 0x3fb8aa3b, v186
	v_mul_f32_e32 v187, 0x3fb8aa3b, v187
	v_mul_f32_e32 v188, 0x3fb8aa3b, v188
	v_mul_f32_e32 v189, 0x3fb8aa3b, v189
	v_exp_f32_e32 v186, v186
	v_exp_f32_e32 v187, v187
	v_exp_f32_e32 v188, v188
	v_exp_f32_e32 v189, v189
	v_add_f32_e32 v186, 1.0, v186
	v_add_f32_e32 v187, 1.0, v187
	v_add_f32_e32 v188, 1.0, v188
	v_add_f32_e32 v189, 1.0, v189
	v_rcp_f32_e32 v186, v186
	v_rcp_f32_e32 v187, v187
	v_rcp_f32_e32 v188, v188
	v_rcp_f32_e32 v189, v189
	v_mul_f32_e32 v182, v182, v186
	v_mul_f32_e32 v183, v183, v187
	v_mul_f32_e32 v184, v184, v188
	v_mul_f32_e32 v185, v185, v189
	v_cvt_pk_bf16_f32 v148, v182, v183
	v_cvt_pk_bf16_f32 v149, v184, v185
	global_store_dwordx2 v156, v[148:149], s[12:13]
	ds_read_b128 v[124:127], v152 offset:4352
	ds_read_b128 v[128:131], v152 offset:4416
	ds_read_b128 v[132:135], v152 offset:4480
	ds_read_b128 v[136:139], v152 offset:4544
	ds_read_b64 v[168:169], v171 offset:512
	ds_read_b64 v[160:161], v163 offset:512
	s_waitcnt lgkmcnt(5)
	v_mfma_f32_16x16x32_bf16 v[140:143], v[100:103], v[124:127], 0
	s_waitcnt lgkmcnt(4)
	v_mfma_f32_16x16x32_bf16 v[140:143], v[104:107], v[128:131], v[140:143]
	s_waitcnt lgkmcnt(3)
	v_mfma_f32_16x16x32_bf16 v[140:143], v[108:111], v[132:135], v[140:143]
	s_waitcnt lgkmcnt(2)
	v_mfma_f32_16x16x32_bf16 v[140:143], v[112:115], v[136:139], v[140:143]
	s_nop 9
	s_waitcnt lgkmcnt(0)
	v_lshlrev_b32_e32 v182, 16, v168
	v_and_b32_e32 v183, 0xffff0000, v168
	v_lshlrev_b32_e32 v184, 16, v169
	v_and_b32_e32 v185, 0xffff0000, v169
	v_add_f32_e32 v182, v182, v140
	v_add_f32_e32 v183, v183, v141
	v_add_f32_e32 v184, v184, v142
	v_add_f32_e32 v185, v185, v143
	v_lshlrev_b32_e32 v186, 16, v160
	v_and_b32_e32 v187, 0xffff0000, v160
	v_lshlrev_b32_e32 v188, 16, v161
	v_and_b32_e32 v189, 0xffff0000, v161
	v_fmac_f32_e32 v182, v164, v186
	v_fmac_f32_e32 v183, v165, v187
	v_fmac_f32_e32 v184, v166, v188
	v_fmac_f32_e32 v185, v167, v189
	v_mul_f32_e32 v186, 0x3d372713, v182
	v_mul_f32_e32 v187, 0x3d372713, v183
	v_mul_f32_e32 v188, 0x3d372713, v184
	v_mul_f32_e32 v189, 0x3d372713, v185
	v_mul_f32_e32 v186, v182, v186
	v_mul_f32_e32 v187, v183, v187
	v_mul_f32_e32 v188, v184, v188
	v_mul_f32_e32 v189, v185, v189
	v_fma_f32 v186, v182, v186, v182
	v_fma_f32 v187, v183, v187, v183
	v_fma_f32 v188, v184, v188, v184
	v_fma_f32 v189, v185, v189, v185
	v_mul_f32_e32 v186, 0xbfcc422a, v186
	v_mul_f32_e32 v187, 0xbfcc422a, v187
	v_mul_f32_e32 v188, 0xbfcc422a, v188
	v_mul_f32_e32 v189, 0xbfcc422a, v189
	v_mul_f32_e32 v186, 0x3fb8aa3b, v186
	v_mul_f32_e32 v187, 0x3fb8aa3b, v187
	v_mul_f32_e32 v188, 0x3fb8aa3b, v188
	v_mul_f32_e32 v189, 0x3fb8aa3b, v189
	v_exp_f32_e32 v186, v186
	v_exp_f32_e32 v187, v187
	v_exp_f32_e32 v188, v188
	v_exp_f32_e32 v189, v189
	v_add_f32_e32 v186, 1.0, v186
	v_add_f32_e32 v187, 1.0, v187
	v_add_f32_e32 v188, 1.0, v188
	v_add_f32_e32 v189, 1.0, v189
	v_rcp_f32_e32 v186, v186
	v_rcp_f32_e32 v187, v187
	v_rcp_f32_e32 v188, v188
	v_rcp_f32_e32 v189, v189
	v_mul_f32_e32 v182, v182, v186
	v_mul_f32_e32 v183, v183, v187
	v_mul_f32_e32 v184, v184, v188
	v_mul_f32_e32 v185, v185, v189
	v_cvt_pk_bf16_f32 v148, v182, v183
	v_cvt_pk_bf16_f32 v149, v184, v185
	global_store_dwordx2 v159, v[148:149], s[12:13]
	s_sub_u32 s12, s12, 65536
	s_subb_u32 s13, s13, 0
	s_sub_u32 s36, s36, 1024
	s_add_u32 s14, s14, 2
	s_cmp_lt_u32 s14, 8
	s_cbranch_scc1 .Lssm_tile_d1m2
	s_add_u32 s30, s30, 0x8000000
	s_add_u32 s16, s60, s30
	s_addc_u32 s17, s61, 0
	global_store_dword v180, v120, s[16:17]
	global_store_dword v180, v121, s[16:17] offset:64
	s_waitcnt vmcnt(0) lgkmcnt(0)
	s_add_u32 s27, s27, 1
	s_cmp_lt_u32 s27, 2
	s_cbranch_scc1 .Lssm_ctx_loop
